# GEMM K-loops: priority raise moved in front of the phase barrier and the already-satisfied lgkmcnt wait dropped, so the first MFMA issues directly after the barrier
# speedup vs baseline: 1.0045x; 1.0045x over previous
.LBB0_849:
	ds_read_b128 v[146:149], v155
	ds_read_b128 v[160:163], v155 offset:1024
	ds_read_b128 v[164:167], v155 offset:2048
	ds_read_b128 v[168:171], v155 offset:3072
	ds_read_b128 v[172:175], v156
	ds_read_b128 v[176:179], v156 offset:1024
	ds_read_b128 v[180:183], v156 offset:2048
	ds_read_b128 v[184:187], v156 offset:3072
	s_add_u32 s74, s72, 0xfff80080
	s_addc_u32 s75, s73, -1
	s_cmp_eq_u32 s85, 28
	s_cselect_b32 s77, s63, s75
	s_cselect_b32 s76, s69, s74
	s_cselect_b32 s75, s57, s84
	s_cselect_b32 s74, s71, s83
	v_lshl_add_u64 v[220:221], s[72:73], 0, v[138:139]
	s_add_i32 m0, s3, 0xc000
	ds_read_b128 v[188:191], v157
	ds_read_b128 v[192:195], v157 offset:1024
	ds_read_b128 v[196:199], v157 offset:2048
	ds_read_b128 v[200:203], v157 offset:3072
	ds_read_b128 v[204:207], v157 offset:4096
	ds_read_b128 v[208:211], v157 offset:5120
	ds_read_b128 v[212:215], v157 offset:6144
	ds_read_b128 v[216:219], v157 offset:7168
	global_load_lds_dwordx4 v[220:221], off
	v_lshl_add_u64 v[220:221], s[72:73], 0, v[140:141]
	s_add_i32 m0, s3, 0xe000
	s_nop 0
	global_load_lds_dwordx4 v[220:221], off
	s_waitcnt vmcnt(8)
	s_waitcnt lgkmcnt(0)
	s_setprio 1
	s_barrier
	v_mfma_f32_16x16x32_bf16 v[124:127], v[146:149], v[188:191], v[124:127]
	v_mfma_f32_16x16x32_bf16 v[120:123], v[164:167], v[188:191], v[120:123]
	v_mfma_f32_16x16x32_bf16 v[108:111], v[146:149], v[196:199], v[108:111]
	v_mfma_f32_16x16x32_bf16 v[104:107], v[164:167], v[196:199], v[104:107]
	v_mfma_f32_16x16x32_bf16 v[92:95], v[146:149], v[204:207], v[92:95]
	v_mfma_f32_16x16x32_bf16 v[88:91], v[164:167], v[204:207], v[88:91]
	v_mfma_f32_16x16x32_bf16 v[76:79], v[146:149], v[212:215], v[76:79]
	v_mfma_f32_16x16x32_bf16 v[72:75], v[164:167], v[212:215], v[72:75]
	v_mfma_f32_16x16x32_bf16 v[124:127], v[160:163], v[192:195], v[124:127]
	v_mfma_f32_16x16x32_bf16 v[120:123], v[168:171], v[192:195], v[120:123]
	v_mfma_f32_16x16x32_bf16 v[108:111], v[160:163], v[200:203], v[108:111]
	v_mfma_f32_16x16x32_bf16 v[104:107], v[168:171], v[200:203], v[104:107]
	v_mfma_f32_16x16x32_bf16 v[92:95], v[160:163], v[208:211], v[92:95]
	v_mfma_f32_16x16x32_bf16 v[88:91], v[168:171], v[208:211], v[88:91]
	v_mfma_f32_16x16x32_bf16 v[76:79], v[160:163], v[216:219], v[76:79]
	v_mfma_f32_16x16x32_bf16 v[72:75], v[168:171], v[216:219], v[72:75]
	v_mfma_f32_16x16x32_bf16 v[116:119], v[172:175], v[188:191], v[116:119]
	v_mfma_f32_16x16x32_bf16 v[112:115], v[180:183], v[188:191], v[112:115]
	v_mfma_f32_16x16x32_bf16 v[100:103], v[172:175], v[196:199], v[100:103]
	v_mfma_f32_16x16x32_bf16 v[96:99], v[180:183], v[196:199], v[96:99]
	v_mfma_f32_16x16x32_bf16 v[84:87], v[172:175], v[204:207], v[84:87]
	v_mfma_f32_16x16x32_bf16 v[80:83], v[180:183], v[204:207], v[80:83]
	v_mfma_f32_16x16x32_bf16 v[68:71], v[172:175], v[212:215], v[68:71]
	v_mfma_f32_16x16x32_bf16 v[64:67], v[180:183], v[212:215], v[64:67]
	v_mfma_f32_16x16x32_bf16 v[116:119], v[176:179], v[192:195], v[116:119]
	v_mfma_f32_16x16x32_bf16 v[112:115], v[184:187], v[192:195], v[112:115]
	v_mfma_f32_16x16x32_bf16 v[100:103], v[176:179], v[200:203], v[100:103]
	v_mfma_f32_16x16x32_bf16 v[96:99], v[184:187], v[200:203], v[96:99]
	v_mfma_f32_16x16x32_bf16 v[84:87], v[176:179], v[208:211], v[84:87]
	v_mfma_f32_16x16x32_bf16 v[80:83], v[184:187], v[208:211], v[80:83]
	v_mfma_f32_16x16x32_bf16 v[68:71], v[176:179], v[216:219], v[68:71]
	v_mfma_f32_16x16x32_bf16 v[64:67], v[184:187], v[216:219], v[64:67]
	s_setprio 0
	s_barrier
	s_add_i32 s86, s79, s94
	v_lshl_add_u64 v[220:221], s[74:75], 0, v[130:131]
	s_mov_b32 m0, s86
	ds_read_b128 v[188:191], v157 offset:16384
	ds_read_b128 v[192:195], v157 offset:17408
	ds_read_b128 v[196:199], v157 offset:18432
	ds_read_b128 v[200:203], v157 offset:19456
	ds_read_b128 v[204:207], v157 offset:20480
	ds_read_b128 v[208:211], v157 offset:21504
	ds_read_b128 v[212:215], v157 offset:22528
	ds_read_b128 v[216:219], v157 offset:23552
	global_load_lds_dwordx4 v[220:221], off
	s_add_i32 m0, s86, 0x2000
	s_add_u32 s86, s74, 0x80000
	v_lshl_add_u64 v[222:223], s[74:75], 0, v[134:135]
	s_addc_u32 s87, s75, 0
	s_add_i32 s88, s81, s94
	global_load_lds_dwordx4 v[222:223], off
	v_lshl_add_u64 v[224:225], s[86:87], 0, v[130:131]
	s_mov_b32 m0, s88
	v_lshl_add_u64 v[226:227], s[76:77], 0, v[132:133]
	global_load_lds_dwordx4 v[224:225], off
	v_lshl_add_u64 v[224:225], s[86:87], 0, v[134:135]
	s_add_i32 m0, s88, 0x2000
	s_nop 0
	global_load_lds_dwordx4 v[224:225], off
	v_lshl_add_u64 v[224:225], s[76:77], 0, v[128:129]
	s_mov_b32 m0, s3
	s_nop 0
	global_load_lds_dwordx4 v[224:225], off
	s_mov_b32 m0, s6
	s_nop 0
	global_load_lds_dwordx4 v[226:227], off
	s_waitcnt vmcnt(8)
	s_waitcnt lgkmcnt(0)
	s_setprio 1
	s_barrier
	v_mfma_f32_16x16x32_bf16 v[60:63], v[146:149], v[188:191], v[60:63]
	v_mfma_f32_16x16x32_bf16 v[56:59], v[164:167], v[188:191], v[56:59]
	v_mfma_f32_16x16x32_bf16 v[44:47], v[146:149], v[196:199], v[44:47]
	v_mfma_f32_16x16x32_bf16 v[40:43], v[164:167], v[196:199], v[40:43]
	v_mfma_f32_16x16x32_bf16 v[28:31], v[146:149], v[204:207], v[28:31]
	v_mfma_f32_16x16x32_bf16 v[24:27], v[164:167], v[204:207], v[24:27]
	v_mfma_f32_16x16x32_bf16 v[12:15], v[146:149], v[212:215], v[12:15]
	v_mfma_f32_16x16x32_bf16 v[8:11], v[164:167], v[212:215], v[8:11]
	v_mfma_f32_16x16x32_bf16 v[60:63], v[160:163], v[192:195], v[60:63]
	v_mfma_f32_16x16x32_bf16 v[56:59], v[168:171], v[192:195], v[56:59]
	v_mfma_f32_16x16x32_bf16 v[44:47], v[160:163], v[200:203], v[44:47]
	v_mfma_f32_16x16x32_bf16 v[40:43], v[168:171], v[200:203], v[40:43]
	v_mfma_f32_16x16x32_bf16 v[28:31], v[160:163], v[208:211], v[28:31]
	v_mfma_f32_16x16x32_bf16 v[24:27], v[168:171], v[208:211], v[24:27]
	v_mfma_f32_16x16x32_bf16 v[12:15], v[160:163], v[216:219], v[12:15]
	v_mfma_f32_16x16x32_bf16 v[8:11], v[168:171], v[216:219], v[8:11]
	v_mfma_f32_16x16x32_bf16 v[52:55], v[172:175], v[188:191], v[52:55]
	v_mfma_f32_16x16x32_bf16 v[48:51], v[180:183], v[188:191], v[48:51]
	v_mfma_f32_16x16x32_bf16 v[36:39], v[172:175], v[196:199], v[36:39]
	v_mfma_f32_16x16x32_bf16 v[32:35], v[180:183], v[196:199], v[32:35]
	v_mfma_f32_16x16x32_bf16 v[20:23], v[172:175], v[204:207], v[20:23]
	v_mfma_f32_16x16x32_bf16 v[16:19], v[180:183], v[204:207], v[16:19]
	v_mfma_f32_16x16x32_bf16 v[4:7], v[172:175], v[212:215], v[4:7]
	v_mfma_f32_16x16x32_bf16 v[0:3], v[180:183], v[212:215], v[0:3]
	v_mfma_f32_16x16x32_bf16 v[52:55], v[176:179], v[192:195], v[52:55]
	v_mfma_f32_16x16x32_bf16 v[48:51], v[184:187], v[192:195], v[48:51]
	v_mfma_f32_16x16x32_bf16 v[36:39], v[176:179], v[200:203], v[36:39]
	v_mfma_f32_16x16x32_bf16 v[32:35], v[184:187], v[200:203], v[32:35]
	v_mfma_f32_16x16x32_bf16 v[20:23], v[176:179], v[208:211], v[20:23]
	v_mfma_f32_16x16x32_bf16 v[16:19], v[184:187], v[208:211], v[16:19]
	v_mfma_f32_16x16x32_bf16 v[4:7], v[176:179], v[216:219], v[4:7]
	v_mfma_f32_16x16x32_bf16 v[0:3], v[184:187], v[216:219], v[0:3]
	s_setprio 0
	s_barrier
	s_add_i32 s86, 0, 0x18000
	v_add_u32_e32 v159, s86, v151
	s_add_i32 s87, 0, 0x1c000
	ds_read_b128 v[146:149], v159
	ds_read_b128 v[160:163], v159 offset:1024
	ds_read_b128 v[164:167], v159 offset:2048
	ds_read_b128 v[168:171], v159 offset:3072
	v_add_u32_e32 v159, s87, v151
	ds_read_b128 v[172:175], v159
	ds_read_b128 v[176:179], v159 offset:1024
	ds_read_b128 v[180:183], v159 offset:2048
	ds_read_b128 v[184:187], v159 offset:3072
	s_add_u32 s76, s76, 0x80000
	s_addc_u32 s77, s77, 0
	s_mov_b32 m0, s7
	v_lshl_add_u64 v[228:229], s[76:77], 0, v[128:129]
	ds_read_b128 v[188:191], v157 offset:32768
	ds_read_b128 v[192:195], v157 offset:33792
	ds_read_b128 v[196:199], v157 offset:34816
	ds_read_b128 v[200:203], v157 offset:35840
	ds_read_b128 v[204:207], v157 offset:36864
	ds_read_b128 v[208:211], v157 offset:37888
	ds_read_b128 v[212:215], v157 offset:38912
	ds_read_b128 v[216:219], v157 offset:39936
	global_load_lds_dwordx4 v[228:229], off
	v_lshl_add_u64 v[228:229], s[76:77], 0, v[132:133]
	s_mov_b32 m0, s29
	s_nop 0
	global_load_lds_dwordx4 v[228:229], off
	s_waitcnt vmcnt(8)
	s_waitcnt lgkmcnt(0)
	s_setprio 1
	s_barrier
	v_mfma_f32_16x16x32_bf16 v[124:127], v[146:149], v[188:191], v[124:127]
	v_mfma_f32_16x16x32_bf16 v[120:123], v[164:167], v[188:191], v[120:123]
	v_mfma_f32_16x16x32_bf16 v[108:111], v[146:149], v[196:199], v[108:111]
	v_mfma_f32_16x16x32_bf16 v[104:107], v[164:167], v[196:199], v[104:107]
	v_mfma_f32_16x16x32_bf16 v[92:95], v[146:149], v[204:207], v[92:95]
	v_mfma_f32_16x16x32_bf16 v[88:91], v[164:167], v[204:207], v[88:91]
	v_mfma_f32_16x16x32_bf16 v[76:79], v[146:149], v[212:215], v[76:79]
	v_mfma_f32_16x16x32_bf16 v[72:75], v[164:167], v[212:215], v[72:75]
	v_mfma_f32_16x16x32_bf16 v[124:127], v[160:163], v[192:195], v[124:127]
	v_mfma_f32_16x16x32_bf16 v[120:123], v[168:171], v[192:195], v[120:123]
	v_mfma_f32_16x16x32_bf16 v[108:111], v[160:163], v[200:203], v[108:111]
	v_mfma_f32_16x16x32_bf16 v[104:107], v[168:171], v[200:203], v[104:107]
	v_mfma_f32_16x16x32_bf16 v[92:95], v[160:163], v[208:211], v[92:95]
	v_mfma_f32_16x16x32_bf16 v[88:91], v[168:171], v[208:211], v[88:91]
	v_mfma_f32_16x16x32_bf16 v[76:79], v[160:163], v[216:219], v[76:79]
	v_mfma_f32_16x16x32_bf16 v[72:75], v[168:171], v[216:219], v[72:75]
	v_mfma_f32_16x16x32_bf16 v[116:119], v[172:175], v[188:191], v[116:119]
	v_mfma_f32_16x16x32_bf16 v[112:115], v[180:183], v[188:191], v[112:115]
	v_mfma_f32_16x16x32_bf16 v[100:103], v[172:175], v[196:199], v[100:103]
	v_mfma_f32_16x16x32_bf16 v[96:99], v[180:183], v[196:199], v[96:99]
	v_mfma_f32_16x16x32_bf16 v[84:87], v[172:175], v[204:207], v[84:87]
	v_mfma_f32_16x16x32_bf16 v[80:83], v[180:183], v[204:207], v[80:83]
	v_mfma_f32_16x16x32_bf16 v[68:71], v[172:175], v[212:215], v[68:71]
	v_mfma_f32_16x16x32_bf16 v[64:67], v[180:183], v[212:215], v[64:67]
	v_mfma_f32_16x16x32_bf16 v[116:119], v[176:179], v[192:195], v[116:119]
	v_mfma_f32_16x16x32_bf16 v[112:115], v[184:187], v[192:195], v[112:115]
	v_mfma_f32_16x16x32_bf16 v[100:103], v[176:179], v[200:203], v[100:103]
	v_mfma_f32_16x16x32_bf16 v[96:99], v[184:187], v[200:203], v[96:99]
	v_mfma_f32_16x16x32_bf16 v[84:87], v[176:179], v[208:211], v[84:87]
	v_mfma_f32_16x16x32_bf16 v[80:83], v[184:187], v[208:211], v[80:83]
	v_mfma_f32_16x16x32_bf16 v[68:71], v[176:179], v[216:219], v[68:71]
	v_mfma_f32_16x16x32_bf16 v[64:67], v[184:187], v[216:219], v[64:67]
	s_setprio 0
	s_barrier
	s_add_i32 s76, s86, s94
	v_lshl_add_u64 v[220:221], v[220:221], 0, s[18:19]
	s_mov_b32 m0, s76
	ds_read_b128 v[188:191], v157 offset:49152
	ds_read_b128 v[192:195], v157 offset:50176
	ds_read_b128 v[196:199], v157 offset:51200
	ds_read_b128 v[200:203], v157 offset:52224
	ds_read_b128 v[204:207], v157 offset:53248
	ds_read_b128 v[208:211], v157 offset:54272
	ds_read_b128 v[212:215], v157 offset:55296
	ds_read_b128 v[216:219], v157 offset:56320
	global_load_lds_dwordx4 v[220:221], off
	s_add_i32 m0, s76, 0x2000
	s_add_u32 s74, s74, 0x80080
	v_lshl_add_u64 v[220:221], v[222:223], 0, s[18:19]
	s_addc_u32 s75, s75, 0
	s_add_i32 s76, s87, s94
	global_load_lds_dwordx4 v[220:221], off
	v_lshl_add_u64 v[220:221], s[74:75], 0, v[130:131]
	s_mov_b32 m0, s76
	s_nop 0
	global_load_lds_dwordx4 v[220:221], off
	v_lshl_add_u64 v[220:221], s[74:75], 0, v[134:135]
	s_add_i32 m0, s76, 0x2000
	s_nop 0
	global_load_lds_dwordx4 v[220:221], off
	v_lshl_add_u64 v[220:221], v[224:225], 0, s[18:19]
	s_mov_b32 m0, s34
	s_nop 0
	global_load_lds_dwordx4 v[220:221], off
	v_lshl_add_u64 v[220:221], v[226:227], 0, s[18:19]
	s_mov_b32 m0, s35
	s_nop 0
	global_load_lds_dwordx4 v[220:221], off
	s_waitcnt vmcnt(8)
	s_waitcnt lgkmcnt(0)
	s_setprio 1
	s_barrier
	v_mfma_f32_16x16x32_bf16 v[60:63], v[146:149], v[188:191], v[60:63]
	v_mfma_f32_16x16x32_bf16 v[56:59], v[164:167], v[188:191], v[56:59]
	v_mfma_f32_16x16x32_bf16 v[44:47], v[146:149], v[196:199], v[44:47]
	v_mfma_f32_16x16x32_bf16 v[40:43], v[164:167], v[196:199], v[40:43]
	v_mfma_f32_16x16x32_bf16 v[28:31], v[146:149], v[204:207], v[28:31]
	v_mfma_f32_16x16x32_bf16 v[24:27], v[164:167], v[204:207], v[24:27]
	v_mfma_f32_16x16x32_bf16 v[12:15], v[146:149], v[212:215], v[12:15]
	v_mfma_f32_16x16x32_bf16 v[8:11], v[164:167], v[212:215], v[8:11]
	v_mfma_f32_16x16x32_bf16 v[60:63], v[160:163], v[192:195], v[60:63]
	v_mfma_f32_16x16x32_bf16 v[56:59], v[168:171], v[192:195], v[56:59]
	v_mfma_f32_16x16x32_bf16 v[44:47], v[160:163], v[200:203], v[44:47]
	v_mfma_f32_16x16x32_bf16 v[40:43], v[168:171], v[200:203], v[40:43]
	v_mfma_f32_16x16x32_bf16 v[28:31], v[160:163], v[208:211], v[28:31]
	v_mfma_f32_16x16x32_bf16 v[24:27], v[168:171], v[208:211], v[24:27]
	v_mfma_f32_16x16x32_bf16 v[12:15], v[160:163], v[216:219], v[12:15]
	v_mfma_f32_16x16x32_bf16 v[8:11], v[168:171], v[216:219], v[8:11]
	v_mfma_f32_16x16x32_bf16 v[52:55], v[172:175], v[188:191], v[52:55]
	v_mfma_f32_16x16x32_bf16 v[48:51], v[180:183], v[188:191], v[48:51]
	v_mfma_f32_16x16x32_bf16 v[36:39], v[172:175], v[196:199], v[36:39]
	v_mfma_f32_16x16x32_bf16 v[32:35], v[180:183], v[196:199], v[32:35]
	v_mfma_f32_16x16x32_bf16 v[20:23], v[172:175], v[204:207], v[20:23]
	v_mfma_f32_16x16x32_bf16 v[16:19], v[180:183], v[204:207], v[16:19]
	v_mfma_f32_16x16x32_bf16 v[4:7], v[172:175], v[212:215], v[4:7]
	v_mfma_f32_16x16x32_bf16 v[0:3], v[180:183], v[212:215], v[0:3]
	v_mfma_f32_16x16x32_bf16 v[52:55], v[176:179], v[192:195], v[52:55]
	v_mfma_f32_16x16x32_bf16 v[48:51], v[184:187], v[192:195], v[48:51]
	v_mfma_f32_16x16x32_bf16 v[36:39], v[176:179], v[200:203], v[36:39]
	v_mfma_f32_16x16x32_bf16 v[32:35], v[184:187], v[200:203], v[32:35]
	v_mfma_f32_16x16x32_bf16 v[20:23], v[176:179], v[208:211], v[20:23]
	v_mfma_f32_16x16x32_bf16 v[16:19], v[184:187], v[208:211], v[16:19]
	v_mfma_f32_16x16x32_bf16 v[4:7], v[176:179], v[216:219], v[4:7]
	v_mfma_f32_16x16x32_bf16 v[0:3], v[184:187], v[216:219], v[0:3]
	s_setprio 0
	s_barrier
	s_add_i32 s85, s85, 2
	s_add_u32 s72, s72, 0x100
	s_addc_u32 s73, s73, 0
	s_add_u32 s83, s83, 0x100
	s_addc_u32 s84, s84, 0
	s_cmp_gt_u32 s85, 29
	s_cbranch_scc0 .LBB0_849
	s_and_b64 vcc, exec, s[20:21]
	s_cbranch_vccz .LBB0_852
	s_barrier

.LBB0_946:
	ds_read_b128 v[148:151], v143
	ds_read_b128 v[152:155], v143 offset:1024
	ds_read_b128 v[156:159], v143 offset:2048
	ds_read_b128 v[160:163], v143 offset:3072
	ds_read_b128 v[164:167], v144
	ds_read_b128 v[168:171], v144 offset:1024
	ds_read_b128 v[172:175], v144 offset:2048
	ds_read_b128 v[176:179], v144 offset:3072
	s_add_u32 s18, s14, s16
	s_addc_u32 s19, s15, s17
	s_add_u32 s18, s18, 0x7498100
	s_addc_u32 s19, s19, 0
	s_add_u32 s20, s24, s16
	s_addc_u32 s21, s25, s17
	s_add_u32 s69, s20, 0x1308100
	s_addc_u32 s70, s21, 0
	s_cmpk_eq_i32 s16, 0xf00
	s_cselect_b32 s21, s11, s19
	s_cselect_b32 s20, s10, s18
	s_cselect_b32 s19, s9, s70
	s_cselect_b32 s18, s8, s69
	s_mov_b32 m0, s46
	v_lshl_add_u64 v[212:213], v[136:137], 0, s[16:17]
	ds_read_b128 v[180:183], v145
	ds_read_b128 v[184:187], v145 offset:1024
	ds_read_b128 v[188:191], v145 offset:2048
	ds_read_b128 v[192:195], v145 offset:3072
	ds_read_b128 v[196:199], v145 offset:4096
	ds_read_b128 v[200:203], v145 offset:5120
	ds_read_b128 v[204:207], v145 offset:6144
	ds_read_b128 v[208:211], v145 offset:7168
	global_load_lds_dwordx4 v[212:213], off
	v_lshl_add_u64 v[212:213], v[138:139], 0, s[16:17]
	s_mov_b32 m0, s56
	s_nop 0
	global_load_lds_dwordx4 v[212:213], off
	s_waitcnt vmcnt(8)
	s_waitcnt lgkmcnt(0)
	s_setprio 1
	s_barrier
	v_mfma_f32_16x16x32_bf16 v[124:127], v[148:151], v[180:183], v[124:127]
	v_mfma_f32_16x16x32_bf16 v[120:123], v[156:159], v[180:183], v[120:123]
	v_mfma_f32_16x16x32_bf16 v[108:111], v[148:151], v[188:191], v[108:111]
	v_mfma_f32_16x16x32_bf16 v[104:107], v[156:159], v[188:191], v[104:107]
	v_mfma_f32_16x16x32_bf16 v[92:95], v[148:151], v[196:199], v[92:95]
	v_mfma_f32_16x16x32_bf16 v[88:91], v[156:159], v[196:199], v[88:91]
	v_mfma_f32_16x16x32_bf16 v[76:79], v[148:151], v[204:207], v[76:79]
	v_mfma_f32_16x16x32_bf16 v[72:75], v[156:159], v[204:207], v[72:75]
	v_mfma_f32_16x16x32_bf16 v[124:127], v[152:155], v[184:187], v[124:127]
	v_mfma_f32_16x16x32_bf16 v[120:123], v[160:163], v[184:187], v[120:123]
	v_mfma_f32_16x16x32_bf16 v[108:111], v[152:155], v[192:195], v[108:111]
	v_mfma_f32_16x16x32_bf16 v[104:107], v[160:163], v[192:195], v[104:107]
	v_mfma_f32_16x16x32_bf16 v[92:95], v[152:155], v[200:203], v[92:95]
	v_mfma_f32_16x16x32_bf16 v[88:91], v[160:163], v[200:203], v[88:91]
	v_mfma_f32_16x16x32_bf16 v[76:79], v[152:155], v[208:211], v[76:79]
	v_mfma_f32_16x16x32_bf16 v[72:75], v[160:163], v[208:211], v[72:75]
	v_mfma_f32_16x16x32_bf16 v[116:119], v[164:167], v[180:183], v[116:119]
	v_mfma_f32_16x16x32_bf16 v[112:115], v[172:175], v[180:183], v[112:115]
	v_mfma_f32_16x16x32_bf16 v[100:103], v[164:167], v[188:191], v[100:103]
	v_mfma_f32_16x16x32_bf16 v[96:99], v[172:175], v[188:191], v[96:99]
	v_mfma_f32_16x16x32_bf16 v[84:87], v[164:167], v[196:199], v[84:87]
	v_mfma_f32_16x16x32_bf16 v[80:83], v[172:175], v[196:199], v[80:83]
	v_mfma_f32_16x16x32_bf16 v[68:71], v[164:167], v[204:207], v[68:71]
	v_mfma_f32_16x16x32_bf16 v[64:67], v[172:175], v[204:207], v[64:67]
	v_mfma_f32_16x16x32_bf16 v[116:119], v[168:171], v[184:187], v[116:119]
	v_mfma_f32_16x16x32_bf16 v[112:115], v[176:179], v[184:187], v[112:115]
	v_mfma_f32_16x16x32_bf16 v[100:103], v[168:171], v[192:195], v[100:103]
	v_mfma_f32_16x16x32_bf16 v[96:99], v[176:179], v[192:195], v[96:99]
	v_mfma_f32_16x16x32_bf16 v[84:87], v[168:171], v[200:203], v[84:87]
	v_mfma_f32_16x16x32_bf16 v[80:83], v[176:179], v[200:203], v[80:83]
	v_mfma_f32_16x16x32_bf16 v[68:71], v[168:171], v[208:211], v[68:71]
	v_mfma_f32_16x16x32_bf16 v[64:67], v[176:179], v[208:211], v[64:67]
	s_setprio 0
	s_barrier
	s_mov_b32 m0, s57
	v_lshl_add_u64 v[212:213], s[18:19], 0, v[132:133]
	s_add_u32 s70, s18, 0x80000
	ds_read_b128 v[180:183], v145 offset:16384
	ds_read_b128 v[184:187], v145 offset:17408
	ds_read_b128 v[188:191], v145 offset:18432
	ds_read_b128 v[192:195], v145 offset:19456
	ds_read_b128 v[196:199], v145 offset:20480
	ds_read_b128 v[200:203], v145 offset:21504
	ds_read_b128 v[204:207], v145 offset:22528
	ds_read_b128 v[208:211], v145 offset:23552
	global_load_lds_dwordx4 v[212:213], off
	v_lshl_add_u64 v[214:215], s[18:19], 0, v[128:129]
	s_mov_b32 m0, s62
	s_addc_u32 s71, s19, 0
	global_load_lds_dwordx4 v[214:215], off
	v_lshl_add_u64 v[216:217], s[70:71], 0, v[132:133]
	s_mov_b32 m0, s63
	v_lshl_add_u64 v[218:219], s[20:21], 0, v[130:131]
	global_load_lds_dwordx4 v[216:217], off
	v_lshl_add_u64 v[216:217], s[70:71], 0, v[128:129]
	s_mov_b32 m0, s64
	s_nop 0
	global_load_lds_dwordx4 v[216:217], off
	v_lshl_add_u64 v[216:217], s[20:21], 0, v[134:135]
	s_mov_b32 m0, s3
	s_nop 0
	global_load_lds_dwordx4 v[216:217], off
	s_mov_b32 m0, s6
	s_nop 0
	global_load_lds_dwordx4 v[218:219], off
	s_waitcnt vmcnt(8)
	s_waitcnt lgkmcnt(0)
	s_setprio 1
	s_barrier
	v_mfma_f32_16x16x32_bf16 v[60:63], v[148:151], v[180:183], v[60:63]
	v_mfma_f32_16x16x32_bf16 v[56:59], v[156:159], v[180:183], v[56:59]
	v_mfma_f32_16x16x32_bf16 v[44:47], v[148:151], v[188:191], v[44:47]
	v_mfma_f32_16x16x32_bf16 v[40:43], v[156:159], v[188:191], v[40:43]
	v_mfma_f32_16x16x32_bf16 v[28:31], v[148:151], v[196:199], v[28:31]
	v_mfma_f32_16x16x32_bf16 v[24:27], v[156:159], v[196:199], v[24:27]
	v_mfma_f32_16x16x32_bf16 v[12:15], v[148:151], v[204:207], v[12:15]
	v_mfma_f32_16x16x32_bf16 v[8:11], v[156:159], v[204:207], v[8:11]
	v_mfma_f32_16x16x32_bf16 v[60:63], v[152:155], v[184:187], v[60:63]
	v_mfma_f32_16x16x32_bf16 v[56:59], v[160:163], v[184:187], v[56:59]
	v_mfma_f32_16x16x32_bf16 v[44:47], v[152:155], v[192:195], v[44:47]
	v_mfma_f32_16x16x32_bf16 v[40:43], v[160:163], v[192:195], v[40:43]
	v_mfma_f32_16x16x32_bf16 v[28:31], v[152:155], v[200:203], v[28:31]
	v_mfma_f32_16x16x32_bf16 v[24:27], v[160:163], v[200:203], v[24:27]
	v_mfma_f32_16x16x32_bf16 v[12:15], v[152:155], v[208:211], v[12:15]
	v_mfma_f32_16x16x32_bf16 v[8:11], v[160:163], v[208:211], v[8:11]
	v_mfma_f32_16x16x32_bf16 v[52:55], v[164:167], v[180:183], v[52:55]
	v_mfma_f32_16x16x32_bf16 v[48:51], v[172:175], v[180:183], v[48:51]
	v_mfma_f32_16x16x32_bf16 v[36:39], v[164:167], v[188:191], v[36:39]
	v_mfma_f32_16x16x32_bf16 v[32:35], v[172:175], v[188:191], v[32:35]
	v_mfma_f32_16x16x32_bf16 v[20:23], v[164:167], v[196:199], v[20:23]
	v_mfma_f32_16x16x32_bf16 v[16:19], v[172:175], v[196:199], v[16:19]
	v_mfma_f32_16x16x32_bf16 v[4:7], v[164:167], v[204:207], v[4:7]
	v_mfma_f32_16x16x32_bf16 v[0:3], v[172:175], v[204:207], v[0:3]
	v_mfma_f32_16x16x32_bf16 v[52:55], v[168:171], v[184:187], v[52:55]
	v_mfma_f32_16x16x32_bf16 v[48:51], v[176:179], v[184:187], v[48:51]
	v_mfma_f32_16x16x32_bf16 v[36:39], v[168:171], v[192:195], v[36:39]
	v_mfma_f32_16x16x32_bf16 v[32:35], v[176:179], v[192:195], v[32:35]
	v_mfma_f32_16x16x32_bf16 v[20:23], v[168:171], v[200:203], v[20:23]
	v_mfma_f32_16x16x32_bf16 v[16:19], v[176:179], v[200:203], v[16:19]
	v_mfma_f32_16x16x32_bf16 v[4:7], v[168:171], v[208:211], v[4:7]
	v_mfma_f32_16x16x32_bf16 v[0:3], v[176:179], v[208:211], v[0:3]
	s_setprio 0
	s_barrier
	ds_read_b128 v[148:151], v146
	ds_read_b128 v[152:155], v146 offset:1024
	ds_read_b128 v[156:159], v146 offset:2048
	ds_read_b128 v[160:163], v146 offset:3072
	ds_read_b128 v[164:167], v147
	ds_read_b128 v[168:171], v147 offset:1024
	ds_read_b128 v[172:175], v147 offset:2048
	ds_read_b128 v[176:179], v147 offset:3072
	s_add_u32 s20, s20, 0x80000
	s_addc_u32 s21, s21, 0
	s_mov_b32 m0, s7
	v_lshl_add_u64 v[220:221], s[20:21], 0, v[134:135]
	ds_read_b128 v[180:183], v145 offset:32768
	ds_read_b128 v[184:187], v145 offset:33792
	ds_read_b128 v[188:191], v145 offset:34816
	ds_read_b128 v[192:195], v145 offset:35840
	ds_read_b128 v[196:199], v145 offset:36864
	ds_read_b128 v[200:203], v145 offset:37888
	ds_read_b128 v[204:207], v145 offset:38912
	ds_read_b128 v[208:211], v145 offset:39936
	global_load_lds_dwordx4 v[220:221], off
	v_lshl_add_u64 v[220:221], s[20:21], 0, v[130:131]
	s_mov_b32 m0, s29
	s_nop 0
	global_load_lds_dwordx4 v[220:221], off
	s_waitcnt vmcnt(8)
	s_waitcnt lgkmcnt(0)
	s_setprio 1
	s_barrier
	v_mfma_f32_16x16x32_bf16 v[124:127], v[148:151], v[180:183], v[124:127]
	v_mfma_f32_16x16x32_bf16 v[120:123], v[156:159], v[180:183], v[120:123]
	v_mfma_f32_16x16x32_bf16 v[108:111], v[148:151], v[188:191], v[108:111]
	v_mfma_f32_16x16x32_bf16 v[104:107], v[156:159], v[188:191], v[104:107]
	v_mfma_f32_16x16x32_bf16 v[92:95], v[148:151], v[196:199], v[92:95]
	v_mfma_f32_16x16x32_bf16 v[88:91], v[156:159], v[196:199], v[88:91]
	v_mfma_f32_16x16x32_bf16 v[76:79], v[148:151], v[204:207], v[76:79]
	v_mfma_f32_16x16x32_bf16 v[72:75], v[156:159], v[204:207], v[72:75]
	v_mfma_f32_16x16x32_bf16 v[124:127], v[152:155], v[184:187], v[124:127]
	v_mfma_f32_16x16x32_bf16 v[120:123], v[160:163], v[184:187], v[120:123]
	v_mfma_f32_16x16x32_bf16 v[108:111], v[152:155], v[192:195], v[108:111]
	v_mfma_f32_16x16x32_bf16 v[104:107], v[160:163], v[192:195], v[104:107]
	v_mfma_f32_16x16x32_bf16 v[92:95], v[152:155], v[200:203], v[92:95]
	v_mfma_f32_16x16x32_bf16 v[88:91], v[160:163], v[200:203], v[88:91]
	v_mfma_f32_16x16x32_bf16 v[76:79], v[152:155], v[208:211], v[76:79]
	v_mfma_f32_16x16x32_bf16 v[72:75], v[160:163], v[208:211], v[72:75]
	v_mfma_f32_16x16x32_bf16 v[116:119], v[164:167], v[180:183], v[116:119]
	v_mfma_f32_16x16x32_bf16 v[112:115], v[172:175], v[180:183], v[112:115]
	v_mfma_f32_16x16x32_bf16 v[100:103], v[164:167], v[188:191], v[100:103]
	v_mfma_f32_16x16x32_bf16 v[96:99], v[172:175], v[188:191], v[96:99]
	v_mfma_f32_16x16x32_bf16 v[84:87], v[164:167], v[196:199], v[84:87]
	v_mfma_f32_16x16x32_bf16 v[80:83], v[172:175], v[196:199], v[80:83]
	v_mfma_f32_16x16x32_bf16 v[68:71], v[164:167], v[204:207], v[68:71]
	v_mfma_f32_16x16x32_bf16 v[64:67], v[172:175], v[204:207], v[64:67]
	v_mfma_f32_16x16x32_bf16 v[116:119], v[168:171], v[184:187], v[116:119]
	v_mfma_f32_16x16x32_bf16 v[112:115], v[176:179], v[184:187], v[112:115]
	v_mfma_f32_16x16x32_bf16 v[100:103], v[168:171], v[192:195], v[100:103]
	v_mfma_f32_16x16x32_bf16 v[96:99], v[176:179], v[192:195], v[96:99]
	v_mfma_f32_16x16x32_bf16 v[84:87], v[168:171], v[200:203], v[84:87]
	v_mfma_f32_16x16x32_bf16 v[80:83], v[176:179], v[200:203], v[80:83]
	v_mfma_f32_16x16x32_bf16 v[68:71], v[168:171], v[208:211], v[68:71]
	v_mfma_f32_16x16x32_bf16 v[64:67], v[176:179], v[208:211], v[64:67]
	s_setprio 0
	s_barrier
	s_mov_b32 m0, s65
	v_lshl_add_u64 v[212:213], v[212:213], 0, s[12:13]
	s_add_u32 s18, s18, 0x80080
	ds_read_b128 v[180:183], v145 offset:49152
	ds_read_b128 v[184:187], v145 offset:50176
	ds_read_b128 v[188:191], v145 offset:51200
	ds_read_b128 v[192:195], v145 offset:52224
	ds_read_b128 v[196:199], v145 offset:53248
	ds_read_b128 v[200:203], v145 offset:54272
	ds_read_b128 v[204:207], v145 offset:55296
	ds_read_b128 v[208:211], v145 offset:56320
	global_load_lds_dwordx4 v[212:213], off
	v_lshl_add_u64 v[212:213], v[214:215], 0, s[12:13]
	s_mov_b32 m0, s66
	s_addc_u32 s19, s19, 0
	global_load_lds_dwordx4 v[212:213], off
	v_lshl_add_u64 v[212:213], s[18:19], 0, v[132:133]
	s_mov_b32 m0, s67
	s_nop 0
	global_load_lds_dwordx4 v[212:213], off
	v_lshl_add_u64 v[212:213], s[18:19], 0, v[128:129]
	s_mov_b32 m0, s68
	s_nop 0
	global_load_lds_dwordx4 v[212:213], off
	v_lshl_add_u64 v[212:213], v[216:217], 0, s[12:13]
	s_mov_b32 m0, s30
	s_nop 0
	global_load_lds_dwordx4 v[212:213], off
	v_lshl_add_u64 v[212:213], v[218:219], 0, s[12:13]
	s_mov_b32 m0, s34
	s_nop 0
	global_load_lds_dwordx4 v[212:213], off
	s_waitcnt vmcnt(8)
	s_waitcnt lgkmcnt(0)
	s_setprio 1
	s_barrier
	v_mfma_f32_16x16x32_bf16 v[60:63], v[148:151], v[180:183], v[60:63]
	v_mfma_f32_16x16x32_bf16 v[56:59], v[156:159], v[180:183], v[56:59]
	v_mfma_f32_16x16x32_bf16 v[44:47], v[148:151], v[188:191], v[44:47]
	v_mfma_f32_16x16x32_bf16 v[40:43], v[156:159], v[188:191], v[40:43]
	v_mfma_f32_16x16x32_bf16 v[28:31], v[148:151], v[196:199], v[28:31]
	v_mfma_f32_16x16x32_bf16 v[24:27], v[156:159], v[196:199], v[24:27]
	v_mfma_f32_16x16x32_bf16 v[12:15], v[148:151], v[204:207], v[12:15]
	v_mfma_f32_16x16x32_bf16 v[8:11], v[156:159], v[204:207], v[8:11]
	v_mfma_f32_16x16x32_bf16 v[60:63], v[152:155], v[184:187], v[60:63]
	v_mfma_f32_16x16x32_bf16 v[56:59], v[160:163], v[184:187], v[56:59]
	v_mfma_f32_16x16x32_bf16 v[44:47], v[152:155], v[192:195], v[44:47]
	v_mfma_f32_16x16x32_bf16 v[40:43], v[160:163], v[192:195], v[40:43]
	v_mfma_f32_16x16x32_bf16 v[28:31], v[152:155], v[200:203], v[28:31]
	v_mfma_f32_16x16x32_bf16 v[24:27], v[160:163], v[200:203], v[24:27]
	v_mfma_f32_16x16x32_bf16 v[12:15], v[152:155], v[208:211], v[12:15]
	v_mfma_f32_16x16x32_bf16 v[8:11], v[160:163], v[208:211], v[8:11]
	v_mfma_f32_16x16x32_bf16 v[52:55], v[164:167], v[180:183], v[52:55]
	v_mfma_f32_16x16x32_bf16 v[48:51], v[172:175], v[180:183], v[48:51]
	v_mfma_f32_16x16x32_bf16 v[36:39], v[164:167], v[188:191], v[36:39]
	v_mfma_f32_16x16x32_bf16 v[32:35], v[172:175], v[188:191], v[32:35]
	v_mfma_f32_16x16x32_bf16 v[20:23], v[164:167], v[196:199], v[20:23]
	v_mfma_f32_16x16x32_bf16 v[16:19], v[172:175], v[196:199], v[16:19]
	v_mfma_f32_16x16x32_bf16 v[4:7], v[164:167], v[204:207], v[4:7]
	v_mfma_f32_16x16x32_bf16 v[0:3], v[172:175], v[204:207], v[0:3]
	v_mfma_f32_16x16x32_bf16 v[52:55], v[168:171], v[184:187], v[52:55]
	v_mfma_f32_16x16x32_bf16 v[48:51], v[176:179], v[184:187], v[48:51]
	v_mfma_f32_16x16x32_bf16 v[36:39], v[168:171], v[192:195], v[36:39]
	v_mfma_f32_16x16x32_bf16 v[32:35], v[176:179], v[192:195], v[32:35]
	v_mfma_f32_16x16x32_bf16 v[20:23], v[168:171], v[200:203], v[20:23]
	v_mfma_f32_16x16x32_bf16 v[16:19], v[176:179], v[200:203], v[16:19]
	v_mfma_f32_16x16x32_bf16 v[4:7], v[168:171], v[208:211], v[4:7]
	v_mfma_f32_16x16x32_bf16 v[0:3], v[176:179], v[208:211], v[0:3]
	s_setprio 0
	s_barrier
	s_add_i32 s35, s35, 2
	s_add_u32 s16, s16, 0x100
	s_addc_u32 s17, s17, 0
	s_cmp_gt_u32 s35, 29
	s_cbranch_scc0 .LBB0_946
	s_cmpk_lt_u32 s80, 0x100
	s_cbranch_scc0 .LBB0_949
	s_barrier

.LBB0_1693:
	ds_read_b128 v[140:143], v149
	ds_read_b128 v[152:155], v149 offset:1024
	ds_read_b128 v[156:159], v149 offset:2048
	ds_read_b128 v[160:163], v149 offset:3072
	ds_read_b128 v[164:167], v150
	ds_read_b128 v[168:171], v150 offset:1024
	ds_read_b128 v[172:175], v150 offset:2048
	ds_read_b128 v[176:179], v150 offset:3072
	s_add_u32 s76, s74, 0xfff80080
	s_addc_u32 s77, s75, -1
	s_cmp_eq_u32 s86, 28
	s_cselect_b32 s79, s67, s77
	s_cselect_b32 s78, s73, s76
	s_cselect_b32 s77, s65, s85
	s_cselect_b32 s76, s83, s84
	v_lshl_add_u64 v[212:213], s[74:75], 0, v[132:133]
	s_add_i32 m0, s6, 0xc000
	ds_read_b128 v[180:183], v151
	ds_read_b128 v[184:187], v151 offset:1024
	ds_read_b128 v[188:191], v151 offset:2048
	ds_read_b128 v[192:195], v151 offset:3072
	ds_read_b128 v[196:199], v151 offset:4096
	ds_read_b128 v[200:203], v151 offset:5120
	ds_read_b128 v[204:207], v151 offset:6144
	ds_read_b128 v[208:211], v151 offset:7168
	global_load_lds_dwordx4 v[212:213], off
	v_lshl_add_u64 v[212:213], s[74:75], 0, v[134:135]
	s_add_i32 m0, s6, 0xe000
	s_nop 0
	global_load_lds_dwordx4 v[212:213], off
	s_waitcnt vmcnt(8)
	s_waitcnt lgkmcnt(0)
	s_setprio 1
	s_barrier
	v_mfma_f32_16x16x32_bf16 v[124:127], v[140:143], v[180:183], v[124:127]
	v_mfma_f32_16x16x32_bf16 v[120:123], v[156:159], v[180:183], v[120:123]
	v_mfma_f32_16x16x32_bf16 v[108:111], v[140:143], v[188:191], v[108:111]
	v_mfma_f32_16x16x32_bf16 v[104:107], v[156:159], v[188:191], v[104:107]
	v_mfma_f32_16x16x32_bf16 v[92:95], v[140:143], v[196:199], v[92:95]
	v_mfma_f32_16x16x32_bf16 v[88:91], v[156:159], v[196:199], v[88:91]
	v_mfma_f32_16x16x32_bf16 v[76:79], v[140:143], v[204:207], v[76:79]
	v_mfma_f32_16x16x32_bf16 v[72:75], v[156:159], v[204:207], v[72:75]
	v_mfma_f32_16x16x32_bf16 v[124:127], v[152:155], v[184:187], v[124:127]
	v_mfma_f32_16x16x32_bf16 v[120:123], v[160:163], v[184:187], v[120:123]
	v_mfma_f32_16x16x32_bf16 v[108:111], v[152:155], v[192:195], v[108:111]
	v_mfma_f32_16x16x32_bf16 v[104:107], v[160:163], v[192:195], v[104:107]
	v_mfma_f32_16x16x32_bf16 v[92:95], v[152:155], v[200:203], v[92:95]
	v_mfma_f32_16x16x32_bf16 v[88:91], v[160:163], v[200:203], v[88:91]
	v_mfma_f32_16x16x32_bf16 v[76:79], v[152:155], v[208:211], v[76:79]
	v_mfma_f32_16x16x32_bf16 v[72:75], v[160:163], v[208:211], v[72:75]
	v_mfma_f32_16x16x32_bf16 v[116:119], v[164:167], v[180:183], v[116:119]
	v_mfma_f32_16x16x32_bf16 v[112:115], v[172:175], v[180:183], v[112:115]
	v_mfma_f32_16x16x32_bf16 v[100:103], v[164:167], v[188:191], v[100:103]
	v_mfma_f32_16x16x32_bf16 v[96:99], v[172:175], v[188:191], v[96:99]
	v_mfma_f32_16x16x32_bf16 v[84:87], v[164:167], v[196:199], v[84:87]
	v_mfma_f32_16x16x32_bf16 v[80:83], v[172:175], v[196:199], v[80:83]
	v_mfma_f32_16x16x32_bf16 v[68:71], v[164:167], v[204:207], v[68:71]
	v_mfma_f32_16x16x32_bf16 v[64:67], v[172:175], v[204:207], v[64:67]
	v_mfma_f32_16x16x32_bf16 v[116:119], v[168:171], v[184:187], v[116:119]
	v_mfma_f32_16x16x32_bf16 v[112:115], v[176:179], v[184:187], v[112:115]
	v_mfma_f32_16x16x32_bf16 v[100:103], v[168:171], v[192:195], v[100:103]
	v_mfma_f32_16x16x32_bf16 v[96:99], v[176:179], v[192:195], v[96:99]
	v_mfma_f32_16x16x32_bf16 v[84:87], v[168:171], v[200:203], v[84:87]
	v_mfma_f32_16x16x32_bf16 v[80:83], v[176:179], v[200:203], v[80:83]
	v_mfma_f32_16x16x32_bf16 v[68:71], v[168:171], v[208:211], v[68:71]
	v_mfma_f32_16x16x32_bf16 v[64:67], v[176:179], v[208:211], v[64:67]
	s_setprio 0
	s_barrier
	s_add_i32 s87, s57, s94
	v_lshl_add_u64 v[212:213], s[76:77], 0, v[128:129]
	s_mov_b32 m0, s87
	ds_read_b128 v[180:183], v151 offset:16384
	ds_read_b128 v[184:187], v151 offset:17408
	ds_read_b128 v[188:191], v151 offset:18432
	ds_read_b128 v[192:195], v151 offset:19456
	ds_read_b128 v[196:199], v151 offset:20480
	ds_read_b128 v[200:203], v151 offset:21504
	ds_read_b128 v[204:207], v151 offset:22528
	ds_read_b128 v[208:211], v151 offset:23552
	global_load_lds_dwordx4 v[212:213], off
	s_add_i32 m0, s87, 0x2000
	s_add_u32 s88, s76, 0x80000
	v_lshl_add_u64 v[214:215], s[76:77], 0, v[130:131]
	s_addc_u32 s89, s77, 0
	s_add_i32 s87, s81, s94
	global_load_lds_dwordx4 v[214:215], off
	v_lshl_add_u64 v[216:217], s[88:89], 0, v[128:129]
	s_mov_b32 m0, s87
	v_lshl_add_u64 v[218:219], s[78:79], 0, v[130:131]
	global_load_lds_dwordx4 v[216:217], off
	v_lshl_add_u64 v[216:217], s[88:89], 0, v[130:131]
	s_add_i32 m0, s87, 0x2000
	s_nop 0
	global_load_lds_dwordx4 v[216:217], off
	v_lshl_add_u64 v[216:217], s[78:79], 0, v[128:129]
	s_mov_b32 m0, s6
	s_nop 0
	global_load_lds_dwordx4 v[216:217], off
	s_mov_b32 m0, s7
	s_nop 0
	global_load_lds_dwordx4 v[218:219], off
	s_waitcnt vmcnt(8)
	s_waitcnt lgkmcnt(0)
	s_setprio 1
	s_barrier
	v_mfma_f32_16x16x32_bf16 v[60:63], v[140:143], v[180:183], v[60:63]
	v_mfma_f32_16x16x32_bf16 v[56:59], v[156:159], v[180:183], v[56:59]
	v_mfma_f32_16x16x32_bf16 v[44:47], v[140:143], v[188:191], v[44:47]
	v_mfma_f32_16x16x32_bf16 v[40:43], v[156:159], v[188:191], v[40:43]
	v_mfma_f32_16x16x32_bf16 v[28:31], v[140:143], v[196:199], v[28:31]
	v_mfma_f32_16x16x32_bf16 v[24:27], v[156:159], v[196:199], v[24:27]
	v_mfma_f32_16x16x32_bf16 v[12:15], v[140:143], v[204:207], v[12:15]
	v_mfma_f32_16x16x32_bf16 v[8:11], v[156:159], v[204:207], v[8:11]
	v_mfma_f32_16x16x32_bf16 v[60:63], v[152:155], v[184:187], v[60:63]
	v_mfma_f32_16x16x32_bf16 v[56:59], v[160:163], v[184:187], v[56:59]
	v_mfma_f32_16x16x32_bf16 v[44:47], v[152:155], v[192:195], v[44:47]
	v_mfma_f32_16x16x32_bf16 v[40:43], v[160:163], v[192:195], v[40:43]
	v_mfma_f32_16x16x32_bf16 v[28:31], v[152:155], v[200:203], v[28:31]
	v_mfma_f32_16x16x32_bf16 v[24:27], v[160:163], v[200:203], v[24:27]
	v_mfma_f32_16x16x32_bf16 v[12:15], v[152:155], v[208:211], v[12:15]
	v_mfma_f32_16x16x32_bf16 v[8:11], v[160:163], v[208:211], v[8:11]
	v_mfma_f32_16x16x32_bf16 v[52:55], v[164:167], v[180:183], v[52:55]
	v_mfma_f32_16x16x32_bf16 v[48:51], v[172:175], v[180:183], v[48:51]
	v_mfma_f32_16x16x32_bf16 v[36:39], v[164:167], v[188:191], v[36:39]
	v_mfma_f32_16x16x32_bf16 v[32:35], v[172:175], v[188:191], v[32:35]
	v_mfma_f32_16x16x32_bf16 v[20:23], v[164:167], v[196:199], v[20:23]
	v_mfma_f32_16x16x32_bf16 v[16:19], v[172:175], v[196:199], v[16:19]
	v_mfma_f32_16x16x32_bf16 v[4:7], v[164:167], v[204:207], v[4:7]
	v_mfma_f32_16x16x32_bf16 v[0:3], v[172:175], v[204:207], v[0:3]
	v_mfma_f32_16x16x32_bf16 v[52:55], v[168:171], v[184:187], v[52:55]
	v_mfma_f32_16x16x32_bf16 v[48:51], v[176:179], v[184:187], v[48:51]
	v_mfma_f32_16x16x32_bf16 v[36:39], v[168:171], v[192:195], v[36:39]
	v_mfma_f32_16x16x32_bf16 v[32:35], v[176:179], v[192:195], v[32:35]
	v_mfma_f32_16x16x32_bf16 v[20:23], v[168:171], v[200:203], v[20:23]
	v_mfma_f32_16x16x32_bf16 v[16:19], v[176:179], v[200:203], v[16:19]
	v_mfma_f32_16x16x32_bf16 v[4:7], v[168:171], v[208:211], v[4:7]
	v_mfma_f32_16x16x32_bf16 v[0:3], v[176:179], v[208:211], v[0:3]
	s_setprio 0
	s_barrier
	s_add_i32 s87, 0, 0x18000
	s_add_i32 s88, 0, 0x1c000
	v_add_u32_e32 v160, s87, v145
	v_add_u32_e32 v176, s88, v145
	ds_read_b128 v[140:143], v160
	ds_read_b128 v[152:155], v160 offset:1024
	ds_read_b128 v[156:159], v160 offset:2048
	ds_read_b128 v[160:163], v160 offset:3072
	ds_read_b128 v[164:167], v176
	ds_read_b128 v[168:171], v176 offset:1024
	ds_read_b128 v[172:175], v176 offset:2048
	ds_read_b128 v[176:179], v176 offset:3072
	s_add_u32 s78, s78, 0x80000
	s_addc_u32 s79, s79, 0
	s_mov_b32 m0, s29
	v_lshl_add_u64 v[220:221], s[78:79], 0, v[128:129]
	ds_read_b128 v[180:183], v151 offset:32768
	ds_read_b128 v[184:187], v151 offset:33792
	ds_read_b128 v[188:191], v151 offset:34816
	ds_read_b128 v[192:195], v151 offset:35840
	ds_read_b128 v[196:199], v151 offset:36864
	ds_read_b128 v[200:203], v151 offset:37888
	ds_read_b128 v[204:207], v151 offset:38912
	ds_read_b128 v[208:211], v151 offset:39936
	global_load_lds_dwordx4 v[220:221], off
	v_lshl_add_u64 v[220:221], s[78:79], 0, v[130:131]
	s_mov_b32 m0, s30
	s_nop 0
	global_load_lds_dwordx4 v[220:221], off
	s_waitcnt vmcnt(8)
	s_waitcnt lgkmcnt(0)
	s_setprio 1
	s_barrier
	v_mfma_f32_16x16x32_bf16 v[124:127], v[140:143], v[180:183], v[124:127]
	v_mfma_f32_16x16x32_bf16 v[120:123], v[156:159], v[180:183], v[120:123]
	v_mfma_f32_16x16x32_bf16 v[108:111], v[140:143], v[188:191], v[108:111]
	v_mfma_f32_16x16x32_bf16 v[104:107], v[156:159], v[188:191], v[104:107]
	v_mfma_f32_16x16x32_bf16 v[92:95], v[140:143], v[196:199], v[92:95]
	v_mfma_f32_16x16x32_bf16 v[88:91], v[156:159], v[196:199], v[88:91]
	v_mfma_f32_16x16x32_bf16 v[76:79], v[140:143], v[204:207], v[76:79]
	v_mfma_f32_16x16x32_bf16 v[72:75], v[156:159], v[204:207], v[72:75]
	v_mfma_f32_16x16x32_bf16 v[124:127], v[152:155], v[184:187], v[124:127]
	v_mfma_f32_16x16x32_bf16 v[120:123], v[160:163], v[184:187], v[120:123]
	v_mfma_f32_16x16x32_bf16 v[108:111], v[152:155], v[192:195], v[108:111]
	v_mfma_f32_16x16x32_bf16 v[104:107], v[160:163], v[192:195], v[104:107]
	v_mfma_f32_16x16x32_bf16 v[92:95], v[152:155], v[200:203], v[92:95]
	v_mfma_f32_16x16x32_bf16 v[88:91], v[160:163], v[200:203], v[88:91]
	v_mfma_f32_16x16x32_bf16 v[76:79], v[152:155], v[208:211], v[76:79]
	v_mfma_f32_16x16x32_bf16 v[72:75], v[160:163], v[208:211], v[72:75]
	v_mfma_f32_16x16x32_bf16 v[116:119], v[164:167], v[180:183], v[116:119]
	v_mfma_f32_16x16x32_bf16 v[112:115], v[172:175], v[180:183], v[112:115]
	v_mfma_f32_16x16x32_bf16 v[100:103], v[164:167], v[188:191], v[100:103]
	v_mfma_f32_16x16x32_bf16 v[96:99], v[172:175], v[188:191], v[96:99]
	v_mfma_f32_16x16x32_bf16 v[84:87], v[164:167], v[196:199], v[84:87]
	v_mfma_f32_16x16x32_bf16 v[80:83], v[172:175], v[196:199], v[80:83]
	v_mfma_f32_16x16x32_bf16 v[68:71], v[164:167], v[204:207], v[68:71]
	v_mfma_f32_16x16x32_bf16 v[64:67], v[172:175], v[204:207], v[64:67]
	v_mfma_f32_16x16x32_bf16 v[116:119], v[168:171], v[184:187], v[116:119]
	v_mfma_f32_16x16x32_bf16 v[112:115], v[176:179], v[184:187], v[112:115]
	v_mfma_f32_16x16x32_bf16 v[100:103], v[168:171], v[192:195], v[100:103]
	v_mfma_f32_16x16x32_bf16 v[96:99], v[176:179], v[192:195], v[96:99]
	v_mfma_f32_16x16x32_bf16 v[84:87], v[168:171], v[200:203], v[84:87]
	v_mfma_f32_16x16x32_bf16 v[80:83], v[176:179], v[200:203], v[80:83]
	v_mfma_f32_16x16x32_bf16 v[68:71], v[168:171], v[208:211], v[68:71]
	v_mfma_f32_16x16x32_bf16 v[64:67], v[176:179], v[208:211], v[64:67]
	s_setprio 0
	s_barrier
	s_add_i32 s78, s87, s94
	v_lshl_add_u64 v[212:213], v[212:213], 0, s[58:59]
	s_mov_b32 m0, s78
	ds_read_b128 v[180:183], v151 offset:49152
	ds_read_b128 v[184:187], v151 offset:50176
	ds_read_b128 v[188:191], v151 offset:51200
	ds_read_b128 v[192:195], v151 offset:52224
	ds_read_b128 v[196:199], v151 offset:53248
	ds_read_b128 v[200:203], v151 offset:54272
	ds_read_b128 v[204:207], v151 offset:55296
	ds_read_b128 v[208:211], v151 offset:56320
	global_load_lds_dwordx4 v[212:213], off
	s_add_i32 m0, s78, 0x2000
	s_add_u32 s76, s76, 0x80080
	v_lshl_add_u64 v[212:213], v[214:215], 0, s[58:59]
	s_addc_u32 s77, s77, 0
	s_add_i32 s78, s88, s94
	global_load_lds_dwordx4 v[212:213], off
	v_lshl_add_u64 v[212:213], s[76:77], 0, v[128:129]
	s_mov_b32 m0, s78
	s_nop 0
	global_load_lds_dwordx4 v[212:213], off
	v_lshl_add_u64 v[212:213], s[76:77], 0, v[130:131]
	s_add_i32 m0, s78, 0x2000
	s_nop 0
	global_load_lds_dwordx4 v[212:213], off
	v_lshl_add_u64 v[212:213], v[216:217], 0, s[58:59]
	s_mov_b32 m0, s34
	s_nop 0
	global_load_lds_dwordx4 v[212:213], off
	v_lshl_add_u64 v[212:213], v[218:219], 0, s[58:59]
	s_mov_b32 m0, s35
	s_nop 0
	global_load_lds_dwordx4 v[212:213], off
	s_waitcnt vmcnt(8)
	s_waitcnt lgkmcnt(0)
	s_setprio 1
	s_barrier
	v_mfma_f32_16x16x32_bf16 v[60:63], v[140:143], v[180:183], v[60:63]
	v_mfma_f32_16x16x32_bf16 v[56:59], v[156:159], v[180:183], v[56:59]
	v_mfma_f32_16x16x32_bf16 v[44:47], v[140:143], v[188:191], v[44:47]
	v_mfma_f32_16x16x32_bf16 v[40:43], v[156:159], v[188:191], v[40:43]
	v_mfma_f32_16x16x32_bf16 v[28:31], v[140:143], v[196:199], v[28:31]
	v_mfma_f32_16x16x32_bf16 v[24:27], v[156:159], v[196:199], v[24:27]
	v_mfma_f32_16x16x32_bf16 v[12:15], v[140:143], v[204:207], v[12:15]
	v_mfma_f32_16x16x32_bf16 v[8:11], v[156:159], v[204:207], v[8:11]
	v_mfma_f32_16x16x32_bf16 v[60:63], v[152:155], v[184:187], v[60:63]
	v_mfma_f32_16x16x32_bf16 v[56:59], v[160:163], v[184:187], v[56:59]
	v_mfma_f32_16x16x32_bf16 v[44:47], v[152:155], v[192:195], v[44:47]
	v_mfma_f32_16x16x32_bf16 v[40:43], v[160:163], v[192:195], v[40:43]
	v_mfma_f32_16x16x32_bf16 v[28:31], v[152:155], v[200:203], v[28:31]
	v_mfma_f32_16x16x32_bf16 v[24:27], v[160:163], v[200:203], v[24:27]
	v_mfma_f32_16x16x32_bf16 v[12:15], v[152:155], v[208:211], v[12:15]
	v_mfma_f32_16x16x32_bf16 v[8:11], v[160:163], v[208:211], v[8:11]
	v_mfma_f32_16x16x32_bf16 v[52:55], v[164:167], v[180:183], v[52:55]
	v_mfma_f32_16x16x32_bf16 v[48:51], v[172:175], v[180:183], v[48:51]
	v_mfma_f32_16x16x32_bf16 v[36:39], v[164:167], v[188:191], v[36:39]
	v_mfma_f32_16x16x32_bf16 v[32:35], v[172:175], v[188:191], v[32:35]
	v_mfma_f32_16x16x32_bf16 v[20:23], v[164:167], v[196:199], v[20:23]
	v_mfma_f32_16x16x32_bf16 v[16:19], v[172:175], v[196:199], v[16:19]
	v_mfma_f32_16x16x32_bf16 v[4:7], v[164:167], v[204:207], v[4:7]
	v_mfma_f32_16x16x32_bf16 v[0:3], v[172:175], v[204:207], v[0:3]
	v_mfma_f32_16x16x32_bf16 v[52:55], v[168:171], v[184:187], v[52:55]
	v_mfma_f32_16x16x32_bf16 v[48:51], v[176:179], v[184:187], v[48:51]
	v_mfma_f32_16x16x32_bf16 v[36:39], v[168:171], v[192:195], v[36:39]
	v_mfma_f32_16x16x32_bf16 v[32:35], v[176:179], v[192:195], v[32:35]
	v_mfma_f32_16x16x32_bf16 v[20:23], v[168:171], v[200:203], v[20:23]
	v_mfma_f32_16x16x32_bf16 v[16:19], v[176:179], v[200:203], v[16:19]
	v_mfma_f32_16x16x32_bf16 v[4:7], v[168:171], v[208:211], v[4:7]
	v_mfma_f32_16x16x32_bf16 v[0:3], v[176:179], v[208:211], v[0:3]
	s_setprio 0
	s_barrier
	s_add_i32 s86, s86, 2
	s_add_u32 s74, s74, 0x100
	s_addc_u32 s75, s75, 0
	s_add_u32 s84, s84, 0x100
	s_addc_u32 s85, s85, 0
	s_cmp_gt_u32 s86, 29
	s_cbranch_scc0 .LBB0_1693
	s_and_b64 vcc, exec, s[60:61]
	s_cbranch_vccz .LBB0_1696
	s_barrier

.LBB0_1785:
	ds_read_b128 v[146:149], v155
	ds_read_b128 v[160:163], v155 offset:1024
	ds_read_b128 v[164:167], v155 offset:2048
	ds_read_b128 v[168:171], v155 offset:3072
	ds_read_b128 v[172:175], v156
	ds_read_b128 v[176:179], v156 offset:1024
	ds_read_b128 v[180:183], v156 offset:2048
	ds_read_b128 v[184:187], v156 offset:3072
	s_add_u32 s60, s72, 0xfff80080
	s_addc_u32 s61, s73, -1
	s_cmp_eq_u32 s78, 28
	s_cselect_b32 s77, s56, s61
	s_cselect_b32 s76, s57, s60
	s_cselect_b32 s75, s23, s71
	s_cselect_b32 s74, s63, s69
	v_lshl_add_u64 v[220:221], s[72:73], 0, v[138:139]
	s_add_i32 m0, s6, 0xc000
	ds_read_b128 v[188:191], v157
	ds_read_b128 v[192:195], v157 offset:1024
	ds_read_b128 v[196:199], v157 offset:2048
	ds_read_b128 v[200:203], v157 offset:3072
	ds_read_b128 v[204:207], v157 offset:4096
	ds_read_b128 v[208:211], v157 offset:5120
	ds_read_b128 v[212:215], v157 offset:6144
	ds_read_b128 v[216:219], v157 offset:7168
	global_load_lds_dwordx4 v[220:221], off
	v_lshl_add_u64 v[220:221], s[72:73], 0, v[140:141]
	s_add_i32 m0, s6, 0xe000
	s_nop 0
	global_load_lds_dwordx4 v[220:221], off
	s_waitcnt vmcnt(8)
	s_waitcnt lgkmcnt(0)
	s_setprio 1
	s_barrier
	v_mfma_f32_16x16x32_bf16 v[124:127], v[146:149], v[188:191], v[124:127]
	v_mfma_f32_16x16x32_bf16 v[120:123], v[164:167], v[188:191], v[120:123]
	v_mfma_f32_16x16x32_bf16 v[108:111], v[146:149], v[196:199], v[108:111]
	v_mfma_f32_16x16x32_bf16 v[104:107], v[164:167], v[196:199], v[104:107]
	v_mfma_f32_16x16x32_bf16 v[92:95], v[146:149], v[204:207], v[92:95]
	v_mfma_f32_16x16x32_bf16 v[88:91], v[164:167], v[204:207], v[88:91]
	v_mfma_f32_16x16x32_bf16 v[76:79], v[146:149], v[212:215], v[76:79]
	v_mfma_f32_16x16x32_bf16 v[72:75], v[164:167], v[212:215], v[72:75]
	v_mfma_f32_16x16x32_bf16 v[124:127], v[160:163], v[192:195], v[124:127]
	v_mfma_f32_16x16x32_bf16 v[120:123], v[168:171], v[192:195], v[120:123]
	v_mfma_f32_16x16x32_bf16 v[108:111], v[160:163], v[200:203], v[108:111]
	v_mfma_f32_16x16x32_bf16 v[104:107], v[168:171], v[200:203], v[104:107]
	v_mfma_f32_16x16x32_bf16 v[92:95], v[160:163], v[208:211], v[92:95]
	v_mfma_f32_16x16x32_bf16 v[88:91], v[168:171], v[208:211], v[88:91]
	v_mfma_f32_16x16x32_bf16 v[76:79], v[160:163], v[216:219], v[76:79]
	v_mfma_f32_16x16x32_bf16 v[72:75], v[168:171], v[216:219], v[72:75]
	v_mfma_f32_16x16x32_bf16 v[116:119], v[172:175], v[188:191], v[116:119]
	v_mfma_f32_16x16x32_bf16 v[112:115], v[180:183], v[188:191], v[112:115]
	v_mfma_f32_16x16x32_bf16 v[100:103], v[172:175], v[196:199], v[100:103]
	v_mfma_f32_16x16x32_bf16 v[96:99], v[180:183], v[196:199], v[96:99]
	v_mfma_f32_16x16x32_bf16 v[84:87], v[172:175], v[204:207], v[84:87]
	v_mfma_f32_16x16x32_bf16 v[80:83], v[180:183], v[204:207], v[80:83]
	v_mfma_f32_16x16x32_bf16 v[68:71], v[172:175], v[212:215], v[68:71]
	v_mfma_f32_16x16x32_bf16 v[64:67], v[180:183], v[212:215], v[64:67]
	v_mfma_f32_16x16x32_bf16 v[116:119], v[176:179], v[192:195], v[116:119]
	v_mfma_f32_16x16x32_bf16 v[112:115], v[184:187], v[192:195], v[112:115]
	v_mfma_f32_16x16x32_bf16 v[100:103], v[176:179], v[200:203], v[100:103]
	v_mfma_f32_16x16x32_bf16 v[96:99], v[184:187], v[200:203], v[96:99]
	v_mfma_f32_16x16x32_bf16 v[84:87], v[176:179], v[208:211], v[84:87]
	v_mfma_f32_16x16x32_bf16 v[80:83], v[184:187], v[208:211], v[80:83]
	v_mfma_f32_16x16x32_bf16 v[68:71], v[176:179], v[216:219], v[68:71]
	v_mfma_f32_16x16x32_bf16 v[64:67], v[184:187], v[216:219], v[64:67]
	s_setprio 0
	s_barrier
	s_add_i32 s60, s35, s94
	v_lshl_add_u64 v[220:221], s[74:75], 0, v[130:131]
	s_mov_b32 m0, s60
	ds_read_b128 v[188:191], v157 offset:16384
	ds_read_b128 v[192:195], v157 offset:17408
	ds_read_b128 v[196:199], v157 offset:18432
	ds_read_b128 v[200:203], v157 offset:19456
	ds_read_b128 v[204:207], v157 offset:20480
	ds_read_b128 v[208:211], v157 offset:21504
	ds_read_b128 v[212:215], v157 offset:22528
	ds_read_b128 v[216:219], v157 offset:23552
	global_load_lds_dwordx4 v[220:221], off
	s_add_i32 m0, s60, 0x2000
	s_add_u32 s80, s74, 0x80000
	v_lshl_add_u64 v[222:223], s[74:75], 0, v[134:135]
	s_addc_u32 s81, s75, 0
	s_add_i32 s60, s46, s94
	global_load_lds_dwordx4 v[222:223], off
	v_lshl_add_u64 v[224:225], s[80:81], 0, v[130:131]
	s_mov_b32 m0, s60
	v_lshl_add_u64 v[226:227], s[76:77], 0, v[132:133]
	global_load_lds_dwordx4 v[224:225], off
	v_lshl_add_u64 v[224:225], s[80:81], 0, v[134:135]
	s_add_i32 m0, s60, 0x2000
	s_nop 0
	global_load_lds_dwordx4 v[224:225], off
	v_lshl_add_u64 v[224:225], s[76:77], 0, v[128:129]
	s_mov_b32 m0, s6
	s_nop 0
	global_load_lds_dwordx4 v[224:225], off
	s_mov_b32 m0, s7
	s_nop 0
	global_load_lds_dwordx4 v[226:227], off
	s_waitcnt vmcnt(8)
	s_waitcnt lgkmcnt(0)
	s_setprio 1
	s_barrier
	v_mfma_f32_16x16x32_bf16 v[60:63], v[146:149], v[188:191], v[60:63]
	v_mfma_f32_16x16x32_bf16 v[56:59], v[164:167], v[188:191], v[56:59]
	v_mfma_f32_16x16x32_bf16 v[44:47], v[146:149], v[196:199], v[44:47]
	v_mfma_f32_16x16x32_bf16 v[40:43], v[164:167], v[196:199], v[40:43]
	v_mfma_f32_16x16x32_bf16 v[28:31], v[146:149], v[204:207], v[28:31]
	v_mfma_f32_16x16x32_bf16 v[24:27], v[164:167], v[204:207], v[24:27]
	v_mfma_f32_16x16x32_bf16 v[12:15], v[146:149], v[212:215], v[12:15]
	v_mfma_f32_16x16x32_bf16 v[8:11], v[164:167], v[212:215], v[8:11]
	v_mfma_f32_16x16x32_bf16 v[60:63], v[160:163], v[192:195], v[60:63]
	v_mfma_f32_16x16x32_bf16 v[56:59], v[168:171], v[192:195], v[56:59]
	v_mfma_f32_16x16x32_bf16 v[44:47], v[160:163], v[200:203], v[44:47]
	v_mfma_f32_16x16x32_bf16 v[40:43], v[168:171], v[200:203], v[40:43]
	v_mfma_f32_16x16x32_bf16 v[28:31], v[160:163], v[208:211], v[28:31]
	v_mfma_f32_16x16x32_bf16 v[24:27], v[168:171], v[208:211], v[24:27]
	v_mfma_f32_16x16x32_bf16 v[12:15], v[160:163], v[216:219], v[12:15]
	v_mfma_f32_16x16x32_bf16 v[8:11], v[168:171], v[216:219], v[8:11]
	v_mfma_f32_16x16x32_bf16 v[52:55], v[172:175], v[188:191], v[52:55]
	v_mfma_f32_16x16x32_bf16 v[48:51], v[180:183], v[188:191], v[48:51]
	v_mfma_f32_16x16x32_bf16 v[36:39], v[172:175], v[196:199], v[36:39]
	v_mfma_f32_16x16x32_bf16 v[32:35], v[180:183], v[196:199], v[32:35]
	v_mfma_f32_16x16x32_bf16 v[20:23], v[172:175], v[204:207], v[20:23]
	v_mfma_f32_16x16x32_bf16 v[16:19], v[180:183], v[204:207], v[16:19]
	v_mfma_f32_16x16x32_bf16 v[4:7], v[172:175], v[212:215], v[4:7]
	v_mfma_f32_16x16x32_bf16 v[0:3], v[180:183], v[212:215], v[0:3]
	v_mfma_f32_16x16x32_bf16 v[52:55], v[176:179], v[192:195], v[52:55]
	v_mfma_f32_16x16x32_bf16 v[48:51], v[184:187], v[192:195], v[48:51]
	v_mfma_f32_16x16x32_bf16 v[36:39], v[176:179], v[200:203], v[36:39]
	v_mfma_f32_16x16x32_bf16 v[32:35], v[184:187], v[200:203], v[32:35]
	v_mfma_f32_16x16x32_bf16 v[20:23], v[176:179], v[208:211], v[20:23]
	v_mfma_f32_16x16x32_bf16 v[16:19], v[184:187], v[208:211], v[16:19]
	v_mfma_f32_16x16x32_bf16 v[4:7], v[176:179], v[216:219], v[4:7]
	v_mfma_f32_16x16x32_bf16 v[0:3], v[184:187], v[216:219], v[0:3]
	s_setprio 0
	s_barrier
	s_add_i32 s60, 0, 0x18000
	v_add_u32_e32 v159, s60, v151
	s_add_i32 s61, 0, 0x1c000
	ds_read_b128 v[146:149], v159
	ds_read_b128 v[160:163], v159 offset:1024
	ds_read_b128 v[164:167], v159 offset:2048
	ds_read_b128 v[168:171], v159 offset:3072
	v_add_u32_e32 v159, s61, v151
	ds_read_b128 v[172:175], v159
	ds_read_b128 v[176:179], v159 offset:1024
	ds_read_b128 v[180:183], v159 offset:2048
	ds_read_b128 v[184:187], v159 offset:3072
	s_add_u32 s76, s76, 0x80000
	s_addc_u32 s77, s77, 0
	s_mov_b32 m0, s12
	v_lshl_add_u64 v[228:229], s[76:77], 0, v[128:129]
	ds_read_b128 v[188:191], v157 offset:32768
	ds_read_b128 v[192:195], v157 offset:33792
	ds_read_b128 v[196:199], v157 offset:34816
	ds_read_b128 v[200:203], v157 offset:35840
	ds_read_b128 v[204:207], v157 offset:36864
	ds_read_b128 v[208:211], v157 offset:37888
	ds_read_b128 v[212:215], v157 offset:38912
	ds_read_b128 v[216:219], v157 offset:39936
	global_load_lds_dwordx4 v[228:229], off
	v_lshl_add_u64 v[228:229], s[76:77], 0, v[132:133]
	s_mov_b32 m0, s13
	s_nop 0
	global_load_lds_dwordx4 v[228:229], off
	s_waitcnt vmcnt(8)
	s_waitcnt lgkmcnt(0)
	s_setprio 1
	s_barrier
	v_mfma_f32_16x16x32_bf16 v[124:127], v[146:149], v[188:191], v[124:127]
	v_mfma_f32_16x16x32_bf16 v[120:123], v[164:167], v[188:191], v[120:123]
	v_mfma_f32_16x16x32_bf16 v[108:111], v[146:149], v[196:199], v[108:111]
	v_mfma_f32_16x16x32_bf16 v[104:107], v[164:167], v[196:199], v[104:107]
	v_mfma_f32_16x16x32_bf16 v[92:95], v[146:149], v[204:207], v[92:95]
	v_mfma_f32_16x16x32_bf16 v[88:91], v[164:167], v[204:207], v[88:91]
	v_mfma_f32_16x16x32_bf16 v[76:79], v[146:149], v[212:215], v[76:79]
	v_mfma_f32_16x16x32_bf16 v[72:75], v[164:167], v[212:215], v[72:75]
	v_mfma_f32_16x16x32_bf16 v[124:127], v[160:163], v[192:195], v[124:127]
	v_mfma_f32_16x16x32_bf16 v[120:123], v[168:171], v[192:195], v[120:123]
	v_mfma_f32_16x16x32_bf16 v[108:111], v[160:163], v[200:203], v[108:111]
	v_mfma_f32_16x16x32_bf16 v[104:107], v[168:171], v[200:203], v[104:107]
	v_mfma_f32_16x16x32_bf16 v[92:95], v[160:163], v[208:211], v[92:95]
	v_mfma_f32_16x16x32_bf16 v[88:91], v[168:171], v[208:211], v[88:91]
	v_mfma_f32_16x16x32_bf16 v[76:79], v[160:163], v[216:219], v[76:79]
	v_mfma_f32_16x16x32_bf16 v[72:75], v[168:171], v[216:219], v[72:75]
	v_mfma_f32_16x16x32_bf16 v[116:119], v[172:175], v[188:191], v[116:119]
	v_mfma_f32_16x16x32_bf16 v[112:115], v[180:183], v[188:191], v[112:115]
	v_mfma_f32_16x16x32_bf16 v[100:103], v[172:175], v[196:199], v[100:103]
	v_mfma_f32_16x16x32_bf16 v[96:99], v[180:183], v[196:199], v[96:99]
	v_mfma_f32_16x16x32_bf16 v[84:87], v[172:175], v[204:207], v[84:87]
	v_mfma_f32_16x16x32_bf16 v[80:83], v[180:183], v[204:207], v[80:83]
	v_mfma_f32_16x16x32_bf16 v[68:71], v[172:175], v[212:215], v[68:71]
	v_mfma_f32_16x16x32_bf16 v[64:67], v[180:183], v[212:215], v[64:67]
	v_mfma_f32_16x16x32_bf16 v[116:119], v[176:179], v[192:195], v[116:119]
	v_mfma_f32_16x16x32_bf16 v[112:115], v[184:187], v[192:195], v[112:115]
	v_mfma_f32_16x16x32_bf16 v[100:103], v[176:179], v[200:203], v[100:103]
	v_mfma_f32_16x16x32_bf16 v[96:99], v[184:187], v[200:203], v[96:99]
	v_mfma_f32_16x16x32_bf16 v[84:87], v[176:179], v[208:211], v[84:87]
	v_mfma_f32_16x16x32_bf16 v[80:83], v[184:187], v[208:211], v[80:83]
	v_mfma_f32_16x16x32_bf16 v[68:71], v[176:179], v[216:219], v[68:71]
	v_mfma_f32_16x16x32_bf16 v[64:67], v[184:187], v[216:219], v[64:67]
	s_setprio 0
	s_barrier
	s_add_i32 s60, s60, s94
	v_lshl_add_u64 v[220:221], v[220:221], 0, s[20:21]
	s_mov_b32 m0, s60
	ds_read_b128 v[188:191], v157 offset:49152
	ds_read_b128 v[192:195], v157 offset:50176
	ds_read_b128 v[196:199], v157 offset:51200
	ds_read_b128 v[200:203], v157 offset:52224
	ds_read_b128 v[204:207], v157 offset:53248
	ds_read_b128 v[208:211], v157 offset:54272
	ds_read_b128 v[212:215], v157 offset:55296
	ds_read_b128 v[216:219], v157 offset:56320
	global_load_lds_dwordx4 v[220:221], off
	s_add_i32 m0, s60, 0x2000
	s_add_u32 s74, s74, 0x80080
	v_lshl_add_u64 v[220:221], v[222:223], 0, s[20:21]
	s_addc_u32 s75, s75, 0
	s_add_i32 s60, s61, s94
	global_load_lds_dwordx4 v[220:221], off
	v_lshl_add_u64 v[220:221], s[74:75], 0, v[130:131]
	s_mov_b32 m0, s60
	s_nop 0
	global_load_lds_dwordx4 v[220:221], off
	v_lshl_add_u64 v[220:221], s[74:75], 0, v[134:135]
	s_add_i32 m0, s60, 0x2000
	s_nop 0
	global_load_lds_dwordx4 v[220:221], off
	v_lshl_add_u64 v[220:221], v[224:225], 0, s[20:21]
	s_mov_b32 m0, s30
	s_nop 0
	global_load_lds_dwordx4 v[220:221], off
	v_lshl_add_u64 v[220:221], v[226:227], 0, s[20:21]
	s_mov_b32 m0, s34
	s_nop 0
	global_load_lds_dwordx4 v[220:221], off
	s_waitcnt vmcnt(8)
	s_waitcnt lgkmcnt(0)
	s_setprio 1
	s_barrier
	v_mfma_f32_16x16x32_bf16 v[60:63], v[146:149], v[188:191], v[60:63]
	v_mfma_f32_16x16x32_bf16 v[56:59], v[164:167], v[188:191], v[56:59]
	v_mfma_f32_16x16x32_bf16 v[44:47], v[146:149], v[196:199], v[44:47]
	v_mfma_f32_16x16x32_bf16 v[40:43], v[164:167], v[196:199], v[40:43]
	v_mfma_f32_16x16x32_bf16 v[28:31], v[146:149], v[204:207], v[28:31]
	v_mfma_f32_16x16x32_bf16 v[24:27], v[164:167], v[204:207], v[24:27]
	v_mfma_f32_16x16x32_bf16 v[12:15], v[146:149], v[212:215], v[12:15]
	v_mfma_f32_16x16x32_bf16 v[8:11], v[164:167], v[212:215], v[8:11]
	v_mfma_f32_16x16x32_bf16 v[60:63], v[160:163], v[192:195], v[60:63]
	v_mfma_f32_16x16x32_bf16 v[56:59], v[168:171], v[192:195], v[56:59]
	v_mfma_f32_16x16x32_bf16 v[44:47], v[160:163], v[200:203], v[44:47]
	v_mfma_f32_16x16x32_bf16 v[40:43], v[168:171], v[200:203], v[40:43]
	v_mfma_f32_16x16x32_bf16 v[28:31], v[160:163], v[208:211], v[28:31]
	v_mfma_f32_16x16x32_bf16 v[24:27], v[168:171], v[208:211], v[24:27]
	v_mfma_f32_16x16x32_bf16 v[12:15], v[160:163], v[216:219], v[12:15]
	v_mfma_f32_16x16x32_bf16 v[8:11], v[168:171], v[216:219], v[8:11]
	v_mfma_f32_16x16x32_bf16 v[52:55], v[172:175], v[188:191], v[52:55]
	v_mfma_f32_16x16x32_bf16 v[48:51], v[180:183], v[188:191], v[48:51]
	v_mfma_f32_16x16x32_bf16 v[36:39], v[172:175], v[196:199], v[36:39]
	v_mfma_f32_16x16x32_bf16 v[32:35], v[180:183], v[196:199], v[32:35]
	v_mfma_f32_16x16x32_bf16 v[20:23], v[172:175], v[204:207], v[20:23]
	v_mfma_f32_16x16x32_bf16 v[16:19], v[180:183], v[204:207], v[16:19]
	v_mfma_f32_16x16x32_bf16 v[4:7], v[172:175], v[212:215], v[4:7]
	v_mfma_f32_16x16x32_bf16 v[0:3], v[180:183], v[212:215], v[0:3]
	v_mfma_f32_16x16x32_bf16 v[52:55], v[176:179], v[192:195], v[52:55]
	v_mfma_f32_16x16x32_bf16 v[48:51], v[184:187], v[192:195], v[48:51]
	v_mfma_f32_16x16x32_bf16 v[36:39], v[176:179], v[200:203], v[36:39]
	v_mfma_f32_16x16x32_bf16 v[32:35], v[184:187], v[200:203], v[32:35]
	v_mfma_f32_16x16x32_bf16 v[20:23], v[176:179], v[208:211], v[20:23]
	v_mfma_f32_16x16x32_bf16 v[16:19], v[184:187], v[208:211], v[16:19]
	v_mfma_f32_16x16x32_bf16 v[4:7], v[176:179], v[216:219], v[4:7]
	v_mfma_f32_16x16x32_bf16 v[0:3], v[184:187], v[216:219], v[0:3]
	s_setprio 0
	s_barrier
	s_add_i32 s78, s78, 2
	s_add_u32 s72, s72, 0x100
	s_addc_u32 s73, s73, 0
	s_add_u32 s69, s69, 0x100
	s_addc_u32 s71, s71, 0
	s_cmp_gt_u32 s78, 29
	s_cbranch_scc0 .LBB0_1785
	s_and_b64 vcc, exec, s[58:59]
	s_cbranch_vccz .LBB0_1788
	s_barrier

.LBB0_1897:
	ds_read_b128 v[140:143], v149
	ds_read_b128 v[152:155], v149 offset:1024
	ds_read_b128 v[156:159], v149 offset:2048
	ds_read_b128 v[160:163], v149 offset:3072
	ds_read_b128 v[164:167], v150
	ds_read_b128 v[168:171], v150 offset:1024
	ds_read_b128 v[172:175], v150 offset:2048
	ds_read_b128 v[176:179], v150 offset:3072
	s_add_u32 s60, s72, 0xffe00080
	s_addc_u32 s61, s73, -1
	s_cmpk_eq_i32 s79, 0x7c
	s_cselect_b32 s77, s56, s61
	s_cselect_b32 s76, s57, s60
	s_cselect_b32 s75, s63, s78
	s_cselect_b32 s74, s65, s71
	v_lshl_add_u64 v[212:213], s[72:73], 0, v[132:133]
	s_add_i32 m0, s6, 0xc000
	ds_read_b128 v[180:183], v151
	ds_read_b128 v[184:187], v151 offset:1024
	ds_read_b128 v[188:191], v151 offset:2048
	ds_read_b128 v[192:195], v151 offset:3072
	ds_read_b128 v[196:199], v151 offset:4096
	ds_read_b128 v[200:203], v151 offset:5120
	ds_read_b128 v[204:207], v151 offset:6144
	ds_read_b128 v[208:211], v151 offset:7168
	global_load_lds_dwordx4 v[212:213], off
	v_lshl_add_u64 v[212:213], s[72:73], 0, v[134:135]
	s_add_i32 m0, s6, 0xe000
	s_nop 0
	global_load_lds_dwordx4 v[212:213], off
	s_waitcnt vmcnt(8)
	s_waitcnt lgkmcnt(0)
	s_setprio 1
	s_barrier
	v_mfma_f32_16x16x32_bf16 v[124:127], v[140:143], v[180:183], v[124:127]
	v_mfma_f32_16x16x32_bf16 v[120:123], v[156:159], v[180:183], v[120:123]
	v_mfma_f32_16x16x32_bf16 v[108:111], v[140:143], v[188:191], v[108:111]
	v_mfma_f32_16x16x32_bf16 v[104:107], v[156:159], v[188:191], v[104:107]
	v_mfma_f32_16x16x32_bf16 v[92:95], v[140:143], v[196:199], v[92:95]
	v_mfma_f32_16x16x32_bf16 v[88:91], v[156:159], v[196:199], v[88:91]
	v_mfma_f32_16x16x32_bf16 v[76:79], v[140:143], v[204:207], v[76:79]
	v_mfma_f32_16x16x32_bf16 v[72:75], v[156:159], v[204:207], v[72:75]
	v_mfma_f32_16x16x32_bf16 v[124:127], v[152:155], v[184:187], v[124:127]
	v_mfma_f32_16x16x32_bf16 v[120:123], v[160:163], v[184:187], v[120:123]
	v_mfma_f32_16x16x32_bf16 v[108:111], v[152:155], v[192:195], v[108:111]
	v_mfma_f32_16x16x32_bf16 v[104:107], v[160:163], v[192:195], v[104:107]
	v_mfma_f32_16x16x32_bf16 v[92:95], v[152:155], v[200:203], v[92:95]
	v_mfma_f32_16x16x32_bf16 v[88:91], v[160:163], v[200:203], v[88:91]
	v_mfma_f32_16x16x32_bf16 v[76:79], v[152:155], v[208:211], v[76:79]
	v_mfma_f32_16x16x32_bf16 v[72:75], v[160:163], v[208:211], v[72:75]
	v_mfma_f32_16x16x32_bf16 v[116:119], v[164:167], v[180:183], v[116:119]
	v_mfma_f32_16x16x32_bf16 v[112:115], v[172:175], v[180:183], v[112:115]
	v_mfma_f32_16x16x32_bf16 v[100:103], v[164:167], v[188:191], v[100:103]
	v_mfma_f32_16x16x32_bf16 v[96:99], v[172:175], v[188:191], v[96:99]
	v_mfma_f32_16x16x32_bf16 v[84:87], v[164:167], v[196:199], v[84:87]
	v_mfma_f32_16x16x32_bf16 v[80:83], v[172:175], v[196:199], v[80:83]
	v_mfma_f32_16x16x32_bf16 v[68:71], v[164:167], v[204:207], v[68:71]
	v_mfma_f32_16x16x32_bf16 v[64:67], v[172:175], v[204:207], v[64:67]
	v_mfma_f32_16x16x32_bf16 v[116:119], v[168:171], v[184:187], v[116:119]
	v_mfma_f32_16x16x32_bf16 v[112:115], v[176:179], v[184:187], v[112:115]
	v_mfma_f32_16x16x32_bf16 v[100:103], v[168:171], v[192:195], v[100:103]
	v_mfma_f32_16x16x32_bf16 v[96:99], v[176:179], v[192:195], v[96:99]
	v_mfma_f32_16x16x32_bf16 v[84:87], v[168:171], v[200:203], v[84:87]
	v_mfma_f32_16x16x32_bf16 v[80:83], v[176:179], v[200:203], v[80:83]
	v_mfma_f32_16x16x32_bf16 v[68:71], v[168:171], v[208:211], v[68:71]
	v_mfma_f32_16x16x32_bf16 v[64:67], v[176:179], v[208:211], v[64:67]
	s_setprio 0
	s_barrier
	s_add_i32 s60, s34, s94
	v_lshl_add_u64 v[212:213], s[74:75], 0, v[128:129]
	s_mov_b32 m0, s60
	ds_read_b128 v[180:183], v151 offset:16384
	ds_read_b128 v[184:187], v151 offset:17408
	ds_read_b128 v[188:191], v151 offset:18432
	ds_read_b128 v[192:195], v151 offset:19456
	ds_read_b128 v[196:199], v151 offset:20480
	ds_read_b128 v[200:203], v151 offset:21504
	ds_read_b128 v[204:207], v151 offset:22528
	ds_read_b128 v[208:211], v151 offset:23552
	global_load_lds_dwordx4 v[212:213], off
	s_add_i32 m0, s60, 0x2000
	s_add_u32 s80, s74, 0x200000
	v_lshl_add_u64 v[214:215], s[74:75], 0, v[130:131]
	s_addc_u32 s81, s75, 0
	s_add_i32 s60, s35, s94
	global_load_lds_dwordx4 v[214:215], off
	v_lshl_add_u64 v[216:217], s[80:81], 0, v[128:129]
	s_mov_b32 m0, s60
	v_lshl_add_u64 v[218:219], s[76:77], 0, v[130:131]
	global_load_lds_dwordx4 v[216:217], off
	v_lshl_add_u64 v[216:217], s[80:81], 0, v[130:131]
	s_add_i32 m0, s60, 0x2000
	s_nop 0
	global_load_lds_dwordx4 v[216:217], off
	v_lshl_add_u64 v[216:217], s[76:77], 0, v[128:129]
	s_mov_b32 m0, s6
	s_nop 0
	global_load_lds_dwordx4 v[216:217], off
	s_mov_b32 m0, s7
	s_nop 0
	global_load_lds_dwordx4 v[218:219], off
	s_waitcnt vmcnt(8)
	s_waitcnt lgkmcnt(0)
	s_setprio 1
	s_barrier
	v_mfma_f32_16x16x32_bf16 v[60:63], v[140:143], v[180:183], v[60:63]
	v_mfma_f32_16x16x32_bf16 v[56:59], v[156:159], v[180:183], v[56:59]
	v_mfma_f32_16x16x32_bf16 v[44:47], v[140:143], v[188:191], v[44:47]
	v_mfma_f32_16x16x32_bf16 v[40:43], v[156:159], v[188:191], v[40:43]
	v_mfma_f32_16x16x32_bf16 v[28:31], v[140:143], v[196:199], v[28:31]
	v_mfma_f32_16x16x32_bf16 v[24:27], v[156:159], v[196:199], v[24:27]
	v_mfma_f32_16x16x32_bf16 v[12:15], v[140:143], v[204:207], v[12:15]
	v_mfma_f32_16x16x32_bf16 v[8:11], v[156:159], v[204:207], v[8:11]
	v_mfma_f32_16x16x32_bf16 v[60:63], v[152:155], v[184:187], v[60:63]
	v_mfma_f32_16x16x32_bf16 v[56:59], v[160:163], v[184:187], v[56:59]
	v_mfma_f32_16x16x32_bf16 v[44:47], v[152:155], v[192:195], v[44:47]
	v_mfma_f32_16x16x32_bf16 v[40:43], v[160:163], v[192:195], v[40:43]
	v_mfma_f32_16x16x32_bf16 v[28:31], v[152:155], v[200:203], v[28:31]
	v_mfma_f32_16x16x32_bf16 v[24:27], v[160:163], v[200:203], v[24:27]
	v_mfma_f32_16x16x32_bf16 v[12:15], v[152:155], v[208:211], v[12:15]
	v_mfma_f32_16x16x32_bf16 v[8:11], v[160:163], v[208:211], v[8:11]
	v_mfma_f32_16x16x32_bf16 v[52:55], v[164:167], v[180:183], v[52:55]
	v_mfma_f32_16x16x32_bf16 v[48:51], v[172:175], v[180:183], v[48:51]
	v_mfma_f32_16x16x32_bf16 v[36:39], v[164:167], v[188:191], v[36:39]
	v_mfma_f32_16x16x32_bf16 v[32:35], v[172:175], v[188:191], v[32:35]
	v_mfma_f32_16x16x32_bf16 v[20:23], v[164:167], v[196:199], v[20:23]
	v_mfma_f32_16x16x32_bf16 v[16:19], v[172:175], v[196:199], v[16:19]
	v_mfma_f32_16x16x32_bf16 v[4:7], v[164:167], v[204:207], v[4:7]
	v_mfma_f32_16x16x32_bf16 v[0:3], v[172:175], v[204:207], v[0:3]
	v_mfma_f32_16x16x32_bf16 v[52:55], v[168:171], v[184:187], v[52:55]
	v_mfma_f32_16x16x32_bf16 v[48:51], v[176:179], v[184:187], v[48:51]
	v_mfma_f32_16x16x32_bf16 v[36:39], v[168:171], v[192:195], v[36:39]
	v_mfma_f32_16x16x32_bf16 v[32:35], v[176:179], v[192:195], v[32:35]
	v_mfma_f32_16x16x32_bf16 v[20:23], v[168:171], v[200:203], v[20:23]
	v_mfma_f32_16x16x32_bf16 v[16:19], v[176:179], v[200:203], v[16:19]
	v_mfma_f32_16x16x32_bf16 v[4:7], v[168:171], v[208:211], v[4:7]
	v_mfma_f32_16x16x32_bf16 v[0:3], v[176:179], v[208:211], v[0:3]
	s_setprio 0
	s_barrier
	s_add_i32 s60, 0, 0x18000
	s_add_i32 s61, 0, 0x1c000
	v_add_u32_e32 v160, s60, v145
	v_add_u32_e32 v176, s61, v145
	ds_read_b128 v[140:143], v160
	ds_read_b128 v[152:155], v160 offset:1024
	ds_read_b128 v[156:159], v160 offset:2048
	ds_read_b128 v[160:163], v160 offset:3072
	ds_read_b128 v[164:167], v176
	ds_read_b128 v[168:171], v176 offset:1024
	ds_read_b128 v[172:175], v176 offset:2048
	ds_read_b128 v[176:179], v176 offset:3072
	s_add_u32 s76, s76, 0x200000
	s_addc_u32 s77, s77, 0
	s_mov_b32 m0, s12
	v_lshl_add_u64 v[220:221], s[76:77], 0, v[128:129]
	ds_read_b128 v[180:183], v151 offset:32768
	ds_read_b128 v[184:187], v151 offset:33792
	ds_read_b128 v[188:191], v151 offset:34816
	ds_read_b128 v[192:195], v151 offset:35840
	ds_read_b128 v[196:199], v151 offset:36864
	ds_read_b128 v[200:203], v151 offset:37888
	ds_read_b128 v[204:207], v151 offset:38912
	ds_read_b128 v[208:211], v151 offset:39936
	global_load_lds_dwordx4 v[220:221], off
	v_lshl_add_u64 v[220:221], s[76:77], 0, v[130:131]
	s_mov_b32 m0, s13
	s_nop 0
	global_load_lds_dwordx4 v[220:221], off
	s_waitcnt vmcnt(8)
	s_waitcnt lgkmcnt(0)
	s_setprio 1
	s_barrier
	v_mfma_f32_16x16x32_bf16 v[124:127], v[140:143], v[180:183], v[124:127]
	v_mfma_f32_16x16x32_bf16 v[120:123], v[156:159], v[180:183], v[120:123]
	v_mfma_f32_16x16x32_bf16 v[108:111], v[140:143], v[188:191], v[108:111]
	v_mfma_f32_16x16x32_bf16 v[104:107], v[156:159], v[188:191], v[104:107]
	v_mfma_f32_16x16x32_bf16 v[92:95], v[140:143], v[196:199], v[92:95]
	v_mfma_f32_16x16x32_bf16 v[88:91], v[156:159], v[196:199], v[88:91]
	v_mfma_f32_16x16x32_bf16 v[76:79], v[140:143], v[204:207], v[76:79]
	v_mfma_f32_16x16x32_bf16 v[72:75], v[156:159], v[204:207], v[72:75]
	v_mfma_f32_16x16x32_bf16 v[124:127], v[152:155], v[184:187], v[124:127]
	v_mfma_f32_16x16x32_bf16 v[120:123], v[160:163], v[184:187], v[120:123]
	v_mfma_f32_16x16x32_bf16 v[108:111], v[152:155], v[192:195], v[108:111]
	v_mfma_f32_16x16x32_bf16 v[104:107], v[160:163], v[192:195], v[104:107]
	v_mfma_f32_16x16x32_bf16 v[92:95], v[152:155], v[200:203], v[92:95]
	v_mfma_f32_16x16x32_bf16 v[88:91], v[160:163], v[200:203], v[88:91]
	v_mfma_f32_16x16x32_bf16 v[76:79], v[152:155], v[208:211], v[76:79]
	v_mfma_f32_16x16x32_bf16 v[72:75], v[160:163], v[208:211], v[72:75]
	v_mfma_f32_16x16x32_bf16 v[116:119], v[164:167], v[180:183], v[116:119]
	v_mfma_f32_16x16x32_bf16 v[112:115], v[172:175], v[180:183], v[112:115]
	v_mfma_f32_16x16x32_bf16 v[100:103], v[164:167], v[188:191], v[100:103]
	v_mfma_f32_16x16x32_bf16 v[96:99], v[172:175], v[188:191], v[96:99]
	v_mfma_f32_16x16x32_bf16 v[84:87], v[164:167], v[196:199], v[84:87]
	v_mfma_f32_16x16x32_bf16 v[80:83], v[172:175], v[196:199], v[80:83]
	v_mfma_f32_16x16x32_bf16 v[68:71], v[164:167], v[204:207], v[68:71]
	v_mfma_f32_16x16x32_bf16 v[64:67], v[172:175], v[204:207], v[64:67]
	v_mfma_f32_16x16x32_bf16 v[116:119], v[168:171], v[184:187], v[116:119]
	v_mfma_f32_16x16x32_bf16 v[112:115], v[176:179], v[184:187], v[112:115]
	v_mfma_f32_16x16x32_bf16 v[100:103], v[168:171], v[192:195], v[100:103]
	v_mfma_f32_16x16x32_bf16 v[96:99], v[176:179], v[192:195], v[96:99]
	v_mfma_f32_16x16x32_bf16 v[84:87], v[168:171], v[200:203], v[84:87]
	v_mfma_f32_16x16x32_bf16 v[80:83], v[176:179], v[200:203], v[80:83]
	v_mfma_f32_16x16x32_bf16 v[68:71], v[168:171], v[208:211], v[68:71]
	v_mfma_f32_16x16x32_bf16 v[64:67], v[176:179], v[208:211], v[64:67]
	s_setprio 0
	s_barrier
	s_add_i32 s60, s60, s94
	v_lshl_add_u64 v[212:213], v[212:213], 0, s[22:23]
	s_mov_b32 m0, s60
	ds_read_b128 v[180:183], v151 offset:49152
	ds_read_b128 v[184:187], v151 offset:50176
	ds_read_b128 v[188:191], v151 offset:51200
	ds_read_b128 v[192:195], v151 offset:52224
	ds_read_b128 v[196:199], v151 offset:53248
	ds_read_b128 v[200:203], v151 offset:54272
	ds_read_b128 v[204:207], v151 offset:55296
	ds_read_b128 v[208:211], v151 offset:56320
	global_load_lds_dwordx4 v[212:213], off
	s_add_i32 m0, s60, 0x2000
	s_add_u32 s74, s74, 0x200080
	v_lshl_add_u64 v[212:213], v[214:215], 0, s[22:23]
	s_addc_u32 s75, s75, 0
	s_add_i32 s60, s61, s94
	global_load_lds_dwordx4 v[212:213], off
	v_lshl_add_u64 v[212:213], s[74:75], 0, v[128:129]
	s_mov_b32 m0, s60
	s_nop 0
	global_load_lds_dwordx4 v[212:213], off
	v_lshl_add_u64 v[212:213], s[74:75], 0, v[130:131]
	s_add_i32 m0, s60, 0x2000
	s_nop 0
	global_load_lds_dwordx4 v[212:213], off
	v_lshl_add_u64 v[212:213], v[216:217], 0, s[22:23]
	s_mov_b32 m0, s29
	s_nop 0
	global_load_lds_dwordx4 v[212:213], off
	v_lshl_add_u64 v[212:213], v[218:219], 0, s[22:23]
	s_mov_b32 m0, s30
	s_nop 0
	global_load_lds_dwordx4 v[212:213], off
	s_waitcnt vmcnt(8)
	s_waitcnt lgkmcnt(0)
	s_setprio 1
	s_barrier
	v_mfma_f32_16x16x32_bf16 v[60:63], v[140:143], v[180:183], v[60:63]
	v_mfma_f32_16x16x32_bf16 v[56:59], v[156:159], v[180:183], v[56:59]
	v_mfma_f32_16x16x32_bf16 v[44:47], v[140:143], v[188:191], v[44:47]
	v_mfma_f32_16x16x32_bf16 v[40:43], v[156:159], v[188:191], v[40:43]
	v_mfma_f32_16x16x32_bf16 v[28:31], v[140:143], v[196:199], v[28:31]
	v_mfma_f32_16x16x32_bf16 v[24:27], v[156:159], v[196:199], v[24:27]
	v_mfma_f32_16x16x32_bf16 v[12:15], v[140:143], v[204:207], v[12:15]
	v_mfma_f32_16x16x32_bf16 v[8:11], v[156:159], v[204:207], v[8:11]
	v_mfma_f32_16x16x32_bf16 v[60:63], v[152:155], v[184:187], v[60:63]
	v_mfma_f32_16x16x32_bf16 v[56:59], v[160:163], v[184:187], v[56:59]
	v_mfma_f32_16x16x32_bf16 v[44:47], v[152:155], v[192:195], v[44:47]
	v_mfma_f32_16x16x32_bf16 v[40:43], v[160:163], v[192:195], v[40:43]
	v_mfma_f32_16x16x32_bf16 v[28:31], v[152:155], v[200:203], v[28:31]
	v_mfma_f32_16x16x32_bf16 v[24:27], v[160:163], v[200:203], v[24:27]
	v_mfma_f32_16x16x32_bf16 v[12:15], v[152:155], v[208:211], v[12:15]
	v_mfma_f32_16x16x32_bf16 v[8:11], v[160:163], v[208:211], v[8:11]
	v_mfma_f32_16x16x32_bf16 v[52:55], v[164:167], v[180:183], v[52:55]
	v_mfma_f32_16x16x32_bf16 v[48:51], v[172:175], v[180:183], v[48:51]
	v_mfma_f32_16x16x32_bf16 v[36:39], v[164:167], v[188:191], v[36:39]
	v_mfma_f32_16x16x32_bf16 v[32:35], v[172:175], v[188:191], v[32:35]
	v_mfma_f32_16x16x32_bf16 v[20:23], v[164:167], v[196:199], v[20:23]
	v_mfma_f32_16x16x32_bf16 v[16:19], v[172:175], v[196:199], v[16:19]
	v_mfma_f32_16x16x32_bf16 v[4:7], v[164:167], v[204:207], v[4:7]
	v_mfma_f32_16x16x32_bf16 v[0:3], v[172:175], v[204:207], v[0:3]
	v_mfma_f32_16x16x32_bf16 v[52:55], v[168:171], v[184:187], v[52:55]
	v_mfma_f32_16x16x32_bf16 v[48:51], v[176:179], v[184:187], v[48:51]
	v_mfma_f32_16x16x32_bf16 v[36:39], v[168:171], v[192:195], v[36:39]
	v_mfma_f32_16x16x32_bf16 v[32:35], v[176:179], v[192:195], v[32:35]
	v_mfma_f32_16x16x32_bf16 v[20:23], v[168:171], v[200:203], v[20:23]
	v_mfma_f32_16x16x32_bf16 v[16:19], v[176:179], v[200:203], v[16:19]
	v_mfma_f32_16x16x32_bf16 v[4:7], v[168:171], v[208:211], v[4:7]
	v_mfma_f32_16x16x32_bf16 v[0:3], v[176:179], v[208:211], v[0:3]
	s_setprio 0
	s_barrier
	s_add_i32 s79, s79, 2
	s_add_u32 s72, s72, 0x100
	s_addc_u32 s73, s73, 0
	s_add_u32 s71, s71, 0x100
	s_addc_u32 s78, s78, 0
	s_cmpk_gt_u32 s79, 0x7d
	s_cbranch_scc0 .LBB0_1897
	s_and_b64 vcc, exec, s[58:59]
	s_cbranch_vccz .LBB0_1900
	s_barrier

.LBB0_2128:
	ds_read_b128 v[148:151], v179
	ds_read_b128 v[152:155], v179 offset:1024
	ds_read_b128 v[156:159], v179 offset:2048
	ds_read_b128 v[160:163], v179 offset:3072
	ds_read_b128 v[164:167], v180
	ds_read_b128 v[168:171], v180 offset:1024
	ds_read_b128 v[184:187], v180 offset:2048
	ds_read_b128 v[188:191], v180 offset:3072
	s_add_u32 s60, s84, 0xfff80080
	s_addc_u32 s61, s85, -1
	s_cmp_eq_u32 s95, 28
	s_cselect_b32 s89, s23, s61
	s_cselect_b32 s88, s79, s60
	s_cselect_b32 s87, s77, s97
	s_cselect_b32 s86, vcc_lo, vcc_hi
	v_lshl_add_u64 v[172:173], s[84:85], 0, v[140:141]
	s_add_i32 m0, s6, 0xc000
	ds_read_b128 v[192:195], v181
	ds_read_b128 v[196:199], v181 offset:1024
	ds_read_b128 v[200:203], v181 offset:2048
	ds_read_b128 v[204:207], v181 offset:3072
	ds_read_b128 v[208:211], v181 offset:4096
	ds_read_b128 v[212:215], v181 offset:5120
	ds_read_b128 v[216:219], v181 offset:6144
	ds_read_b128 v[220:223], v181 offset:7168
	global_load_lds_dwordx4 v[172:173], off
	v_lshl_add_u64 v[172:173], s[84:85], 0, v[142:143]
	s_add_i32 m0, s6, 0xe000
	s_nop 0
	global_load_lds_dwordx4 v[172:173], off
	s_waitcnt vmcnt(8)
	s_waitcnt lgkmcnt(0)
	s_setprio 1
	s_barrier
	v_mfma_f32_16x16x32_bf16 v[124:127], v[148:151], v[192:195], v[124:127]
	v_mfma_f32_16x16x32_bf16 v[120:123], v[156:159], v[192:195], v[120:123]
	v_mfma_f32_16x16x32_bf16 v[108:111], v[148:151], v[200:203], v[108:111]
	v_mfma_f32_16x16x32_bf16 v[104:107], v[156:159], v[200:203], v[104:107]
	v_mfma_f32_16x16x32_bf16 v[92:95], v[148:151], v[208:211], v[92:95]
	v_mfma_f32_16x16x32_bf16 v[88:91], v[156:159], v[208:211], v[88:91]
	v_mfma_f32_16x16x32_bf16 v[76:79], v[148:151], v[216:219], v[76:79]
	v_mfma_f32_16x16x32_bf16 v[72:75], v[156:159], v[216:219], v[72:75]
	v_mfma_f32_16x16x32_bf16 v[124:127], v[152:155], v[196:199], v[124:127]
	v_mfma_f32_16x16x32_bf16 v[120:123], v[160:163], v[196:199], v[120:123]
	v_mfma_f32_16x16x32_bf16 v[108:111], v[152:155], v[204:207], v[108:111]
	v_mfma_f32_16x16x32_bf16 v[104:107], v[160:163], v[204:207], v[104:107]
	v_mfma_f32_16x16x32_bf16 v[92:95], v[152:155], v[212:215], v[92:95]
	v_mfma_f32_16x16x32_bf16 v[88:91], v[160:163], v[212:215], v[88:91]
	v_mfma_f32_16x16x32_bf16 v[76:79], v[152:155], v[220:223], v[76:79]
	v_mfma_f32_16x16x32_bf16 v[72:75], v[160:163], v[220:223], v[72:75]
	v_mfma_f32_16x16x32_bf16 v[116:119], v[164:167], v[192:195], v[116:119]
	v_mfma_f32_16x16x32_bf16 v[112:115], v[184:187], v[192:195], v[112:115]
	v_mfma_f32_16x16x32_bf16 v[100:103], v[164:167], v[200:203], v[100:103]
	v_mfma_f32_16x16x32_bf16 v[96:99], v[184:187], v[200:203], v[96:99]
	v_mfma_f32_16x16x32_bf16 v[84:87], v[164:167], v[208:211], v[84:87]
	v_mfma_f32_16x16x32_bf16 v[80:83], v[184:187], v[208:211], v[80:83]
	v_mfma_f32_16x16x32_bf16 v[68:71], v[164:167], v[216:219], v[68:71]
	v_mfma_f32_16x16x32_bf16 v[64:67], v[184:187], v[216:219], v[64:67]
	v_mfma_f32_16x16x32_bf16 v[116:119], v[168:171], v[196:199], v[116:119]
	v_mfma_f32_16x16x32_bf16 v[112:115], v[188:191], v[196:199], v[112:115]
	v_mfma_f32_16x16x32_bf16 v[100:103], v[168:171], v[204:207], v[100:103]
	v_mfma_f32_16x16x32_bf16 v[96:99], v[188:191], v[204:207], v[96:99]
	v_mfma_f32_16x16x32_bf16 v[84:87], v[168:171], v[212:215], v[84:87]
	v_mfma_f32_16x16x32_bf16 v[80:83], v[188:191], v[212:215], v[80:83]
	v_mfma_f32_16x16x32_bf16 v[68:71], v[168:171], v[220:223], v[68:71]
	v_mfma_f32_16x16x32_bf16 v[64:67], v[188:191], v[220:223], v[64:67]
	s_setprio 0
	s_barrier
	s_add_i32 s60, s12, s94
	v_lshl_add_u64 v[172:173], s[86:87], 0, v[130:131]
	s_mov_b32 m0, s60
	ds_read_b128 v[192:195], v181 offset:16384
	ds_read_b128 v[196:199], v181 offset:17408
	ds_read_b128 v[200:203], v181 offset:18432
	ds_read_b128 v[204:207], v181 offset:19456
	ds_read_b128 v[208:211], v181 offset:20480
	ds_read_b128 v[212:215], v181 offset:21504
	ds_read_b128 v[216:219], v181 offset:22528
	ds_read_b128 v[220:223], v181 offset:23552
	global_load_lds_dwordx4 v[172:173], off
	s_add_i32 m0, s60, 0x2000
	s_add_u32 s60, s86, 0x80000
	v_lshl_add_u64 v[224:225], s[86:87], 0, v[134:135]
	s_addc_u32 s61, s87, 0
	s_add_i32 s96, s13, s94
	global_load_lds_dwordx4 v[224:225], off
	v_lshl_add_u64 v[226:227], s[60:61], 0, v[130:131]
	s_mov_b32 m0, s96
	v_lshl_add_u64 v[228:229], s[88:89], 0, v[132:133]
	global_load_lds_dwordx4 v[226:227], off
	v_lshl_add_u64 v[226:227], s[60:61], 0, v[134:135]
	s_add_i32 m0, s96, 0x2000
	s_nop 0
	global_load_lds_dwordx4 v[226:227], off
	v_lshl_add_u64 v[226:227], s[88:89], 0, v[128:129]
	s_mov_b32 m0, s6
	s_nop 0
	global_load_lds_dwordx4 v[226:227], off
	s_mov_b32 m0, s7
	s_nop 0
	global_load_lds_dwordx4 v[228:229], off
	s_waitcnt vmcnt(8)
	s_waitcnt lgkmcnt(0)
	s_setprio 1
	s_barrier
	v_mfma_f32_16x16x32_bf16 v[60:63], v[148:151], v[192:195], v[60:63]
	v_mfma_f32_16x16x32_bf16 v[56:59], v[156:159], v[192:195], v[56:59]
	v_mfma_f32_16x16x32_bf16 v[44:47], v[148:151], v[200:203], v[44:47]
	v_mfma_f32_16x16x32_bf16 v[40:43], v[156:159], v[200:203], v[40:43]
	v_mfma_f32_16x16x32_bf16 v[28:31], v[148:151], v[208:211], v[28:31]
	v_mfma_f32_16x16x32_bf16 v[24:27], v[156:159], v[208:211], v[24:27]
	v_mfma_f32_16x16x32_bf16 v[12:15], v[148:151], v[216:219], v[12:15]
	v_mfma_f32_16x16x32_bf16 v[8:11], v[156:159], v[216:219], v[8:11]
	v_mfma_f32_16x16x32_bf16 v[60:63], v[152:155], v[196:199], v[60:63]
	v_mfma_f32_16x16x32_bf16 v[56:59], v[160:163], v[196:199], v[56:59]
	v_mfma_f32_16x16x32_bf16 v[44:47], v[152:155], v[204:207], v[44:47]
	v_mfma_f32_16x16x32_bf16 v[40:43], v[160:163], v[204:207], v[40:43]
	v_mfma_f32_16x16x32_bf16 v[28:31], v[152:155], v[212:215], v[28:31]
	v_mfma_f32_16x16x32_bf16 v[24:27], v[160:163], v[212:215], v[24:27]
	v_mfma_f32_16x16x32_bf16 v[12:15], v[152:155], v[220:223], v[12:15]
	v_mfma_f32_16x16x32_bf16 v[8:11], v[160:163], v[220:223], v[8:11]
	v_mfma_f32_16x16x32_bf16 v[52:55], v[164:167], v[192:195], v[52:55]
	v_mfma_f32_16x16x32_bf16 v[48:51], v[184:187], v[192:195], v[48:51]
	v_mfma_f32_16x16x32_bf16 v[36:39], v[164:167], v[200:203], v[36:39]
	v_mfma_f32_16x16x32_bf16 v[32:35], v[184:187], v[200:203], v[32:35]
	v_mfma_f32_16x16x32_bf16 v[20:23], v[164:167], v[208:211], v[20:23]
	v_mfma_f32_16x16x32_bf16 v[16:19], v[184:187], v[208:211], v[16:19]
	v_mfma_f32_16x16x32_bf16 v[4:7], v[164:167], v[216:219], v[4:7]
	v_mfma_f32_16x16x32_bf16 v[0:3], v[184:187], v[216:219], v[0:3]
	v_mfma_f32_16x16x32_bf16 v[52:55], v[168:171], v[196:199], v[52:55]
	v_mfma_f32_16x16x32_bf16 v[48:51], v[188:191], v[196:199], v[48:51]
	v_mfma_f32_16x16x32_bf16 v[36:39], v[168:171], v[204:207], v[36:39]
	v_mfma_f32_16x16x32_bf16 v[32:35], v[188:191], v[204:207], v[32:35]
	v_mfma_f32_16x16x32_bf16 v[20:23], v[168:171], v[212:215], v[20:23]
	v_mfma_f32_16x16x32_bf16 v[16:19], v[188:191], v[212:215], v[16:19]
	v_mfma_f32_16x16x32_bf16 v[4:7], v[168:171], v[220:223], v[4:7]
	v_mfma_f32_16x16x32_bf16 v[0:3], v[188:191], v[220:223], v[0:3]
	s_setprio 0
	s_barrier
	s_add_i32 s96, 0, 0x18000
	v_add_u32_e32 v136, s96, v175
	s_add_i32 s8, 0, 0x1c000
	ds_read_b128 v[148:151], v136
	ds_read_b128 v[152:155], v136 offset:1024
	ds_read_b128 v[156:159], v136 offset:2048
	ds_read_b128 v[160:163], v136 offset:3072
	v_add_u32_e32 v136, s8, v175
	ds_read_b128 v[164:167], v136
	ds_read_b128 v[168:171], v136 offset:1024
	ds_read_b128 v[184:187], v136 offset:2048
	ds_read_b128 v[188:191], v136 offset:3072
	s_add_u32 s60, s88, 0x80000
	s_addc_u32 s61, s89, 0
	s_mov_b32 m0, s34
	v_lshl_add_u64 v[230:231], s[60:61], 0, v[128:129]
	ds_read_b128 v[192:195], v181 offset:32768
	ds_read_b128 v[196:199], v181 offset:33792
	ds_read_b128 v[200:203], v181 offset:34816
	ds_read_b128 v[204:207], v181 offset:35840
	ds_read_b128 v[208:211], v181 offset:36864
	ds_read_b128 v[212:215], v181 offset:37888
	ds_read_b128 v[216:219], v181 offset:38912
	ds_read_b128 v[220:223], v181 offset:39936
	global_load_lds_dwordx4 v[230:231], off
	v_lshl_add_u64 v[230:231], s[60:61], 0, v[132:133]
	s_mov_b32 m0, s46
	s_nop 0
	global_load_lds_dwordx4 v[230:231], off
	s_waitcnt vmcnt(8)
	s_waitcnt lgkmcnt(0)
	s_setprio 1
	s_barrier
	v_mfma_f32_16x16x32_bf16 v[124:127], v[148:151], v[192:195], v[124:127]
	v_mfma_f32_16x16x32_bf16 v[120:123], v[156:159], v[192:195], v[120:123]
	v_mfma_f32_16x16x32_bf16 v[108:111], v[148:151], v[200:203], v[108:111]
	v_mfma_f32_16x16x32_bf16 v[104:107], v[156:159], v[200:203], v[104:107]
	v_mfma_f32_16x16x32_bf16 v[92:95], v[148:151], v[208:211], v[92:95]
	v_mfma_f32_16x16x32_bf16 v[88:91], v[156:159], v[208:211], v[88:91]
	v_mfma_f32_16x16x32_bf16 v[76:79], v[148:151], v[216:219], v[76:79]
	v_mfma_f32_16x16x32_bf16 v[72:75], v[156:159], v[216:219], v[72:75]
	v_mfma_f32_16x16x32_bf16 v[124:127], v[152:155], v[196:199], v[124:127]
	v_mfma_f32_16x16x32_bf16 v[120:123], v[160:163], v[196:199], v[120:123]
	v_mfma_f32_16x16x32_bf16 v[108:111], v[152:155], v[204:207], v[108:111]
	v_mfma_f32_16x16x32_bf16 v[104:107], v[160:163], v[204:207], v[104:107]
	v_mfma_f32_16x16x32_bf16 v[92:95], v[152:155], v[212:215], v[92:95]
	v_mfma_f32_16x16x32_bf16 v[88:91], v[160:163], v[212:215], v[88:91]
	v_mfma_f32_16x16x32_bf16 v[76:79], v[152:155], v[220:223], v[76:79]
	v_mfma_f32_16x16x32_bf16 v[72:75], v[160:163], v[220:223], v[72:75]
	v_mfma_f32_16x16x32_bf16 v[116:119], v[164:167], v[192:195], v[116:119]
	v_mfma_f32_16x16x32_bf16 v[112:115], v[184:187], v[192:195], v[112:115]
	v_mfma_f32_16x16x32_bf16 v[100:103], v[164:167], v[200:203], v[100:103]
	v_mfma_f32_16x16x32_bf16 v[96:99], v[184:187], v[200:203], v[96:99]
	v_mfma_f32_16x16x32_bf16 v[84:87], v[164:167], v[208:211], v[84:87]
	v_mfma_f32_16x16x32_bf16 v[80:83], v[184:187], v[208:211], v[80:83]
	v_mfma_f32_16x16x32_bf16 v[68:71], v[164:167], v[216:219], v[68:71]
	v_mfma_f32_16x16x32_bf16 v[64:67], v[184:187], v[216:219], v[64:67]
	v_mfma_f32_16x16x32_bf16 v[116:119], v[168:171], v[196:199], v[116:119]
	v_mfma_f32_16x16x32_bf16 v[112:115], v[188:191], v[196:199], v[112:115]
	v_mfma_f32_16x16x32_bf16 v[100:103], v[168:171], v[204:207], v[100:103]
	v_mfma_f32_16x16x32_bf16 v[96:99], v[188:191], v[204:207], v[96:99]
	v_mfma_f32_16x16x32_bf16 v[84:87], v[168:171], v[212:215], v[84:87]
	v_mfma_f32_16x16x32_bf16 v[80:83], v[188:191], v[212:215], v[80:83]
	v_mfma_f32_16x16x32_bf16 v[68:71], v[168:171], v[220:223], v[68:71]
	v_mfma_f32_16x16x32_bf16 v[64:67], v[188:191], v[220:223], v[64:67]
	s_setprio 0
	s_barrier
	s_add_i32 s9, s96, s94
	v_lshl_add_u64 v[172:173], v[172:173], 0, s[74:75]
	s_mov_b32 m0, s9
	ds_read_b128 v[192:195], v181 offset:49152
	ds_read_b128 v[196:199], v181 offset:50176
	ds_read_b128 v[200:203], v181 offset:51200
	ds_read_b128 v[204:207], v181 offset:52224
	ds_read_b128 v[208:211], v181 offset:53248
	ds_read_b128 v[212:215], v181 offset:54272
	ds_read_b128 v[216:219], v181 offset:55296
	ds_read_b128 v[220:223], v181 offset:56320
	global_load_lds_dwordx4 v[172:173], off
	s_add_i32 m0, s9, 0x2000
	s_add_u32 s60, s86, 0x80080
	v_lshl_add_u64 v[172:173], v[224:225], 0, s[74:75]
	s_addc_u32 s61, s87, 0
	s_add_i32 s8, s8, s94
	global_load_lds_dwordx4 v[172:173], off
	v_lshl_add_u64 v[172:173], s[60:61], 0, v[130:131]
	s_mov_b32 m0, s8
	s_nop 0
	global_load_lds_dwordx4 v[172:173], off
	v_lshl_add_u64 v[172:173], s[60:61], 0, v[134:135]
	s_add_i32 m0, s8, 0x2000
	s_nop 0
	global_load_lds_dwordx4 v[172:173], off
	v_lshl_add_u64 v[172:173], v[226:227], 0, s[74:75]
	s_mov_b32 m0, s56
	s_nop 0
	global_load_lds_dwordx4 v[172:173], off
	v_lshl_add_u64 v[172:173], v[228:229], 0, s[74:75]
	s_mov_b32 m0, s57
	s_nop 0
	global_load_lds_dwordx4 v[172:173], off
	s_waitcnt vmcnt(8)
	s_waitcnt lgkmcnt(0)
	s_setprio 1
	s_barrier
	v_mfma_f32_16x16x32_bf16 v[60:63], v[148:151], v[192:195], v[60:63]
	v_mfma_f32_16x16x32_bf16 v[56:59], v[156:159], v[192:195], v[56:59]
	v_mfma_f32_16x16x32_bf16 v[44:47], v[148:151], v[200:203], v[44:47]
	v_mfma_f32_16x16x32_bf16 v[40:43], v[156:159], v[200:203], v[40:43]
	v_mfma_f32_16x16x32_bf16 v[28:31], v[148:151], v[208:211], v[28:31]
	v_mfma_f32_16x16x32_bf16 v[24:27], v[156:159], v[208:211], v[24:27]
	v_mfma_f32_16x16x32_bf16 v[12:15], v[148:151], v[216:219], v[12:15]
	v_mfma_f32_16x16x32_bf16 v[8:11], v[156:159], v[216:219], v[8:11]
	v_mfma_f32_16x16x32_bf16 v[60:63], v[152:155], v[196:199], v[60:63]
	v_mfma_f32_16x16x32_bf16 v[56:59], v[160:163], v[196:199], v[56:59]
	v_mfma_f32_16x16x32_bf16 v[44:47], v[152:155], v[204:207], v[44:47]
	v_mfma_f32_16x16x32_bf16 v[40:43], v[160:163], v[204:207], v[40:43]
	v_mfma_f32_16x16x32_bf16 v[28:31], v[152:155], v[212:215], v[28:31]
	v_mfma_f32_16x16x32_bf16 v[24:27], v[160:163], v[212:215], v[24:27]
	v_mfma_f32_16x16x32_bf16 v[12:15], v[152:155], v[220:223], v[12:15]
	v_mfma_f32_16x16x32_bf16 v[8:11], v[160:163], v[220:223], v[8:11]
	v_mfma_f32_16x16x32_bf16 v[52:55], v[164:167], v[192:195], v[52:55]
	v_mfma_f32_16x16x32_bf16 v[48:51], v[184:187], v[192:195], v[48:51]
	v_mfma_f32_16x16x32_bf16 v[36:39], v[164:167], v[200:203], v[36:39]
	v_mfma_f32_16x16x32_bf16 v[32:35], v[184:187], v[200:203], v[32:35]
	v_mfma_f32_16x16x32_bf16 v[20:23], v[164:167], v[208:211], v[20:23]
	v_mfma_f32_16x16x32_bf16 v[16:19], v[184:187], v[208:211], v[16:19]
	v_mfma_f32_16x16x32_bf16 v[4:7], v[164:167], v[216:219], v[4:7]
	v_mfma_f32_16x16x32_bf16 v[0:3], v[184:187], v[216:219], v[0:3]
	v_mfma_f32_16x16x32_bf16 v[52:55], v[168:171], v[196:199], v[52:55]
	v_mfma_f32_16x16x32_bf16 v[48:51], v[188:191], v[196:199], v[48:51]
	v_mfma_f32_16x16x32_bf16 v[36:39], v[168:171], v[204:207], v[36:39]
	v_mfma_f32_16x16x32_bf16 v[32:35], v[188:191], v[204:207], v[32:35]
	v_mfma_f32_16x16x32_bf16 v[20:23], v[168:171], v[212:215], v[20:23]
	v_mfma_f32_16x16x32_bf16 v[16:19], v[188:191], v[212:215], v[16:19]
	v_mfma_f32_16x16x32_bf16 v[4:7], v[168:171], v[220:223], v[4:7]
	v_mfma_f32_16x16x32_bf16 v[0:3], v[188:191], v[220:223], v[0:3]
	s_setprio 0
	s_barrier
	s_add_i32 s95, s95, 2
	s_add_u32 s84, s84, 0x100
	s_addc_u32 s85, s85, 0
	s_add_u32 vcc_hi, vcc_hi, 0x100
	s_addc_u32 s97, s97, 0
	s_cmp_gt_u32 s95, 29
	s_cbranch_scc0 .LBB0_2128
	s_and_b64 vcc, exec, s[58:59]
	s_cbranch_vccz .LBB0_2131
	s_barrier

.LBB0_2459:
	ds_read_b128 v[148:151], v163
	ds_read_b128 v[152:155], v163 offset:1024
	ds_read_b128 v[168:171], v163 offset:2048
	ds_read_b128 v[172:175], v163 offset:3072
	ds_read_b128 v[176:179], v164
	ds_read_b128 v[180:183], v164 offset:1024
	ds_read_b128 v[184:187], v164 offset:2048
	ds_read_b128 v[188:191], v164 offset:3072
	s_add_u32 s16, s70, 0x100
	s_addc_u32 s17, s71, 0
	s_cmp_eq_u32 s86, 8
	s_cselect_b32 s75, s23, s17
	s_cselect_b32 s74, s22, s16
	s_cselect_b32 s73, s49, s85
	s_cselect_b32 s72, s48, s84
	v_lshl_add_u64 v[156:157], s[70:71], 0, v[140:141]
	s_add_i32 m0, s12, 0xc000
	ds_read_b128 v[192:195], v165
	ds_read_b128 v[196:199], v165 offset:1024
	ds_read_b128 v[200:203], v165 offset:2048
	ds_read_b128 v[204:207], v165 offset:3072
	ds_read_b128 v[208:211], v165 offset:4096
	ds_read_b128 v[212:215], v165 offset:5120
	ds_read_b128 v[216:219], v165 offset:6144
	ds_read_b128 v[220:223], v165 offset:7168
	global_load_lds_dwordx4 v[156:157], off
	v_lshl_add_u64 v[156:157], s[70:71], 0, v[142:143]
	s_add_i32 m0, s12, 0xe000
	s_nop 0
	global_load_lds_dwordx4 v[156:157], off
	s_waitcnt vmcnt(8)
	s_waitcnt lgkmcnt(0)
	s_setprio 1
	s_barrier
	v_mfma_f32_16x16x32_bf16 v[124:127], v[148:151], v[192:195], v[124:127]
	v_mfma_f32_16x16x32_bf16 v[120:123], v[168:171], v[192:195], v[120:123]
	v_mfma_f32_16x16x32_bf16 v[108:111], v[148:151], v[200:203], v[108:111]
	v_mfma_f32_16x16x32_bf16 v[104:107], v[168:171], v[200:203], v[104:107]
	v_mfma_f32_16x16x32_bf16 v[92:95], v[148:151], v[208:211], v[92:95]
	v_mfma_f32_16x16x32_bf16 v[88:91], v[168:171], v[208:211], v[88:91]
	v_mfma_f32_16x16x32_bf16 v[76:79], v[148:151], v[216:219], v[76:79]
	v_mfma_f32_16x16x32_bf16 v[72:75], v[168:171], v[216:219], v[72:75]
	v_mfma_f32_16x16x32_bf16 v[124:127], v[152:155], v[196:199], v[124:127]
	v_mfma_f32_16x16x32_bf16 v[120:123], v[172:175], v[196:199], v[120:123]
	v_mfma_f32_16x16x32_bf16 v[108:111], v[152:155], v[204:207], v[108:111]
	v_mfma_f32_16x16x32_bf16 v[104:107], v[172:175], v[204:207], v[104:107]
	v_mfma_f32_16x16x32_bf16 v[92:95], v[152:155], v[212:215], v[92:95]
	v_mfma_f32_16x16x32_bf16 v[88:91], v[172:175], v[212:215], v[88:91]
	v_mfma_f32_16x16x32_bf16 v[76:79], v[152:155], v[220:223], v[76:79]
	v_mfma_f32_16x16x32_bf16 v[72:75], v[172:175], v[220:223], v[72:75]
	v_mfma_f32_16x16x32_bf16 v[116:119], v[176:179], v[192:195], v[116:119]
	v_mfma_f32_16x16x32_bf16 v[112:115], v[184:187], v[192:195], v[112:115]
	v_mfma_f32_16x16x32_bf16 v[100:103], v[176:179], v[200:203], v[100:103]
	v_mfma_f32_16x16x32_bf16 v[96:99], v[184:187], v[200:203], v[96:99]
	v_mfma_f32_16x16x32_bf16 v[84:87], v[176:179], v[208:211], v[84:87]
	v_mfma_f32_16x16x32_bf16 v[80:83], v[184:187], v[208:211], v[80:83]
	v_mfma_f32_16x16x32_bf16 v[68:71], v[176:179], v[216:219], v[68:71]
	v_mfma_f32_16x16x32_bf16 v[64:67], v[184:187], v[216:219], v[64:67]
	v_mfma_f32_16x16x32_bf16 v[116:119], v[180:183], v[196:199], v[116:119]
	v_mfma_f32_16x16x32_bf16 v[112:115], v[188:191], v[196:199], v[112:115]
	v_mfma_f32_16x16x32_bf16 v[100:103], v[180:183], v[204:207], v[100:103]
	v_mfma_f32_16x16x32_bf16 v[96:99], v[188:191], v[204:207], v[96:99]
	v_mfma_f32_16x16x32_bf16 v[84:87], v[180:183], v[212:215], v[84:87]
	v_mfma_f32_16x16x32_bf16 v[80:83], v[188:191], v[212:215], v[80:83]
	v_mfma_f32_16x16x32_bf16 v[68:71], v[180:183], v[220:223], v[68:71]
	v_mfma_f32_16x16x32_bf16 v[64:67], v[188:191], v[220:223], v[64:67]
	s_setprio 0
	s_barrier
	s_add_i32 s8, s76, s94
	v_lshl_add_u64 v[156:157], s[72:73], 0, v[130:131]
	s_mov_b32 m0, s8
	ds_read_b128 v[192:195], v165 offset:16384
	ds_read_b128 v[196:199], v165 offset:17408
	ds_read_b128 v[200:203], v165 offset:18432
	ds_read_b128 v[204:207], v165 offset:19456
	ds_read_b128 v[208:211], v165 offset:20480
	ds_read_b128 v[212:215], v165 offset:21504
	ds_read_b128 v[216:219], v165 offset:22528
	ds_read_b128 v[220:223], v165 offset:23552
	global_load_lds_dwordx4 v[156:157], off
	s_add_i32 m0, s8, 0x2000
	s_add_u32 s60, s72, 0x30000
	v_lshl_add_u64 v[224:225], s[72:73], 0, v[134:135]
	s_addc_u32 s61, s73, 0
	s_add_i32 s8, s77, s94
	global_load_lds_dwordx4 v[224:225], off
	v_lshl_add_u64 v[226:227], s[60:61], 0, v[130:131]
	s_mov_b32 m0, s8
	v_lshl_add_u64 v[228:229], s[74:75], 0, v[132:133]
	global_load_lds_dwordx4 v[226:227], off
	v_lshl_add_u64 v[226:227], s[60:61], 0, v[134:135]
	s_add_i32 m0, s8, 0x2000
	s_nop 0
	global_load_lds_dwordx4 v[226:227], off
	v_lshl_add_u64 v[226:227], s[74:75], 0, v[128:129]
	s_mov_b32 m0, s12
	s_nop 0
	global_load_lds_dwordx4 v[226:227], off
	s_mov_b32 m0, s13
	s_nop 0
	global_load_lds_dwordx4 v[228:229], off
	s_waitcnt vmcnt(8)
	s_waitcnt lgkmcnt(0)
	s_setprio 1
	s_barrier
	v_mfma_f32_16x16x32_bf16 v[60:63], v[148:151], v[192:195], v[60:63]
	v_mfma_f32_16x16x32_bf16 v[56:59], v[168:171], v[192:195], v[56:59]
	v_mfma_f32_16x16x32_bf16 v[44:47], v[148:151], v[200:203], v[44:47]
	v_mfma_f32_16x16x32_bf16 v[40:43], v[168:171], v[200:203], v[40:43]
	v_mfma_f32_16x16x32_bf16 v[28:31], v[148:151], v[208:211], v[28:31]
	v_mfma_f32_16x16x32_bf16 v[24:27], v[168:171], v[208:211], v[24:27]
	v_mfma_f32_16x16x32_bf16 v[12:15], v[148:151], v[216:219], v[12:15]
	v_mfma_f32_16x16x32_bf16 v[8:11], v[168:171], v[216:219], v[8:11]
	v_mfma_f32_16x16x32_bf16 v[60:63], v[152:155], v[196:199], v[60:63]
	v_mfma_f32_16x16x32_bf16 v[56:59], v[172:175], v[196:199], v[56:59]
	v_mfma_f32_16x16x32_bf16 v[44:47], v[152:155], v[204:207], v[44:47]
	v_mfma_f32_16x16x32_bf16 v[40:43], v[172:175], v[204:207], v[40:43]
	v_mfma_f32_16x16x32_bf16 v[28:31], v[152:155], v[212:215], v[28:31]
	v_mfma_f32_16x16x32_bf16 v[24:27], v[172:175], v[212:215], v[24:27]
	v_mfma_f32_16x16x32_bf16 v[12:15], v[152:155], v[220:223], v[12:15]
	v_mfma_f32_16x16x32_bf16 v[8:11], v[172:175], v[220:223], v[8:11]
	v_mfma_f32_16x16x32_bf16 v[52:55], v[176:179], v[192:195], v[52:55]
	v_mfma_f32_16x16x32_bf16 v[48:51], v[184:187], v[192:195], v[48:51]
	v_mfma_f32_16x16x32_bf16 v[36:39], v[176:179], v[200:203], v[36:39]
	v_mfma_f32_16x16x32_bf16 v[32:35], v[184:187], v[200:203], v[32:35]
	v_mfma_f32_16x16x32_bf16 v[20:23], v[176:179], v[208:211], v[20:23]
	v_mfma_f32_16x16x32_bf16 v[16:19], v[184:187], v[208:211], v[16:19]
	v_mfma_f32_16x16x32_bf16 v[4:7], v[176:179], v[216:219], v[4:7]
	v_mfma_f32_16x16x32_bf16 v[0:3], v[184:187], v[216:219], v[0:3]
	v_mfma_f32_16x16x32_bf16 v[52:55], v[180:183], v[196:199], v[52:55]
	v_mfma_f32_16x16x32_bf16 v[48:51], v[188:191], v[196:199], v[48:51]
	v_mfma_f32_16x16x32_bf16 v[36:39], v[180:183], v[204:207], v[36:39]
	v_mfma_f32_16x16x32_bf16 v[32:35], v[188:191], v[204:207], v[32:35]
	v_mfma_f32_16x16x32_bf16 v[20:23], v[180:183], v[212:215], v[20:23]
	v_mfma_f32_16x16x32_bf16 v[16:19], v[188:191], v[212:215], v[16:19]
	v_mfma_f32_16x16x32_bf16 v[4:7], v[180:183], v[220:223], v[4:7]
	v_mfma_f32_16x16x32_bf16 v[0:3], v[188:191], v[220:223], v[0:3]
	s_setprio 0
	s_barrier
	s_add_i32 s8, 0, 0x18000
	v_add_u32_e32 v136, s8, v159
	s_add_i32 s9, 0, 0x1c000
	ds_read_b128 v[148:151], v136
	ds_read_b128 v[152:155], v136 offset:1024
	ds_read_b128 v[168:171], v136 offset:2048
	ds_read_b128 v[172:175], v136 offset:3072
	v_add_u32_e32 v136, s9, v159
	ds_read_b128 v[176:179], v136
	ds_read_b128 v[180:183], v136 offset:1024
	ds_read_b128 v[184:187], v136 offset:2048
	ds_read_b128 v[188:191], v136 offset:3072
	s_add_u32 s60, s74, 0x60000
	s_addc_u32 s61, s75, 0
	s_mov_b32 m0, s29
	v_lshl_add_u64 v[230:231], s[60:61], 0, v[128:129]
	ds_read_b128 v[192:195], v165 offset:32768
	ds_read_b128 v[196:199], v165 offset:33792
	ds_read_b128 v[200:203], v165 offset:34816
	ds_read_b128 v[204:207], v165 offset:35840
	ds_read_b128 v[208:211], v165 offset:36864
	ds_read_b128 v[212:215], v165 offset:37888
	ds_read_b128 v[216:219], v165 offset:38912
	ds_read_b128 v[220:223], v165 offset:39936
	global_load_lds_dwordx4 v[230:231], off
	v_lshl_add_u64 v[230:231], s[60:61], 0, v[132:133]
	s_mov_b32 m0, s30
	s_nop 0
	global_load_lds_dwordx4 v[230:231], off
	s_waitcnt vmcnt(8)
	s_waitcnt lgkmcnt(0)
	s_setprio 1
	s_barrier
	v_mfma_f32_16x16x32_bf16 v[124:127], v[148:151], v[192:195], v[124:127]
	v_mfma_f32_16x16x32_bf16 v[120:123], v[168:171], v[192:195], v[120:123]
	v_mfma_f32_16x16x32_bf16 v[108:111], v[148:151], v[200:203], v[108:111]
	v_mfma_f32_16x16x32_bf16 v[104:107], v[168:171], v[200:203], v[104:107]
	v_mfma_f32_16x16x32_bf16 v[92:95], v[148:151], v[208:211], v[92:95]
	v_mfma_f32_16x16x32_bf16 v[88:91], v[168:171], v[208:211], v[88:91]
	v_mfma_f32_16x16x32_bf16 v[76:79], v[148:151], v[216:219], v[76:79]
	v_mfma_f32_16x16x32_bf16 v[72:75], v[168:171], v[216:219], v[72:75]
	v_mfma_f32_16x16x32_bf16 v[124:127], v[152:155], v[196:199], v[124:127]
	v_mfma_f32_16x16x32_bf16 v[120:123], v[172:175], v[196:199], v[120:123]
	v_mfma_f32_16x16x32_bf16 v[108:111], v[152:155], v[204:207], v[108:111]
	v_mfma_f32_16x16x32_bf16 v[104:107], v[172:175], v[204:207], v[104:107]
	v_mfma_f32_16x16x32_bf16 v[92:95], v[152:155], v[212:215], v[92:95]
	v_mfma_f32_16x16x32_bf16 v[88:91], v[172:175], v[212:215], v[88:91]
	v_mfma_f32_16x16x32_bf16 v[76:79], v[152:155], v[220:223], v[76:79]
	v_mfma_f32_16x16x32_bf16 v[72:75], v[172:175], v[220:223], v[72:75]
	v_mfma_f32_16x16x32_bf16 v[116:119], v[176:179], v[192:195], v[116:119]
	v_mfma_f32_16x16x32_bf16 v[112:115], v[184:187], v[192:195], v[112:115]
	v_mfma_f32_16x16x32_bf16 v[100:103], v[176:179], v[200:203], v[100:103]
	v_mfma_f32_16x16x32_bf16 v[96:99], v[184:187], v[200:203], v[96:99]
	v_mfma_f32_16x16x32_bf16 v[84:87], v[176:179], v[208:211], v[84:87]
	v_mfma_f32_16x16x32_bf16 v[80:83], v[184:187], v[208:211], v[80:83]
	v_mfma_f32_16x16x32_bf16 v[68:71], v[176:179], v[216:219], v[68:71]
	v_mfma_f32_16x16x32_bf16 v[64:67], v[184:187], v[216:219], v[64:67]
	v_mfma_f32_16x16x32_bf16 v[116:119], v[180:183], v[196:199], v[116:119]
	v_mfma_f32_16x16x32_bf16 v[112:115], v[188:191], v[196:199], v[112:115]
	v_mfma_f32_16x16x32_bf16 v[100:103], v[180:183], v[204:207], v[100:103]
	v_mfma_f32_16x16x32_bf16 v[96:99], v[188:191], v[204:207], v[96:99]
	v_mfma_f32_16x16x32_bf16 v[84:87], v[180:183], v[212:215], v[84:87]
	v_mfma_f32_16x16x32_bf16 v[80:83], v[188:191], v[212:215], v[80:83]
	v_mfma_f32_16x16x32_bf16 v[68:71], v[180:183], v[220:223], v[68:71]
	v_mfma_f32_16x16x32_bf16 v[64:67], v[188:191], v[220:223], v[64:67]
	s_setprio 0
	s_barrier
	s_add_i32 s8, s8, s94
	v_lshl_add_u64 v[156:157], v[156:157], 0, s[20:21]
	s_mov_b32 m0, s8
	ds_read_b128 v[192:195], v165 offset:49152
	ds_read_b128 v[196:199], v165 offset:50176
	ds_read_b128 v[200:203], v165 offset:51200
	ds_read_b128 v[204:207], v165 offset:52224
	ds_read_b128 v[208:211], v165 offset:53248
	ds_read_b128 v[212:215], v165 offset:54272
	ds_read_b128 v[216:219], v165 offset:55296
	ds_read_b128 v[220:223], v165 offset:56320
	global_load_lds_dwordx4 v[156:157], off
	s_add_i32 m0, s8, 0x2000
	s_add_u32 s60, s72, 0x30080
	v_lshl_add_u64 v[156:157], v[224:225], 0, s[20:21]
	s_addc_u32 s61, s73, 0
	s_add_i32 s8, s9, s94
	global_load_lds_dwordx4 v[156:157], off
	v_lshl_add_u64 v[156:157], s[60:61], 0, v[130:131]
	s_mov_b32 m0, s8
	s_nop 0
	global_load_lds_dwordx4 v[156:157], off
	v_lshl_add_u64 v[156:157], s[60:61], 0, v[134:135]
	s_add_i32 m0, s8, 0x2000
	s_nop 0
	global_load_lds_dwordx4 v[156:157], off
	v_lshl_add_u64 v[156:157], v[226:227], 0, s[20:21]
	s_mov_b32 m0, s46
	s_nop 0
	global_load_lds_dwordx4 v[156:157], off
	v_lshl_add_u64 v[156:157], v[228:229], 0, s[20:21]
	s_mov_b32 m0, s56
	s_nop 0
	global_load_lds_dwordx4 v[156:157], off
	s_waitcnt vmcnt(8)
	s_waitcnt lgkmcnt(0)
	s_setprio 1
	s_barrier
	v_mfma_f32_16x16x32_bf16 v[60:63], v[148:151], v[192:195], v[60:63]
	v_mfma_f32_16x16x32_bf16 v[56:59], v[168:171], v[192:195], v[56:59]
	v_mfma_f32_16x16x32_bf16 v[44:47], v[148:151], v[200:203], v[44:47]
	v_mfma_f32_16x16x32_bf16 v[40:43], v[168:171], v[200:203], v[40:43]
	v_mfma_f32_16x16x32_bf16 v[28:31], v[148:151], v[208:211], v[28:31]
	v_mfma_f32_16x16x32_bf16 v[24:27], v[168:171], v[208:211], v[24:27]
	v_mfma_f32_16x16x32_bf16 v[12:15], v[148:151], v[216:219], v[12:15]
	v_mfma_f32_16x16x32_bf16 v[8:11], v[168:171], v[216:219], v[8:11]
	v_mfma_f32_16x16x32_bf16 v[60:63], v[152:155], v[196:199], v[60:63]
	v_mfma_f32_16x16x32_bf16 v[56:59], v[172:175], v[196:199], v[56:59]
	v_mfma_f32_16x16x32_bf16 v[44:47], v[152:155], v[204:207], v[44:47]
	v_mfma_f32_16x16x32_bf16 v[40:43], v[172:175], v[204:207], v[40:43]
	v_mfma_f32_16x16x32_bf16 v[28:31], v[152:155], v[212:215], v[28:31]
	v_mfma_f32_16x16x32_bf16 v[24:27], v[172:175], v[212:215], v[24:27]
	v_mfma_f32_16x16x32_bf16 v[12:15], v[152:155], v[220:223], v[12:15]
	v_mfma_f32_16x16x32_bf16 v[8:11], v[172:175], v[220:223], v[8:11]
	v_mfma_f32_16x16x32_bf16 v[52:55], v[176:179], v[192:195], v[52:55]
	v_mfma_f32_16x16x32_bf16 v[48:51], v[184:187], v[192:195], v[48:51]
	v_mfma_f32_16x16x32_bf16 v[36:39], v[176:179], v[200:203], v[36:39]
	v_mfma_f32_16x16x32_bf16 v[32:35], v[184:187], v[200:203], v[32:35]
	v_mfma_f32_16x16x32_bf16 v[20:23], v[176:179], v[208:211], v[20:23]
	v_mfma_f32_16x16x32_bf16 v[16:19], v[184:187], v[208:211], v[16:19]
	v_mfma_f32_16x16x32_bf16 v[4:7], v[176:179], v[216:219], v[4:7]
	v_mfma_f32_16x16x32_bf16 v[0:3], v[184:187], v[216:219], v[0:3]
	v_mfma_f32_16x16x32_bf16 v[52:55], v[180:183], v[196:199], v[52:55]
	v_mfma_f32_16x16x32_bf16 v[48:51], v[188:191], v[196:199], v[48:51]
	v_mfma_f32_16x16x32_bf16 v[36:39], v[180:183], v[204:207], v[36:39]
	v_mfma_f32_16x16x32_bf16 v[32:35], v[188:191], v[204:207], v[32:35]
	v_mfma_f32_16x16x32_bf16 v[20:23], v[180:183], v[212:215], v[20:23]
	v_mfma_f32_16x16x32_bf16 v[16:19], v[188:191], v[212:215], v[16:19]
	v_mfma_f32_16x16x32_bf16 v[4:7], v[180:183], v[220:223], v[4:7]
	v_mfma_f32_16x16x32_bf16 v[0:3], v[188:191], v[220:223], v[0:3]
	s_setprio 0
	s_barrier
	s_add_i32 s86, s86, 2
	s_add_u32 s84, s84, 0x100
	s_addc_u32 s85, s85, 0
	s_cmp_gt_u32 s86, 9
	s_mov_b64 s[70:71], s[16:17]
	s_cbranch_scc0 .LBB0_2459
	s_and_b64 vcc, exec, s[58:59]
	s_cbranch_vccz .LBB0_2462
	s_barrier

.LBB0_2535:
	ds_read_b128 v[146:149], v155
	ds_read_b128 v[160:163], v155 offset:1024
	ds_read_b128 v[164:167], v155 offset:2048
	ds_read_b128 v[168:171], v155 offset:3072
	ds_read_b128 v[172:175], v156
	ds_read_b128 v[176:179], v156 offset:1024
	ds_read_b128 v[180:183], v156 offset:2048
	ds_read_b128 v[184:187], v156 offset:3072
	s_add_u32 s16, s68, 0x100
	s_addc_u32 s17, s69, 0
	s_cmp_eq_u32 s80, 4
	s_cselect_b32 s73, s49, s17
	s_cselect_b32 s72, s48, s16
	s_cselect_b32 s71, s43, s79
	s_cselect_b32 s70, s77, s78
	v_lshl_add_u64 v[220:221], s[68:69], 0, v[138:139]
	s_add_i32 m0, s29, 0xc000
	ds_read_b128 v[188:191], v157
	ds_read_b128 v[192:195], v157 offset:1024
	ds_read_b128 v[196:199], v157 offset:2048
	ds_read_b128 v[200:203], v157 offset:3072
	ds_read_b128 v[204:207], v157 offset:4096
	ds_read_b128 v[208:211], v157 offset:5120
	ds_read_b128 v[212:215], v157 offset:6144
	ds_read_b128 v[216:219], v157 offset:7168
	global_load_lds_dwordx4 v[220:221], off
	v_lshl_add_u64 v[220:221], s[68:69], 0, v[140:141]
	s_add_i32 m0, s29, 0xe000
	s_nop 0
	global_load_lds_dwordx4 v[220:221], off
	s_waitcnt vmcnt(8)
	s_waitcnt lgkmcnt(0)
	s_setprio 1
	s_barrier
	v_mfma_f32_16x16x32_bf16 v[124:127], v[146:149], v[188:191], v[124:127]
	v_mfma_f32_16x16x32_bf16 v[120:123], v[164:167], v[188:191], v[120:123]
	v_mfma_f32_16x16x32_bf16 v[108:111], v[146:149], v[196:199], v[108:111]
	v_mfma_f32_16x16x32_bf16 v[104:107], v[164:167], v[196:199], v[104:107]
	v_mfma_f32_16x16x32_bf16 v[92:95], v[146:149], v[204:207], v[92:95]
	v_mfma_f32_16x16x32_bf16 v[88:91], v[164:167], v[204:207], v[88:91]
	v_mfma_f32_16x16x32_bf16 v[76:79], v[146:149], v[212:215], v[76:79]
	v_mfma_f32_16x16x32_bf16 v[72:75], v[164:167], v[212:215], v[72:75]
	v_mfma_f32_16x16x32_bf16 v[124:127], v[160:163], v[192:195], v[124:127]
	v_mfma_f32_16x16x32_bf16 v[120:123], v[168:171], v[192:195], v[120:123]
	v_mfma_f32_16x16x32_bf16 v[108:111], v[160:163], v[200:203], v[108:111]
	v_mfma_f32_16x16x32_bf16 v[104:107], v[168:171], v[200:203], v[104:107]
	v_mfma_f32_16x16x32_bf16 v[92:95], v[160:163], v[208:211], v[92:95]
	v_mfma_f32_16x16x32_bf16 v[88:91], v[168:171], v[208:211], v[88:91]
	v_mfma_f32_16x16x32_bf16 v[76:79], v[160:163], v[216:219], v[76:79]
	v_mfma_f32_16x16x32_bf16 v[72:75], v[168:171], v[216:219], v[72:75]
	v_mfma_f32_16x16x32_bf16 v[116:119], v[172:175], v[188:191], v[116:119]
	v_mfma_f32_16x16x32_bf16 v[112:115], v[180:183], v[188:191], v[112:115]
	v_mfma_f32_16x16x32_bf16 v[100:103], v[172:175], v[196:199], v[100:103]
	v_mfma_f32_16x16x32_bf16 v[96:99], v[180:183], v[196:199], v[96:99]
	v_mfma_f32_16x16x32_bf16 v[84:87], v[172:175], v[204:207], v[84:87]
	v_mfma_f32_16x16x32_bf16 v[80:83], v[180:183], v[204:207], v[80:83]
	v_mfma_f32_16x16x32_bf16 v[68:71], v[172:175], v[212:215], v[68:71]
	v_mfma_f32_16x16x32_bf16 v[64:67], v[180:183], v[212:215], v[64:67]
	v_mfma_f32_16x16x32_bf16 v[116:119], v[176:179], v[192:195], v[116:119]
	v_mfma_f32_16x16x32_bf16 v[112:115], v[184:187], v[192:195], v[112:115]
	v_mfma_f32_16x16x32_bf16 v[100:103], v[176:179], v[200:203], v[100:103]
	v_mfma_f32_16x16x32_bf16 v[96:99], v[184:187], v[200:203], v[96:99]
	v_mfma_f32_16x16x32_bf16 v[84:87], v[176:179], v[208:211], v[84:87]
	v_mfma_f32_16x16x32_bf16 v[80:83], v[184:187], v[208:211], v[80:83]
	v_mfma_f32_16x16x32_bf16 v[68:71], v[176:179], v[216:219], v[68:71]
	v_mfma_f32_16x16x32_bf16 v[64:67], v[184:187], v[216:219], v[64:67]
	s_setprio 0
	s_barrier
	s_add_i32 s8, s67, s94
	v_lshl_add_u64 v[220:221], s[70:71], 0, v[130:131]
	s_mov_b32 m0, s8
	ds_read_b128 v[188:191], v157 offset:16384
	ds_read_b128 v[192:195], v157 offset:17408
	ds_read_b128 v[196:199], v157 offset:18432
	ds_read_b128 v[200:203], v157 offset:19456
	ds_read_b128 v[204:207], v157 offset:20480
	ds_read_b128 v[208:211], v157 offset:21504
	ds_read_b128 v[212:215], v157 offset:22528
	ds_read_b128 v[216:219], v157 offset:23552
	global_load_lds_dwordx4 v[220:221], off
	s_add_i32 m0, s8, 0x2000
	s_add_u32 s60, s70, 0x20000
	v_lshl_add_u64 v[222:223], s[70:71], 0, v[134:135]
	s_addc_u32 s61, s71, 0
	s_add_i32 s8, s74, s94
	global_load_lds_dwordx4 v[222:223], off
	v_lshl_add_u64 v[224:225], s[60:61], 0, v[130:131]
	s_mov_b32 m0, s8
	v_lshl_add_u64 v[226:227], s[72:73], 0, v[132:133]
	global_load_lds_dwordx4 v[224:225], off
	v_lshl_add_u64 v[224:225], s[60:61], 0, v[134:135]
	s_add_i32 m0, s8, 0x2000
	s_nop 0
	global_load_lds_dwordx4 v[224:225], off
	v_lshl_add_u64 v[224:225], s[72:73], 0, v[128:129]
	s_mov_b32 m0, s29
	s_nop 0
	global_load_lds_dwordx4 v[224:225], off
	s_mov_b32 m0, s30
	s_nop 0
	global_load_lds_dwordx4 v[226:227], off
	s_waitcnt vmcnt(8)
	s_waitcnt lgkmcnt(0)
	s_setprio 1
	s_barrier
	v_mfma_f32_16x16x32_bf16 v[60:63], v[146:149], v[188:191], v[60:63]
	v_mfma_f32_16x16x32_bf16 v[56:59], v[164:167], v[188:191], v[56:59]
	v_mfma_f32_16x16x32_bf16 v[44:47], v[146:149], v[196:199], v[44:47]
	v_mfma_f32_16x16x32_bf16 v[40:43], v[164:167], v[196:199], v[40:43]
	v_mfma_f32_16x16x32_bf16 v[28:31], v[146:149], v[204:207], v[28:31]
	v_mfma_f32_16x16x32_bf16 v[24:27], v[164:167], v[204:207], v[24:27]
	v_mfma_f32_16x16x32_bf16 v[12:15], v[146:149], v[212:215], v[12:15]
	v_mfma_f32_16x16x32_bf16 v[8:11], v[164:167], v[212:215], v[8:11]
	v_mfma_f32_16x16x32_bf16 v[60:63], v[160:163], v[192:195], v[60:63]
	v_mfma_f32_16x16x32_bf16 v[56:59], v[168:171], v[192:195], v[56:59]
	v_mfma_f32_16x16x32_bf16 v[44:47], v[160:163], v[200:203], v[44:47]
	v_mfma_f32_16x16x32_bf16 v[40:43], v[168:171], v[200:203], v[40:43]
	v_mfma_f32_16x16x32_bf16 v[28:31], v[160:163], v[208:211], v[28:31]
	v_mfma_f32_16x16x32_bf16 v[24:27], v[168:171], v[208:211], v[24:27]
	v_mfma_f32_16x16x32_bf16 v[12:15], v[160:163], v[216:219], v[12:15]
	v_mfma_f32_16x16x32_bf16 v[8:11], v[168:171], v[216:219], v[8:11]
	v_mfma_f32_16x16x32_bf16 v[52:55], v[172:175], v[188:191], v[52:55]
	v_mfma_f32_16x16x32_bf16 v[48:51], v[180:183], v[188:191], v[48:51]
	v_mfma_f32_16x16x32_bf16 v[36:39], v[172:175], v[196:199], v[36:39]
	v_mfma_f32_16x16x32_bf16 v[32:35], v[180:183], v[196:199], v[32:35]
	v_mfma_f32_16x16x32_bf16 v[20:23], v[172:175], v[204:207], v[20:23]
	v_mfma_f32_16x16x32_bf16 v[16:19], v[180:183], v[204:207], v[16:19]
	v_mfma_f32_16x16x32_bf16 v[4:7], v[172:175], v[212:215], v[4:7]
	v_mfma_f32_16x16x32_bf16 v[0:3], v[180:183], v[212:215], v[0:3]
	v_mfma_f32_16x16x32_bf16 v[52:55], v[176:179], v[192:195], v[52:55]
	v_mfma_f32_16x16x32_bf16 v[48:51], v[184:187], v[192:195], v[48:51]
	v_mfma_f32_16x16x32_bf16 v[36:39], v[176:179], v[200:203], v[36:39]
	v_mfma_f32_16x16x32_bf16 v[32:35], v[184:187], v[200:203], v[32:35]
	v_mfma_f32_16x16x32_bf16 v[20:23], v[176:179], v[208:211], v[20:23]
	v_mfma_f32_16x16x32_bf16 v[16:19], v[184:187], v[208:211], v[16:19]
	v_mfma_f32_16x16x32_bf16 v[4:7], v[176:179], v[216:219], v[4:7]
	v_mfma_f32_16x16x32_bf16 v[0:3], v[184:187], v[216:219], v[0:3]
	s_setprio 0
	s_barrier
	s_add_i32 s8, 0, 0x18000
	v_add_u32_e32 v159, s8, v151
	s_add_i32 s9, 0, 0x1c000
	ds_read_b128 v[146:149], v159
	ds_read_b128 v[160:163], v159 offset:1024
	ds_read_b128 v[164:167], v159 offset:2048
	ds_read_b128 v[168:171], v159 offset:3072
	v_add_u32_e32 v159, s9, v151
	ds_read_b128 v[172:175], v159
	ds_read_b128 v[176:179], v159 offset:1024
	ds_read_b128 v[180:183], v159 offset:2048
	ds_read_b128 v[184:187], v159 offset:3072
	s_add_u32 s60, s72, 0x60000
	s_addc_u32 s61, s73, 0
	s_mov_b32 m0, s34
	v_lshl_add_u64 v[228:229], s[60:61], 0, v[128:129]
	ds_read_b128 v[188:191], v157 offset:32768
	ds_read_b128 v[192:195], v157 offset:33792
	ds_read_b128 v[196:199], v157 offset:34816
	ds_read_b128 v[200:203], v157 offset:35840
	ds_read_b128 v[204:207], v157 offset:36864
	ds_read_b128 v[208:211], v157 offset:37888
	ds_read_b128 v[212:215], v157 offset:38912
	ds_read_b128 v[216:219], v157 offset:39936
	global_load_lds_dwordx4 v[228:229], off
	v_lshl_add_u64 v[228:229], s[60:61], 0, v[132:133]
	s_mov_b32 m0, s35
	s_nop 0
	global_load_lds_dwordx4 v[228:229], off
	s_waitcnt vmcnt(8)
	s_waitcnt lgkmcnt(0)
	s_setprio 1
	s_barrier
	v_mfma_f32_16x16x32_bf16 v[124:127], v[146:149], v[188:191], v[124:127]
	v_mfma_f32_16x16x32_bf16 v[120:123], v[164:167], v[188:191], v[120:123]
	v_mfma_f32_16x16x32_bf16 v[108:111], v[146:149], v[196:199], v[108:111]
	v_mfma_f32_16x16x32_bf16 v[104:107], v[164:167], v[196:199], v[104:107]
	v_mfma_f32_16x16x32_bf16 v[92:95], v[146:149], v[204:207], v[92:95]
	v_mfma_f32_16x16x32_bf16 v[88:91], v[164:167], v[204:207], v[88:91]
	v_mfma_f32_16x16x32_bf16 v[76:79], v[146:149], v[212:215], v[76:79]
	v_mfma_f32_16x16x32_bf16 v[72:75], v[164:167], v[212:215], v[72:75]
	v_mfma_f32_16x16x32_bf16 v[124:127], v[160:163], v[192:195], v[124:127]
	v_mfma_f32_16x16x32_bf16 v[120:123], v[168:171], v[192:195], v[120:123]
	v_mfma_f32_16x16x32_bf16 v[108:111], v[160:163], v[200:203], v[108:111]
	v_mfma_f32_16x16x32_bf16 v[104:107], v[168:171], v[200:203], v[104:107]
	v_mfma_f32_16x16x32_bf16 v[92:95], v[160:163], v[208:211], v[92:95]
	v_mfma_f32_16x16x32_bf16 v[88:91], v[168:171], v[208:211], v[88:91]
	v_mfma_f32_16x16x32_bf16 v[76:79], v[160:163], v[216:219], v[76:79]
	v_mfma_f32_16x16x32_bf16 v[72:75], v[168:171], v[216:219], v[72:75]
	v_mfma_f32_16x16x32_bf16 v[116:119], v[172:175], v[188:191], v[116:119]
	v_mfma_f32_16x16x32_bf16 v[112:115], v[180:183], v[188:191], v[112:115]
	v_mfma_f32_16x16x32_bf16 v[100:103], v[172:175], v[196:199], v[100:103]
	v_mfma_f32_16x16x32_bf16 v[96:99], v[180:183], v[196:199], v[96:99]
	v_mfma_f32_16x16x32_bf16 v[84:87], v[172:175], v[204:207], v[84:87]
	v_mfma_f32_16x16x32_bf16 v[80:83], v[180:183], v[204:207], v[80:83]
	v_mfma_f32_16x16x32_bf16 v[68:71], v[172:175], v[212:215], v[68:71]
	v_mfma_f32_16x16x32_bf16 v[64:67], v[180:183], v[212:215], v[64:67]
	v_mfma_f32_16x16x32_bf16 v[116:119], v[176:179], v[192:195], v[116:119]
	v_mfma_f32_16x16x32_bf16 v[112:115], v[184:187], v[192:195], v[112:115]
	v_mfma_f32_16x16x32_bf16 v[100:103], v[176:179], v[200:203], v[100:103]
	v_mfma_f32_16x16x32_bf16 v[96:99], v[184:187], v[200:203], v[96:99]
	v_mfma_f32_16x16x32_bf16 v[84:87], v[176:179], v[208:211], v[84:87]
	v_mfma_f32_16x16x32_bf16 v[80:83], v[184:187], v[208:211], v[80:83]
	v_mfma_f32_16x16x32_bf16 v[68:71], v[176:179], v[216:219], v[68:71]
	v_mfma_f32_16x16x32_bf16 v[64:67], v[184:187], v[216:219], v[64:67]
	s_setprio 0
	s_barrier
	s_add_i32 s8, s8, s94
	v_lshl_add_u64 v[220:221], v[220:221], 0, s[22:23]
	s_mov_b32 m0, s8
	ds_read_b128 v[188:191], v157 offset:49152
	ds_read_b128 v[192:195], v157 offset:50176
	ds_read_b128 v[196:199], v157 offset:51200
	ds_read_b128 v[200:203], v157 offset:52224
	ds_read_b128 v[204:207], v157 offset:53248
	ds_read_b128 v[208:211], v157 offset:54272
	ds_read_b128 v[212:215], v157 offset:55296
	ds_read_b128 v[216:219], v157 offset:56320
	global_load_lds_dwordx4 v[220:221], off
	s_add_i32 m0, s8, 0x2000
	s_add_u32 s60, s70, 0x20080
	v_lshl_add_u64 v[220:221], v[222:223], 0, s[22:23]
	s_addc_u32 s61, s71, 0
	s_add_i32 s8, s9, s94
	global_load_lds_dwordx4 v[220:221], off
	v_lshl_add_u64 v[220:221], s[60:61], 0, v[130:131]
	s_mov_b32 m0, s8
	s_nop 0
	global_load_lds_dwordx4 v[220:221], off
	v_lshl_add_u64 v[220:221], s[60:61], 0, v[134:135]
	s_add_i32 m0, s8, 0x2000
	s_nop 0
	global_load_lds_dwordx4 v[220:221], off
	v_lshl_add_u64 v[220:221], v[224:225], 0, s[22:23]
	s_mov_b32 m0, s56
	s_nop 0
	global_load_lds_dwordx4 v[220:221], off
	v_lshl_add_u64 v[220:221], v[226:227], 0, s[22:23]
	s_mov_b32 m0, s57
	s_nop 0
	global_load_lds_dwordx4 v[220:221], off
	s_waitcnt vmcnt(8)
	s_waitcnt lgkmcnt(0)
	s_setprio 1
	s_barrier
	v_mfma_f32_16x16x32_bf16 v[60:63], v[146:149], v[188:191], v[60:63]
	v_mfma_f32_16x16x32_bf16 v[56:59], v[164:167], v[188:191], v[56:59]
	v_mfma_f32_16x16x32_bf16 v[44:47], v[146:149], v[196:199], v[44:47]
	v_mfma_f32_16x16x32_bf16 v[40:43], v[164:167], v[196:199], v[40:43]
	v_mfma_f32_16x16x32_bf16 v[28:31], v[146:149], v[204:207], v[28:31]
	v_mfma_f32_16x16x32_bf16 v[24:27], v[164:167], v[204:207], v[24:27]
	v_mfma_f32_16x16x32_bf16 v[12:15], v[146:149], v[212:215], v[12:15]
	v_mfma_f32_16x16x32_bf16 v[8:11], v[164:167], v[212:215], v[8:11]
	v_mfma_f32_16x16x32_bf16 v[60:63], v[160:163], v[192:195], v[60:63]
	v_mfma_f32_16x16x32_bf16 v[56:59], v[168:171], v[192:195], v[56:59]
	v_mfma_f32_16x16x32_bf16 v[44:47], v[160:163], v[200:203], v[44:47]
	v_mfma_f32_16x16x32_bf16 v[40:43], v[168:171], v[200:203], v[40:43]
	v_mfma_f32_16x16x32_bf16 v[28:31], v[160:163], v[208:211], v[28:31]
	v_mfma_f32_16x16x32_bf16 v[24:27], v[168:171], v[208:211], v[24:27]
	v_mfma_f32_16x16x32_bf16 v[12:15], v[160:163], v[216:219], v[12:15]
	v_mfma_f32_16x16x32_bf16 v[8:11], v[168:171], v[216:219], v[8:11]
	v_mfma_f32_16x16x32_bf16 v[52:55], v[172:175], v[188:191], v[52:55]
	v_mfma_f32_16x16x32_bf16 v[48:51], v[180:183], v[188:191], v[48:51]
	v_mfma_f32_16x16x32_bf16 v[36:39], v[172:175], v[196:199], v[36:39]
	v_mfma_f32_16x16x32_bf16 v[32:35], v[180:183], v[196:199], v[32:35]
	v_mfma_f32_16x16x32_bf16 v[20:23], v[172:175], v[204:207], v[20:23]
	v_mfma_f32_16x16x32_bf16 v[16:19], v[180:183], v[204:207], v[16:19]
	v_mfma_f32_16x16x32_bf16 v[4:7], v[172:175], v[212:215], v[4:7]
	v_mfma_f32_16x16x32_bf16 v[0:3], v[180:183], v[212:215], v[0:3]
	v_mfma_f32_16x16x32_bf16 v[52:55], v[176:179], v[192:195], v[52:55]
	v_mfma_f32_16x16x32_bf16 v[48:51], v[184:187], v[192:195], v[48:51]
	v_mfma_f32_16x16x32_bf16 v[36:39], v[176:179], v[200:203], v[36:39]
	v_mfma_f32_16x16x32_bf16 v[32:35], v[184:187], v[200:203], v[32:35]
	v_mfma_f32_16x16x32_bf16 v[20:23], v[176:179], v[208:211], v[20:23]
	v_mfma_f32_16x16x32_bf16 v[16:19], v[184:187], v[208:211], v[16:19]
	v_mfma_f32_16x16x32_bf16 v[4:7], v[176:179], v[216:219], v[4:7]
	v_mfma_f32_16x16x32_bf16 v[0:3], v[184:187], v[216:219], v[0:3]
	s_setprio 0
	s_barrier
	s_add_i32 s80, s80, 2
	s_add_u32 s78, s78, 0x100
	s_addc_u32 s79, s79, 0
	s_cmp_gt_u32 s80, 5
	s_mov_b64 s[68:69], s[16:17]
	s_cbranch_scc0 .LBB0_2535
	s_and_b64 vcc, exec, s[58:59]
	s_cbranch_vccz .LBB0_2538
	s_barrier

.LBB0_2713:
	ds_read_b128 v[140:143], v149
	ds_read_b128 v[152:155], v149 offset:1024
	ds_read_b128 v[156:159], v149 offset:2048
	ds_read_b128 v[160:163], v149 offset:3072
	ds_read_b128 v[164:167], v150
	ds_read_b128 v[168:171], v150 offset:1024
	ds_read_b128 v[172:175], v150 offset:2048
	ds_read_b128 v[176:179], v150 offset:3072
	s_add_u32 s8, s62, 0xfff80080
	s_addc_u32 s9, s63, -1
	s_cmp_eq_u32 s72, 28
	s_cselect_b32 s67, s43, s9
	s_cselect_b32 s66, s57, s8
	s_cselect_b32 s65, s23, s71
	s_cselect_b32 s64, s69, s70
	v_lshl_add_u64 v[212:213], s[62:63], 0, v[132:133]
	s_add_i32 m0, s12, 0xc000
	ds_read_b128 v[180:183], v151
	ds_read_b128 v[184:187], v151 offset:1024
	ds_read_b128 v[188:191], v151 offset:2048
	ds_read_b128 v[192:195], v151 offset:3072
	ds_read_b128 v[196:199], v151 offset:4096
	ds_read_b128 v[200:203], v151 offset:5120
	ds_read_b128 v[204:207], v151 offset:6144
	ds_read_b128 v[208:211], v151 offset:7168
	global_load_lds_dwordx4 v[212:213], off
	v_lshl_add_u64 v[212:213], s[62:63], 0, v[134:135]
	s_add_i32 m0, s12, 0xe000
	s_nop 0
	global_load_lds_dwordx4 v[212:213], off
	s_waitcnt vmcnt(8)
	s_waitcnt lgkmcnt(0)
	s_setprio 1
	s_barrier
	v_mfma_f32_16x16x32_bf16 v[124:127], v[140:143], v[180:183], v[124:127]
	v_mfma_f32_16x16x32_bf16 v[120:123], v[156:159], v[180:183], v[120:123]
	v_mfma_f32_16x16x32_bf16 v[108:111], v[140:143], v[188:191], v[108:111]
	v_mfma_f32_16x16x32_bf16 v[104:107], v[156:159], v[188:191], v[104:107]
	v_mfma_f32_16x16x32_bf16 v[92:95], v[140:143], v[196:199], v[92:95]
	v_mfma_f32_16x16x32_bf16 v[88:91], v[156:159], v[196:199], v[88:91]
	v_mfma_f32_16x16x32_bf16 v[76:79], v[140:143], v[204:207], v[76:79]
	v_mfma_f32_16x16x32_bf16 v[72:75], v[156:159], v[204:207], v[72:75]
	v_mfma_f32_16x16x32_bf16 v[124:127], v[152:155], v[184:187], v[124:127]
	v_mfma_f32_16x16x32_bf16 v[120:123], v[160:163], v[184:187], v[120:123]
	v_mfma_f32_16x16x32_bf16 v[108:111], v[152:155], v[192:195], v[108:111]
	v_mfma_f32_16x16x32_bf16 v[104:107], v[160:163], v[192:195], v[104:107]
	v_mfma_f32_16x16x32_bf16 v[92:95], v[152:155], v[200:203], v[92:95]
	v_mfma_f32_16x16x32_bf16 v[88:91], v[160:163], v[200:203], v[88:91]
	v_mfma_f32_16x16x32_bf16 v[76:79], v[152:155], v[208:211], v[76:79]
	v_mfma_f32_16x16x32_bf16 v[72:75], v[160:163], v[208:211], v[72:75]
	v_mfma_f32_16x16x32_bf16 v[116:119], v[164:167], v[180:183], v[116:119]
	v_mfma_f32_16x16x32_bf16 v[112:115], v[172:175], v[180:183], v[112:115]
	v_mfma_f32_16x16x32_bf16 v[100:103], v[164:167], v[188:191], v[100:103]
	v_mfma_f32_16x16x32_bf16 v[96:99], v[172:175], v[188:191], v[96:99]
	v_mfma_f32_16x16x32_bf16 v[84:87], v[164:167], v[196:199], v[84:87]
	v_mfma_f32_16x16x32_bf16 v[80:83], v[172:175], v[196:199], v[80:83]
	v_mfma_f32_16x16x32_bf16 v[68:71], v[164:167], v[204:207], v[68:71]
	v_mfma_f32_16x16x32_bf16 v[64:67], v[172:175], v[204:207], v[64:67]
	v_mfma_f32_16x16x32_bf16 v[116:119], v[168:171], v[184:187], v[116:119]
	v_mfma_f32_16x16x32_bf16 v[112:115], v[176:179], v[184:187], v[112:115]
	v_mfma_f32_16x16x32_bf16 v[100:103], v[168:171], v[192:195], v[100:103]
	v_mfma_f32_16x16x32_bf16 v[96:99], v[176:179], v[192:195], v[96:99]
	v_mfma_f32_16x16x32_bf16 v[84:87], v[168:171], v[200:203], v[84:87]
	v_mfma_f32_16x16x32_bf16 v[80:83], v[176:179], v[200:203], v[80:83]
	v_mfma_f32_16x16x32_bf16 v[68:71], v[168:171], v[208:211], v[68:71]
	v_mfma_f32_16x16x32_bf16 v[64:67], v[176:179], v[208:211], v[64:67]
	s_setprio 0
	s_barrier
	s_add_i32 s8, s46, s94
	v_lshl_add_u64 v[212:213], s[64:65], 0, v[128:129]
	s_mov_b32 m0, s8
	ds_read_b128 v[180:183], v151 offset:16384
	ds_read_b128 v[184:187], v151 offset:17408
	ds_read_b128 v[188:191], v151 offset:18432
	ds_read_b128 v[192:195], v151 offset:19456
	ds_read_b128 v[196:199], v151 offset:20480
	ds_read_b128 v[200:203], v151 offset:21504
	ds_read_b128 v[204:207], v151 offset:22528
	ds_read_b128 v[208:211], v151 offset:23552
	global_load_lds_dwordx4 v[212:213], off
	s_add_i32 m0, s8, 0x2000
	s_add_u32 s60, s64, 0x80000
	v_lshl_add_u64 v[214:215], s[64:65], 0, v[130:131]
	s_addc_u32 s61, s65, 0
	s_add_i32 s8, s47, s94
	global_load_lds_dwordx4 v[214:215], off
	v_lshl_add_u64 v[216:217], s[60:61], 0, v[128:129]
	s_mov_b32 m0, s8
	v_lshl_add_u64 v[218:219], s[66:67], 0, v[130:131]
	global_load_lds_dwordx4 v[216:217], off
	v_lshl_add_u64 v[216:217], s[60:61], 0, v[130:131]
	s_add_i32 m0, s8, 0x2000
	s_nop 0
	global_load_lds_dwordx4 v[216:217], off
	v_lshl_add_u64 v[216:217], s[66:67], 0, v[128:129]
	s_mov_b32 m0, s12
	s_nop 0
	global_load_lds_dwordx4 v[216:217], off
	s_mov_b32 m0, s13
	s_nop 0
	global_load_lds_dwordx4 v[218:219], off
	s_waitcnt vmcnt(8)
	s_waitcnt lgkmcnt(0)
	s_setprio 1
	s_barrier
	v_mfma_f32_16x16x32_bf16 v[60:63], v[140:143], v[180:183], v[60:63]
	v_mfma_f32_16x16x32_bf16 v[56:59], v[156:159], v[180:183], v[56:59]
	v_mfma_f32_16x16x32_bf16 v[44:47], v[140:143], v[188:191], v[44:47]
	v_mfma_f32_16x16x32_bf16 v[40:43], v[156:159], v[188:191], v[40:43]
	v_mfma_f32_16x16x32_bf16 v[28:31], v[140:143], v[196:199], v[28:31]
	v_mfma_f32_16x16x32_bf16 v[24:27], v[156:159], v[196:199], v[24:27]
	v_mfma_f32_16x16x32_bf16 v[12:15], v[140:143], v[204:207], v[12:15]
	v_mfma_f32_16x16x32_bf16 v[8:11], v[156:159], v[204:207], v[8:11]
	v_mfma_f32_16x16x32_bf16 v[60:63], v[152:155], v[184:187], v[60:63]
	v_mfma_f32_16x16x32_bf16 v[56:59], v[160:163], v[184:187], v[56:59]
	v_mfma_f32_16x16x32_bf16 v[44:47], v[152:155], v[192:195], v[44:47]
	v_mfma_f32_16x16x32_bf16 v[40:43], v[160:163], v[192:195], v[40:43]
	v_mfma_f32_16x16x32_bf16 v[28:31], v[152:155], v[200:203], v[28:31]
	v_mfma_f32_16x16x32_bf16 v[24:27], v[160:163], v[200:203], v[24:27]
	v_mfma_f32_16x16x32_bf16 v[12:15], v[152:155], v[208:211], v[12:15]
	v_mfma_f32_16x16x32_bf16 v[8:11], v[160:163], v[208:211], v[8:11]
	v_mfma_f32_16x16x32_bf16 v[52:55], v[164:167], v[180:183], v[52:55]
	v_mfma_f32_16x16x32_bf16 v[48:51], v[172:175], v[180:183], v[48:51]
	v_mfma_f32_16x16x32_bf16 v[36:39], v[164:167], v[188:191], v[36:39]
	v_mfma_f32_16x16x32_bf16 v[32:35], v[172:175], v[188:191], v[32:35]
	v_mfma_f32_16x16x32_bf16 v[20:23], v[164:167], v[196:199], v[20:23]
	v_mfma_f32_16x16x32_bf16 v[16:19], v[172:175], v[196:199], v[16:19]
	v_mfma_f32_16x16x32_bf16 v[4:7], v[164:167], v[204:207], v[4:7]
	v_mfma_f32_16x16x32_bf16 v[0:3], v[172:175], v[204:207], v[0:3]
	v_mfma_f32_16x16x32_bf16 v[52:55], v[168:171], v[184:187], v[52:55]
	v_mfma_f32_16x16x32_bf16 v[48:51], v[176:179], v[184:187], v[48:51]
	v_mfma_f32_16x16x32_bf16 v[36:39], v[168:171], v[192:195], v[36:39]
	v_mfma_f32_16x16x32_bf16 v[32:35], v[176:179], v[192:195], v[32:35]
	v_mfma_f32_16x16x32_bf16 v[20:23], v[168:171], v[200:203], v[20:23]
	v_mfma_f32_16x16x32_bf16 v[16:19], v[176:179], v[200:203], v[16:19]
	v_mfma_f32_16x16x32_bf16 v[4:7], v[168:171], v[208:211], v[4:7]
	v_mfma_f32_16x16x32_bf16 v[0:3], v[176:179], v[208:211], v[0:3]
	s_setprio 0
	s_barrier
	s_add_i32 s8, 0, 0x18000
	s_add_i32 s9, 0, 0x1c000
	v_add_u32_e32 v160, s8, v145
	v_add_u32_e32 v176, s9, v145
	ds_read_b128 v[140:143], v160
	ds_read_b128 v[152:155], v160 offset:1024
	ds_read_b128 v[156:159], v160 offset:2048
	ds_read_b128 v[160:163], v160 offset:3072
	ds_read_b128 v[164:167], v176
	ds_read_b128 v[168:171], v176 offset:1024
	ds_read_b128 v[172:175], v176 offset:2048
	ds_read_b128 v[176:179], v176 offset:3072
	s_add_u32 s60, s66, 0x80000
	s_addc_u32 s61, s67, 0
	s_mov_b32 m0, s29
	v_lshl_add_u64 v[220:221], s[60:61], 0, v[128:129]
	ds_read_b128 v[180:183], v151 offset:32768
	ds_read_b128 v[184:187], v151 offset:33792
	ds_read_b128 v[188:191], v151 offset:34816
	ds_read_b128 v[192:195], v151 offset:35840
	ds_read_b128 v[196:199], v151 offset:36864
	ds_read_b128 v[200:203], v151 offset:37888
	ds_read_b128 v[204:207], v151 offset:38912
	ds_read_b128 v[208:211], v151 offset:39936
	global_load_lds_dwordx4 v[220:221], off
	v_lshl_add_u64 v[220:221], s[60:61], 0, v[130:131]
	s_mov_b32 m0, s30
	s_nop 0
	global_load_lds_dwordx4 v[220:221], off
	s_waitcnt vmcnt(8)
	s_waitcnt lgkmcnt(0)
	s_setprio 1
	s_barrier
	v_mfma_f32_16x16x32_bf16 v[124:127], v[140:143], v[180:183], v[124:127]
	v_mfma_f32_16x16x32_bf16 v[120:123], v[156:159], v[180:183], v[120:123]
	v_mfma_f32_16x16x32_bf16 v[108:111], v[140:143], v[188:191], v[108:111]
	v_mfma_f32_16x16x32_bf16 v[104:107], v[156:159], v[188:191], v[104:107]
	v_mfma_f32_16x16x32_bf16 v[92:95], v[140:143], v[196:199], v[92:95]
	v_mfma_f32_16x16x32_bf16 v[88:91], v[156:159], v[196:199], v[88:91]
	v_mfma_f32_16x16x32_bf16 v[76:79], v[140:143], v[204:207], v[76:79]
	v_mfma_f32_16x16x32_bf16 v[72:75], v[156:159], v[204:207], v[72:75]
	v_mfma_f32_16x16x32_bf16 v[124:127], v[152:155], v[184:187], v[124:127]
	v_mfma_f32_16x16x32_bf16 v[120:123], v[160:163], v[184:187], v[120:123]
	v_mfma_f32_16x16x32_bf16 v[108:111], v[152:155], v[192:195], v[108:111]
	v_mfma_f32_16x16x32_bf16 v[104:107], v[160:163], v[192:195], v[104:107]
	v_mfma_f32_16x16x32_bf16 v[92:95], v[152:155], v[200:203], v[92:95]
	v_mfma_f32_16x16x32_bf16 v[88:91], v[160:163], v[200:203], v[88:91]
	v_mfma_f32_16x16x32_bf16 v[76:79], v[152:155], v[208:211], v[76:79]
	v_mfma_f32_16x16x32_bf16 v[72:75], v[160:163], v[208:211], v[72:75]
	v_mfma_f32_16x16x32_bf16 v[116:119], v[164:167], v[180:183], v[116:119]
	v_mfma_f32_16x16x32_bf16 v[112:115], v[172:175], v[180:183], v[112:115]
	v_mfma_f32_16x16x32_bf16 v[100:103], v[164:167], v[188:191], v[100:103]
	v_mfma_f32_16x16x32_bf16 v[96:99], v[172:175], v[188:191], v[96:99]
	v_mfma_f32_16x16x32_bf16 v[84:87], v[164:167], v[196:199], v[84:87]
	v_mfma_f32_16x16x32_bf16 v[80:83], v[172:175], v[196:199], v[80:83]
	v_mfma_f32_16x16x32_bf16 v[68:71], v[164:167], v[204:207], v[68:71]
	v_mfma_f32_16x16x32_bf16 v[64:67], v[172:175], v[204:207], v[64:67]
	v_mfma_f32_16x16x32_bf16 v[116:119], v[168:171], v[184:187], v[116:119]
	v_mfma_f32_16x16x32_bf16 v[112:115], v[176:179], v[184:187], v[112:115]
	v_mfma_f32_16x16x32_bf16 v[100:103], v[168:171], v[192:195], v[100:103]
	v_mfma_f32_16x16x32_bf16 v[96:99], v[176:179], v[192:195], v[96:99]
	v_mfma_f32_16x16x32_bf16 v[84:87], v[168:171], v[200:203], v[84:87]
	v_mfma_f32_16x16x32_bf16 v[80:83], v[176:179], v[200:203], v[80:83]
	v_mfma_f32_16x16x32_bf16 v[68:71], v[168:171], v[208:211], v[68:71]
	v_mfma_f32_16x16x32_bf16 v[64:67], v[176:179], v[208:211], v[64:67]
	s_setprio 0
	s_barrier
	s_add_i32 s8, s8, s94
	v_lshl_add_u64 v[212:213], v[212:213], 0, s[20:21]
	s_mov_b32 m0, s8
	ds_read_b128 v[180:183], v151 offset:49152
	ds_read_b128 v[184:187], v151 offset:50176
	ds_read_b128 v[188:191], v151 offset:51200
	ds_read_b128 v[192:195], v151 offset:52224
	ds_read_b128 v[196:199], v151 offset:53248
	ds_read_b128 v[200:203], v151 offset:54272
	ds_read_b128 v[204:207], v151 offset:55296
	ds_read_b128 v[208:211], v151 offset:56320
	global_load_lds_dwordx4 v[212:213], off
	s_add_i32 m0, s8, 0x2000
	s_add_u32 s60, s64, 0x80080
	v_lshl_add_u64 v[212:213], v[214:215], 0, s[20:21]
	s_addc_u32 s61, s65, 0
	s_add_i32 s8, s9, s94
	global_load_lds_dwordx4 v[212:213], off
	v_lshl_add_u64 v[212:213], s[60:61], 0, v[128:129]
	s_mov_b32 m0, s8
	s_nop 0
	global_load_lds_dwordx4 v[212:213], off
	v_lshl_add_u64 v[212:213], s[60:61], 0, v[130:131]
	s_add_i32 m0, s8, 0x2000
	s_nop 0
	global_load_lds_dwordx4 v[212:213], off
	v_lshl_add_u64 v[212:213], v[216:217], 0, s[20:21]
	s_mov_b32 m0, s34
	s_nop 0
	global_load_lds_dwordx4 v[212:213], off
	v_lshl_add_u64 v[212:213], v[218:219], 0, s[20:21]
	s_mov_b32 m0, s35
	s_nop 0
	global_load_lds_dwordx4 v[212:213], off
	s_waitcnt vmcnt(8)
	s_waitcnt lgkmcnt(0)
	s_setprio 1
	s_barrier
	v_mfma_f32_16x16x32_bf16 v[60:63], v[140:143], v[180:183], v[60:63]
	v_mfma_f32_16x16x32_bf16 v[56:59], v[156:159], v[180:183], v[56:59]
	v_mfma_f32_16x16x32_bf16 v[44:47], v[140:143], v[188:191], v[44:47]
	v_mfma_f32_16x16x32_bf16 v[40:43], v[156:159], v[188:191], v[40:43]
	v_mfma_f32_16x16x32_bf16 v[28:31], v[140:143], v[196:199], v[28:31]
	v_mfma_f32_16x16x32_bf16 v[24:27], v[156:159], v[196:199], v[24:27]
	v_mfma_f32_16x16x32_bf16 v[12:15], v[140:143], v[204:207], v[12:15]
	v_mfma_f32_16x16x32_bf16 v[8:11], v[156:159], v[204:207], v[8:11]
	v_mfma_f32_16x16x32_bf16 v[60:63], v[152:155], v[184:187], v[60:63]
	v_mfma_f32_16x16x32_bf16 v[56:59], v[160:163], v[184:187], v[56:59]
	v_mfma_f32_16x16x32_bf16 v[44:47], v[152:155], v[192:195], v[44:47]
	v_mfma_f32_16x16x32_bf16 v[40:43], v[160:163], v[192:195], v[40:43]
	v_mfma_f32_16x16x32_bf16 v[28:31], v[152:155], v[200:203], v[28:31]
	v_mfma_f32_16x16x32_bf16 v[24:27], v[160:163], v[200:203], v[24:27]
	v_mfma_f32_16x16x32_bf16 v[12:15], v[152:155], v[208:211], v[12:15]
	v_mfma_f32_16x16x32_bf16 v[8:11], v[160:163], v[208:211], v[8:11]
	v_mfma_f32_16x16x32_bf16 v[52:55], v[164:167], v[180:183], v[52:55]
	v_mfma_f32_16x16x32_bf16 v[48:51], v[172:175], v[180:183], v[48:51]
	v_mfma_f32_16x16x32_bf16 v[36:39], v[164:167], v[188:191], v[36:39]
	v_mfma_f32_16x16x32_bf16 v[32:35], v[172:175], v[188:191], v[32:35]
	v_mfma_f32_16x16x32_bf16 v[20:23], v[164:167], v[196:199], v[20:23]
	v_mfma_f32_16x16x32_bf16 v[16:19], v[172:175], v[196:199], v[16:19]
	v_mfma_f32_16x16x32_bf16 v[4:7], v[164:167], v[204:207], v[4:7]
	v_mfma_f32_16x16x32_bf16 v[0:3], v[172:175], v[204:207], v[0:3]
	v_mfma_f32_16x16x32_bf16 v[52:55], v[168:171], v[184:187], v[52:55]
	v_mfma_f32_16x16x32_bf16 v[48:51], v[176:179], v[184:187], v[48:51]
	v_mfma_f32_16x16x32_bf16 v[36:39], v[168:171], v[192:195], v[36:39]
	v_mfma_f32_16x16x32_bf16 v[32:35], v[176:179], v[192:195], v[32:35]
	v_mfma_f32_16x16x32_bf16 v[20:23], v[168:171], v[200:203], v[20:23]
	v_mfma_f32_16x16x32_bf16 v[16:19], v[176:179], v[200:203], v[16:19]
	v_mfma_f32_16x16x32_bf16 v[4:7], v[168:171], v[208:211], v[4:7]
	v_mfma_f32_16x16x32_bf16 v[0:3], v[176:179], v[208:211], v[0:3]
	s_setprio 0
	s_barrier
	s_add_i32 s72, s72, 2
	s_add_u32 s62, s62, 0x100
	s_addc_u32 s63, s63, 0
	s_add_u32 s70, s70, 0x100
	s_addc_u32 s71, s71, 0
	s_cmp_gt_u32 s72, 29
	s_cbranch_scc0 .LBB0_2713
	s_and_b64 vcc, exec, s[58:59]
	s_cbranch_vccz .LBB0_2716
	s_barrier

.LBB0_2805:
	ds_read_b128 v[146:149], v155
	ds_read_b128 v[160:163], v155 offset:1024
	ds_read_b128 v[164:167], v155 offset:2048
	ds_read_b128 v[168:171], v155 offset:3072
	ds_read_b128 v[172:175], v156
	ds_read_b128 v[176:179], v156 offset:1024
	ds_read_b128 v[180:183], v156 offset:2048
	ds_read_b128 v[184:187], v156 offset:3072
	s_add_u32 s8, s48, 0xfff80080
	s_addc_u32 s9, s49, -1
	s_cmp_eq_u32 s67, 28
	s_cselect_b32 s61, s21, s9
	s_cselect_b32 s60, s43, s8
	s_cselect_b32 s57, s19, s66
	s_cselect_b32 s56, s45, s65
	v_lshl_add_u64 v[220:221], s[48:49], 0, v[138:139]
	s_add_i32 m0, s29, 0xc000
	ds_read_b128 v[188:191], v157
	ds_read_b128 v[192:195], v157 offset:1024
	ds_read_b128 v[196:199], v157 offset:2048
	ds_read_b128 v[200:203], v157 offset:3072
	ds_read_b128 v[204:207], v157 offset:4096
	ds_read_b128 v[208:211], v157 offset:5120
	ds_read_b128 v[212:215], v157 offset:6144
	ds_read_b128 v[216:219], v157 offset:7168
	global_load_lds_dwordx4 v[220:221], off
	v_lshl_add_u64 v[220:221], s[48:49], 0, v[140:141]
	s_add_i32 m0, s29, 0xe000
	s_nop 0
	global_load_lds_dwordx4 v[220:221], off
	s_waitcnt vmcnt(8)
	s_waitcnt lgkmcnt(0)
	s_setprio 1
	s_barrier
	v_mfma_f32_16x16x32_bf16 v[124:127], v[146:149], v[188:191], v[124:127]
	v_mfma_f32_16x16x32_bf16 v[120:123], v[164:167], v[188:191], v[120:123]
	v_mfma_f32_16x16x32_bf16 v[108:111], v[146:149], v[196:199], v[108:111]
	v_mfma_f32_16x16x32_bf16 v[104:107], v[164:167], v[196:199], v[104:107]
	v_mfma_f32_16x16x32_bf16 v[92:95], v[146:149], v[204:207], v[92:95]
	v_mfma_f32_16x16x32_bf16 v[88:91], v[164:167], v[204:207], v[88:91]
	v_mfma_f32_16x16x32_bf16 v[76:79], v[146:149], v[212:215], v[76:79]
	v_mfma_f32_16x16x32_bf16 v[72:75], v[164:167], v[212:215], v[72:75]
	v_mfma_f32_16x16x32_bf16 v[124:127], v[160:163], v[192:195], v[124:127]
	v_mfma_f32_16x16x32_bf16 v[120:123], v[168:171], v[192:195], v[120:123]
	v_mfma_f32_16x16x32_bf16 v[108:111], v[160:163], v[200:203], v[108:111]
	v_mfma_f32_16x16x32_bf16 v[104:107], v[168:171], v[200:203], v[104:107]
	v_mfma_f32_16x16x32_bf16 v[92:95], v[160:163], v[208:211], v[92:95]
	v_mfma_f32_16x16x32_bf16 v[88:91], v[168:171], v[208:211], v[88:91]
	v_mfma_f32_16x16x32_bf16 v[76:79], v[160:163], v[216:219], v[76:79]
	v_mfma_f32_16x16x32_bf16 v[72:75], v[168:171], v[216:219], v[72:75]
	v_mfma_f32_16x16x32_bf16 v[116:119], v[172:175], v[188:191], v[116:119]
	v_mfma_f32_16x16x32_bf16 v[112:115], v[180:183], v[188:191], v[112:115]
	v_mfma_f32_16x16x32_bf16 v[100:103], v[172:175], v[196:199], v[100:103]
	v_mfma_f32_16x16x32_bf16 v[96:99], v[180:183], v[196:199], v[96:99]
	v_mfma_f32_16x16x32_bf16 v[84:87], v[172:175], v[204:207], v[84:87]
	v_mfma_f32_16x16x32_bf16 v[80:83], v[180:183], v[204:207], v[80:83]
	v_mfma_f32_16x16x32_bf16 v[68:71], v[172:175], v[212:215], v[68:71]
	v_mfma_f32_16x16x32_bf16 v[64:67], v[180:183], v[212:215], v[64:67]
	v_mfma_f32_16x16x32_bf16 v[116:119], v[176:179], v[192:195], v[116:119]
	v_mfma_f32_16x16x32_bf16 v[112:115], v[184:187], v[192:195], v[112:115]
	v_mfma_f32_16x16x32_bf16 v[100:103], v[176:179], v[200:203], v[100:103]
	v_mfma_f32_16x16x32_bf16 v[96:99], v[184:187], v[200:203], v[96:99]
	v_mfma_f32_16x16x32_bf16 v[84:87], v[176:179], v[208:211], v[84:87]
	v_mfma_f32_16x16x32_bf16 v[80:83], v[184:187], v[208:211], v[80:83]
	v_mfma_f32_16x16x32_bf16 v[68:71], v[176:179], v[216:219], v[68:71]
	v_mfma_f32_16x16x32_bf16 v[64:67], v[184:187], v[216:219], v[64:67]
	s_setprio 0
	s_barrier
	s_add_i32 s8, s63, s94
	v_lshl_add_u64 v[220:221], s[56:57], 0, v[130:131]
	s_mov_b32 m0, s8
	ds_read_b128 v[188:191], v157 offset:16384
	ds_read_b128 v[192:195], v157 offset:17408
	ds_read_b128 v[196:199], v157 offset:18432
	ds_read_b128 v[200:203], v157 offset:19456
	ds_read_b128 v[204:207], v157 offset:20480
	ds_read_b128 v[208:211], v157 offset:21504
	ds_read_b128 v[212:215], v157 offset:22528
	ds_read_b128 v[216:219], v157 offset:23552
	global_load_lds_dwordx4 v[220:221], off
	s_add_i32 m0, s8, 0x2000
	s_add_u32 s68, s56, 0x80000
	v_lshl_add_u64 v[222:223], s[56:57], 0, v[134:135]
	s_addc_u32 s69, s57, 0
	s_add_i32 s8, s64, s94
	global_load_lds_dwordx4 v[222:223], off
	v_lshl_add_u64 v[224:225], s[68:69], 0, v[130:131]
	s_mov_b32 m0, s8
	v_lshl_add_u64 v[226:227], s[60:61], 0, v[132:133]
	global_load_lds_dwordx4 v[224:225], off
	v_lshl_add_u64 v[224:225], s[68:69], 0, v[134:135]
	s_add_i32 m0, s8, 0x2000
	s_nop 0
	global_load_lds_dwordx4 v[224:225], off
	v_lshl_add_u64 v[224:225], s[60:61], 0, v[128:129]
	s_mov_b32 m0, s29
	s_nop 0
	global_load_lds_dwordx4 v[224:225], off
	s_mov_b32 m0, s30
	s_nop 0
	global_load_lds_dwordx4 v[226:227], off
	s_waitcnt vmcnt(8)
	s_waitcnt lgkmcnt(0)
	s_setprio 1
	s_barrier
	v_mfma_f32_16x16x32_bf16 v[60:63], v[146:149], v[188:191], v[60:63]
	v_mfma_f32_16x16x32_bf16 v[56:59], v[164:167], v[188:191], v[56:59]
	v_mfma_f32_16x16x32_bf16 v[44:47], v[146:149], v[196:199], v[44:47]
	v_mfma_f32_16x16x32_bf16 v[40:43], v[164:167], v[196:199], v[40:43]
	v_mfma_f32_16x16x32_bf16 v[28:31], v[146:149], v[204:207], v[28:31]
	v_mfma_f32_16x16x32_bf16 v[24:27], v[164:167], v[204:207], v[24:27]
	v_mfma_f32_16x16x32_bf16 v[12:15], v[146:149], v[212:215], v[12:15]
	v_mfma_f32_16x16x32_bf16 v[8:11], v[164:167], v[212:215], v[8:11]
	v_mfma_f32_16x16x32_bf16 v[60:63], v[160:163], v[192:195], v[60:63]
	v_mfma_f32_16x16x32_bf16 v[56:59], v[168:171], v[192:195], v[56:59]
	v_mfma_f32_16x16x32_bf16 v[44:47], v[160:163], v[200:203], v[44:47]
	v_mfma_f32_16x16x32_bf16 v[40:43], v[168:171], v[200:203], v[40:43]
	v_mfma_f32_16x16x32_bf16 v[28:31], v[160:163], v[208:211], v[28:31]
	v_mfma_f32_16x16x32_bf16 v[24:27], v[168:171], v[208:211], v[24:27]
	v_mfma_f32_16x16x32_bf16 v[12:15], v[160:163], v[216:219], v[12:15]
	v_mfma_f32_16x16x32_bf16 v[8:11], v[168:171], v[216:219], v[8:11]
	v_mfma_f32_16x16x32_bf16 v[52:55], v[172:175], v[188:191], v[52:55]
	v_mfma_f32_16x16x32_bf16 v[48:51], v[180:183], v[188:191], v[48:51]
	v_mfma_f32_16x16x32_bf16 v[36:39], v[172:175], v[196:199], v[36:39]
	v_mfma_f32_16x16x32_bf16 v[32:35], v[180:183], v[196:199], v[32:35]
	v_mfma_f32_16x16x32_bf16 v[20:23], v[172:175], v[204:207], v[20:23]
	v_mfma_f32_16x16x32_bf16 v[16:19], v[180:183], v[204:207], v[16:19]
	v_mfma_f32_16x16x32_bf16 v[4:7], v[172:175], v[212:215], v[4:7]
	v_mfma_f32_16x16x32_bf16 v[0:3], v[180:183], v[212:215], v[0:3]
	v_mfma_f32_16x16x32_bf16 v[52:55], v[176:179], v[192:195], v[52:55]
	v_mfma_f32_16x16x32_bf16 v[48:51], v[184:187], v[192:195], v[48:51]
	v_mfma_f32_16x16x32_bf16 v[36:39], v[176:179], v[200:203], v[36:39]
	v_mfma_f32_16x16x32_bf16 v[32:35], v[184:187], v[200:203], v[32:35]
	v_mfma_f32_16x16x32_bf16 v[20:23], v[176:179], v[208:211], v[20:23]
	v_mfma_f32_16x16x32_bf16 v[16:19], v[184:187], v[208:211], v[16:19]
	v_mfma_f32_16x16x32_bf16 v[4:7], v[176:179], v[216:219], v[4:7]
	v_mfma_f32_16x16x32_bf16 v[0:3], v[184:187], v[216:219], v[0:3]
	s_setprio 0
	s_barrier
	s_add_i32 s8, 0, 0x18000
	v_add_u32_e32 v159, s8, v151
	s_add_i32 s9, 0, 0x1c000
	ds_read_b128 v[146:149], v159
	ds_read_b128 v[160:163], v159 offset:1024
	ds_read_b128 v[164:167], v159 offset:2048
	ds_read_b128 v[168:171], v159 offset:3072
	v_add_u32_e32 v159, s9, v151
	ds_read_b128 v[172:175], v159
	ds_read_b128 v[176:179], v159 offset:1024
	ds_read_b128 v[180:183], v159 offset:2048
	ds_read_b128 v[184:187], v159 offset:3072
	s_add_u32 s60, s60, 0x80000
	s_addc_u32 s61, s61, 0
	s_mov_b32 m0, s34
	v_lshl_add_u64 v[228:229], s[60:61], 0, v[128:129]
	ds_read_b128 v[188:191], v157 offset:32768
	ds_read_b128 v[192:195], v157 offset:33792
	ds_read_b128 v[196:199], v157 offset:34816
	ds_read_b128 v[200:203], v157 offset:35840
	ds_read_b128 v[204:207], v157 offset:36864
	ds_read_b128 v[208:211], v157 offset:37888
	ds_read_b128 v[212:215], v157 offset:38912
	ds_read_b128 v[216:219], v157 offset:39936
	global_load_lds_dwordx4 v[228:229], off
	v_lshl_add_u64 v[228:229], s[60:61], 0, v[132:133]
	s_mov_b32 m0, s35
	s_nop 0
	global_load_lds_dwordx4 v[228:229], off
	s_waitcnt vmcnt(8)
	s_waitcnt lgkmcnt(0)
	s_setprio 1
	s_barrier
	v_mfma_f32_16x16x32_bf16 v[124:127], v[146:149], v[188:191], v[124:127]
	v_mfma_f32_16x16x32_bf16 v[120:123], v[164:167], v[188:191], v[120:123]
	v_mfma_f32_16x16x32_bf16 v[108:111], v[146:149], v[196:199], v[108:111]
	v_mfma_f32_16x16x32_bf16 v[104:107], v[164:167], v[196:199], v[104:107]
	v_mfma_f32_16x16x32_bf16 v[92:95], v[146:149], v[204:207], v[92:95]
	v_mfma_f32_16x16x32_bf16 v[88:91], v[164:167], v[204:207], v[88:91]
	v_mfma_f32_16x16x32_bf16 v[76:79], v[146:149], v[212:215], v[76:79]
	v_mfma_f32_16x16x32_bf16 v[72:75], v[164:167], v[212:215], v[72:75]
	v_mfma_f32_16x16x32_bf16 v[124:127], v[160:163], v[192:195], v[124:127]
	v_mfma_f32_16x16x32_bf16 v[120:123], v[168:171], v[192:195], v[120:123]
	v_mfma_f32_16x16x32_bf16 v[108:111], v[160:163], v[200:203], v[108:111]
	v_mfma_f32_16x16x32_bf16 v[104:107], v[168:171], v[200:203], v[104:107]
	v_mfma_f32_16x16x32_bf16 v[92:95], v[160:163], v[208:211], v[92:95]
	v_mfma_f32_16x16x32_bf16 v[88:91], v[168:171], v[208:211], v[88:91]
	v_mfma_f32_16x16x32_bf16 v[76:79], v[160:163], v[216:219], v[76:79]
	v_mfma_f32_16x16x32_bf16 v[72:75], v[168:171], v[216:219], v[72:75]
	v_mfma_f32_16x16x32_bf16 v[116:119], v[172:175], v[188:191], v[116:119]
	v_mfma_f32_16x16x32_bf16 v[112:115], v[180:183], v[188:191], v[112:115]
	v_mfma_f32_16x16x32_bf16 v[100:103], v[172:175], v[196:199], v[100:103]
	v_mfma_f32_16x16x32_bf16 v[96:99], v[180:183], v[196:199], v[96:99]
	v_mfma_f32_16x16x32_bf16 v[84:87], v[172:175], v[204:207], v[84:87]
	v_mfma_f32_16x16x32_bf16 v[80:83], v[180:183], v[204:207], v[80:83]
	v_mfma_f32_16x16x32_bf16 v[68:71], v[172:175], v[212:215], v[68:71]
	v_mfma_f32_16x16x32_bf16 v[64:67], v[180:183], v[212:215], v[64:67]
	v_mfma_f32_16x16x32_bf16 v[116:119], v[176:179], v[192:195], v[116:119]
	v_mfma_f32_16x16x32_bf16 v[112:115], v[184:187], v[192:195], v[112:115]
	v_mfma_f32_16x16x32_bf16 v[100:103], v[176:179], v[200:203], v[100:103]
	v_mfma_f32_16x16x32_bf16 v[96:99], v[184:187], v[200:203], v[96:99]
	v_mfma_f32_16x16x32_bf16 v[84:87], v[176:179], v[208:211], v[84:87]
	v_mfma_f32_16x16x32_bf16 v[80:83], v[184:187], v[208:211], v[80:83]
	v_mfma_f32_16x16x32_bf16 v[68:71], v[176:179], v[216:219], v[68:71]
	v_mfma_f32_16x16x32_bf16 v[64:67], v[184:187], v[216:219], v[64:67]
	s_setprio 0
	s_barrier
	s_add_i32 s8, s8, s94
	v_lshl_add_u64 v[220:221], v[220:221], 0, s[16:17]
	s_mov_b32 m0, s8
	ds_read_b128 v[188:191], v157 offset:49152
	ds_read_b128 v[192:195], v157 offset:50176
	ds_read_b128 v[196:199], v157 offset:51200
	ds_read_b128 v[200:203], v157 offset:52224
	ds_read_b128 v[204:207], v157 offset:53248
	ds_read_b128 v[208:211], v157 offset:54272
	ds_read_b128 v[212:215], v157 offset:55296
	ds_read_b128 v[216:219], v157 offset:56320
	global_load_lds_dwordx4 v[220:221], off
	s_add_i32 m0, s8, 0x2000
	s_add_u32 s56, s56, 0x80080
	v_lshl_add_u64 v[220:221], v[222:223], 0, s[16:17]
	s_addc_u32 s57, s57, 0
	s_add_i32 s8, s9, s94
	global_load_lds_dwordx4 v[220:221], off
	v_lshl_add_u64 v[220:221], s[56:57], 0, v[130:131]
	s_mov_b32 m0, s8
	s_nop 0
	global_load_lds_dwordx4 v[220:221], off
	v_lshl_add_u64 v[220:221], s[56:57], 0, v[134:135]
	s_add_i32 m0, s8, 0x2000
	s_nop 0
	global_load_lds_dwordx4 v[220:221], off
	v_lshl_add_u64 v[220:221], v[224:225], 0, s[16:17]
	s_mov_b32 m0, s47
	s_nop 0
	global_load_lds_dwordx4 v[220:221], off
	v_lshl_add_u64 v[220:221], v[226:227], 0, s[16:17]
	s_mov_b32 m0, s62
	s_nop 0
	global_load_lds_dwordx4 v[220:221], off
	s_waitcnt vmcnt(8)
	s_waitcnt lgkmcnt(0)
	s_setprio 1
	s_barrier
	v_mfma_f32_16x16x32_bf16 v[60:63], v[146:149], v[188:191], v[60:63]
	v_mfma_f32_16x16x32_bf16 v[56:59], v[164:167], v[188:191], v[56:59]
	v_mfma_f32_16x16x32_bf16 v[44:47], v[146:149], v[196:199], v[44:47]
	v_mfma_f32_16x16x32_bf16 v[40:43], v[164:167], v[196:199], v[40:43]
	v_mfma_f32_16x16x32_bf16 v[28:31], v[146:149], v[204:207], v[28:31]
	v_mfma_f32_16x16x32_bf16 v[24:27], v[164:167], v[204:207], v[24:27]
	v_mfma_f32_16x16x32_bf16 v[12:15], v[146:149], v[212:215], v[12:15]
	v_mfma_f32_16x16x32_bf16 v[8:11], v[164:167], v[212:215], v[8:11]
	v_mfma_f32_16x16x32_bf16 v[60:63], v[160:163], v[192:195], v[60:63]
	v_mfma_f32_16x16x32_bf16 v[56:59], v[168:171], v[192:195], v[56:59]
	v_mfma_f32_16x16x32_bf16 v[44:47], v[160:163], v[200:203], v[44:47]
	v_mfma_f32_16x16x32_bf16 v[40:43], v[168:171], v[200:203], v[40:43]
	v_mfma_f32_16x16x32_bf16 v[28:31], v[160:163], v[208:211], v[28:31]
	v_mfma_f32_16x16x32_bf16 v[24:27], v[168:171], v[208:211], v[24:27]
	v_mfma_f32_16x16x32_bf16 v[12:15], v[160:163], v[216:219], v[12:15]
	v_mfma_f32_16x16x32_bf16 v[8:11], v[168:171], v[216:219], v[8:11]
	v_mfma_f32_16x16x32_bf16 v[52:55], v[172:175], v[188:191], v[52:55]
	v_mfma_f32_16x16x32_bf16 v[48:51], v[180:183], v[188:191], v[48:51]
	v_mfma_f32_16x16x32_bf16 v[36:39], v[172:175], v[196:199], v[36:39]
	v_mfma_f32_16x16x32_bf16 v[32:35], v[180:183], v[196:199], v[32:35]
	v_mfma_f32_16x16x32_bf16 v[20:23], v[172:175], v[204:207], v[20:23]
	v_mfma_f32_16x16x32_bf16 v[16:19], v[180:183], v[204:207], v[16:19]
	v_mfma_f32_16x16x32_bf16 v[4:7], v[172:175], v[212:215], v[4:7]
	v_mfma_f32_16x16x32_bf16 v[0:3], v[180:183], v[212:215], v[0:3]
	v_mfma_f32_16x16x32_bf16 v[52:55], v[176:179], v[192:195], v[52:55]
	v_mfma_f32_16x16x32_bf16 v[48:51], v[184:187], v[192:195], v[48:51]
	v_mfma_f32_16x16x32_bf16 v[36:39], v[176:179], v[200:203], v[36:39]
	v_mfma_f32_16x16x32_bf16 v[32:35], v[184:187], v[200:203], v[32:35]
	v_mfma_f32_16x16x32_bf16 v[20:23], v[176:179], v[208:211], v[20:23]
	v_mfma_f32_16x16x32_bf16 v[16:19], v[184:187], v[208:211], v[16:19]
	v_mfma_f32_16x16x32_bf16 v[4:7], v[176:179], v[216:219], v[4:7]
	v_mfma_f32_16x16x32_bf16 v[0:3], v[184:187], v[216:219], v[0:3]
	s_setprio 0
	s_barrier
	s_add_i32 s67, s67, 2
	s_add_u32 s48, s48, 0x100
	s_addc_u32 s49, s49, 0
	s_add_u32 s65, s65, 0x100
	s_addc_u32 s66, s66, 0
	s_cmp_gt_u32 s67, 29
	s_cbranch_scc0 .LBB0_2805
	s_and_b64 vcc, exec, s[58:59]
	s_cbranch_vccz .LBB0_2808
	s_barrier

.LBB0_2917:
	ds_read_b128 v[140:143], v149
	ds_read_b128 v[152:155], v149 offset:1024
	ds_read_b128 v[156:159], v149 offset:2048
	ds_read_b128 v[160:163], v149 offset:3072
	ds_read_b128 v[164:167], v150
	ds_read_b128 v[168:171], v150 offset:1024
	ds_read_b128 v[172:175], v150 offset:2048
	ds_read_b128 v[176:179], v150 offset:3072
	s_add_u32 s42, s40, 0xffe00080
	s_addc_u32 s43, s41, -1
	s_cmpk_eq_i32 s64, 0x7c
	s_cselect_b32 s45, s21, s43
	s_cselect_b32 s44, s39, s42
	s_cselect_b32 s43, s19, s63
	s_cselect_b32 s42, s61, s62
	v_lshl_add_u64 v[212:213], s[40:41], 0, v[132:133]
	s_add_i32 m0, s29, 0xc000
	ds_read_b128 v[180:183], v151
	ds_read_b128 v[184:187], v151 offset:1024
	ds_read_b128 v[188:191], v151 offset:2048
	ds_read_b128 v[192:195], v151 offset:3072
	ds_read_b128 v[196:199], v151 offset:4096
	ds_read_b128 v[200:203], v151 offset:5120
	ds_read_b128 v[204:207], v151 offset:6144
	ds_read_b128 v[208:211], v151 offset:7168
	global_load_lds_dwordx4 v[212:213], off
	v_lshl_add_u64 v[212:213], s[40:41], 0, v[134:135]
	s_add_i32 m0, s29, 0xe000
	s_nop 0
	global_load_lds_dwordx4 v[212:213], off
	s_waitcnt vmcnt(8)
	s_waitcnt lgkmcnt(0)
	s_setprio 1
	s_barrier
	v_mfma_f32_16x16x32_bf16 v[124:127], v[140:143], v[180:183], v[124:127]
	v_mfma_f32_16x16x32_bf16 v[120:123], v[156:159], v[180:183], v[120:123]
	v_mfma_f32_16x16x32_bf16 v[108:111], v[140:143], v[188:191], v[108:111]
	v_mfma_f32_16x16x32_bf16 v[104:107], v[156:159], v[188:191], v[104:107]
	v_mfma_f32_16x16x32_bf16 v[92:95], v[140:143], v[196:199], v[92:95]
	v_mfma_f32_16x16x32_bf16 v[88:91], v[156:159], v[196:199], v[88:91]
	v_mfma_f32_16x16x32_bf16 v[76:79], v[140:143], v[204:207], v[76:79]
	v_mfma_f32_16x16x32_bf16 v[72:75], v[156:159], v[204:207], v[72:75]
	v_mfma_f32_16x16x32_bf16 v[124:127], v[152:155], v[184:187], v[124:127]
	v_mfma_f32_16x16x32_bf16 v[120:123], v[160:163], v[184:187], v[120:123]
	v_mfma_f32_16x16x32_bf16 v[108:111], v[152:155], v[192:195], v[108:111]
	v_mfma_f32_16x16x32_bf16 v[104:107], v[160:163], v[192:195], v[104:107]
	v_mfma_f32_16x16x32_bf16 v[92:95], v[152:155], v[200:203], v[92:95]
	v_mfma_f32_16x16x32_bf16 v[88:91], v[160:163], v[200:203], v[88:91]
	v_mfma_f32_16x16x32_bf16 v[76:79], v[152:155], v[208:211], v[76:79]
	v_mfma_f32_16x16x32_bf16 v[72:75], v[160:163], v[208:211], v[72:75]
	v_mfma_f32_16x16x32_bf16 v[116:119], v[164:167], v[180:183], v[116:119]
	v_mfma_f32_16x16x32_bf16 v[112:115], v[172:175], v[180:183], v[112:115]
	v_mfma_f32_16x16x32_bf16 v[100:103], v[164:167], v[188:191], v[100:103]
	v_mfma_f32_16x16x32_bf16 v[96:99], v[172:175], v[188:191], v[96:99]
	v_mfma_f32_16x16x32_bf16 v[84:87], v[164:167], v[196:199], v[84:87]
	v_mfma_f32_16x16x32_bf16 v[80:83], v[172:175], v[196:199], v[80:83]
	v_mfma_f32_16x16x32_bf16 v[68:71], v[164:167], v[204:207], v[68:71]
	v_mfma_f32_16x16x32_bf16 v[64:67], v[172:175], v[204:207], v[64:67]
	v_mfma_f32_16x16x32_bf16 v[116:119], v[168:171], v[184:187], v[116:119]
	v_mfma_f32_16x16x32_bf16 v[112:115], v[176:179], v[184:187], v[112:115]
	v_mfma_f32_16x16x32_bf16 v[100:103], v[168:171], v[192:195], v[100:103]
	v_mfma_f32_16x16x32_bf16 v[96:99], v[176:179], v[192:195], v[96:99]
	v_mfma_f32_16x16x32_bf16 v[84:87], v[168:171], v[200:203], v[84:87]
	v_mfma_f32_16x16x32_bf16 v[80:83], v[176:179], v[200:203], v[80:83]
	v_mfma_f32_16x16x32_bf16 v[68:71], v[168:171], v[208:211], v[68:71]
	v_mfma_f32_16x16x32_bf16 v[64:67], v[176:179], v[208:211], v[64:67]
	s_setprio 0
	s_barrier
	s_add_i32 s65, s56, s94
	v_lshl_add_u64 v[212:213], s[42:43], 0, v[128:129]
	s_mov_b32 m0, s65
	ds_read_b128 v[180:183], v151 offset:16384
	ds_read_b128 v[184:187], v151 offset:17408
	ds_read_b128 v[188:191], v151 offset:18432
	ds_read_b128 v[192:195], v151 offset:19456
	ds_read_b128 v[196:199], v151 offset:20480
	ds_read_b128 v[200:203], v151 offset:21504
	ds_read_b128 v[204:207], v151 offset:22528
	ds_read_b128 v[208:211], v151 offset:23552
	global_load_lds_dwordx4 v[212:213], off
	s_add_i32 m0, s65, 0x2000
	s_add_u32 s66, s42, 0x200000
	v_lshl_add_u64 v[214:215], s[42:43], 0, v[130:131]
	s_addc_u32 s67, s43, 0
	s_add_i32 s65, s57, s94
	global_load_lds_dwordx4 v[214:215], off
	v_lshl_add_u64 v[216:217], s[66:67], 0, v[128:129]
	s_mov_b32 m0, s65
	v_lshl_add_u64 v[218:219], s[44:45], 0, v[130:131]
	global_load_lds_dwordx4 v[216:217], off
	v_lshl_add_u64 v[216:217], s[66:67], 0, v[130:131]
	s_add_i32 m0, s65, 0x2000
	s_nop 0
	global_load_lds_dwordx4 v[216:217], off
	v_lshl_add_u64 v[216:217], s[44:45], 0, v[128:129]
	s_mov_b32 m0, s29
	s_nop 0
	global_load_lds_dwordx4 v[216:217], off
	s_mov_b32 m0, s30
	s_nop 0
	global_load_lds_dwordx4 v[218:219], off
	s_waitcnt vmcnt(8)
	s_waitcnt lgkmcnt(0)
	s_setprio 1
	s_barrier
	v_mfma_f32_16x16x32_bf16 v[60:63], v[140:143], v[180:183], v[60:63]
	v_mfma_f32_16x16x32_bf16 v[56:59], v[156:159], v[180:183], v[56:59]
	v_mfma_f32_16x16x32_bf16 v[44:47], v[140:143], v[188:191], v[44:47]
	v_mfma_f32_16x16x32_bf16 v[40:43], v[156:159], v[188:191], v[40:43]
	v_mfma_f32_16x16x32_bf16 v[28:31], v[140:143], v[196:199], v[28:31]
	v_mfma_f32_16x16x32_bf16 v[24:27], v[156:159], v[196:199], v[24:27]
	v_mfma_f32_16x16x32_bf16 v[12:15], v[140:143], v[204:207], v[12:15]
	v_mfma_f32_16x16x32_bf16 v[8:11], v[156:159], v[204:207], v[8:11]
	v_mfma_f32_16x16x32_bf16 v[60:63], v[152:155], v[184:187], v[60:63]
	v_mfma_f32_16x16x32_bf16 v[56:59], v[160:163], v[184:187], v[56:59]
	v_mfma_f32_16x16x32_bf16 v[44:47], v[152:155], v[192:195], v[44:47]
	v_mfma_f32_16x16x32_bf16 v[40:43], v[160:163], v[192:195], v[40:43]
	v_mfma_f32_16x16x32_bf16 v[28:31], v[152:155], v[200:203], v[28:31]
	v_mfma_f32_16x16x32_bf16 v[24:27], v[160:163], v[200:203], v[24:27]
	v_mfma_f32_16x16x32_bf16 v[12:15], v[152:155], v[208:211], v[12:15]
	v_mfma_f32_16x16x32_bf16 v[8:11], v[160:163], v[208:211], v[8:11]
	v_mfma_f32_16x16x32_bf16 v[52:55], v[164:167], v[180:183], v[52:55]
	v_mfma_f32_16x16x32_bf16 v[48:51], v[172:175], v[180:183], v[48:51]
	v_mfma_f32_16x16x32_bf16 v[36:39], v[164:167], v[188:191], v[36:39]
	v_mfma_f32_16x16x32_bf16 v[32:35], v[172:175], v[188:191], v[32:35]
	v_mfma_f32_16x16x32_bf16 v[20:23], v[164:167], v[196:199], v[20:23]
	v_mfma_f32_16x16x32_bf16 v[16:19], v[172:175], v[196:199], v[16:19]
	v_mfma_f32_16x16x32_bf16 v[4:7], v[164:167], v[204:207], v[4:7]
	v_mfma_f32_16x16x32_bf16 v[0:3], v[172:175], v[204:207], v[0:3]
	v_mfma_f32_16x16x32_bf16 v[52:55], v[168:171], v[184:187], v[52:55]
	v_mfma_f32_16x16x32_bf16 v[48:51], v[176:179], v[184:187], v[48:51]
	v_mfma_f32_16x16x32_bf16 v[36:39], v[168:171], v[192:195], v[36:39]
	v_mfma_f32_16x16x32_bf16 v[32:35], v[176:179], v[192:195], v[32:35]
	v_mfma_f32_16x16x32_bf16 v[20:23], v[168:171], v[200:203], v[20:23]
	v_mfma_f32_16x16x32_bf16 v[16:19], v[176:179], v[200:203], v[16:19]
	v_mfma_f32_16x16x32_bf16 v[4:7], v[168:171], v[208:211], v[4:7]
	v_mfma_f32_16x16x32_bf16 v[0:3], v[176:179], v[208:211], v[0:3]
	s_setprio 0
	s_barrier
	s_add_i32 s65, 0, 0x18000
	s_add_i32 s66, 0, 0x1c000
	v_add_u32_e32 v160, s65, v145
	v_add_u32_e32 v176, s66, v145
	ds_read_b128 v[140:143], v160
	ds_read_b128 v[152:155], v160 offset:1024
	ds_read_b128 v[156:159], v160 offset:2048
	ds_read_b128 v[160:163], v160 offset:3072
	ds_read_b128 v[164:167], v176
	ds_read_b128 v[168:171], v176 offset:1024
	ds_read_b128 v[172:175], v176 offset:2048
	ds_read_b128 v[176:179], v176 offset:3072
	s_add_u32 s44, s44, 0x200000
	s_addc_u32 s45, s45, 0
	s_mov_b32 m0, s46
	v_lshl_add_u64 v[220:221], s[44:45], 0, v[128:129]
	ds_read_b128 v[180:183], v151 offset:32768
	ds_read_b128 v[184:187], v151 offset:33792
	ds_read_b128 v[188:191], v151 offset:34816
	ds_read_b128 v[192:195], v151 offset:35840
	ds_read_b128 v[196:199], v151 offset:36864
	ds_read_b128 v[200:203], v151 offset:37888
	ds_read_b128 v[204:207], v151 offset:38912
	ds_read_b128 v[208:211], v151 offset:39936
	global_load_lds_dwordx4 v[220:221], off
	v_lshl_add_u64 v[220:221], s[44:45], 0, v[130:131]
	s_mov_b32 m0, s47
	s_nop 0
	global_load_lds_dwordx4 v[220:221], off
	s_waitcnt vmcnt(8)
	s_waitcnt lgkmcnt(0)
	s_setprio 1
	s_barrier
	v_mfma_f32_16x16x32_bf16 v[124:127], v[140:143], v[180:183], v[124:127]
	v_mfma_f32_16x16x32_bf16 v[120:123], v[156:159], v[180:183], v[120:123]
	v_mfma_f32_16x16x32_bf16 v[108:111], v[140:143], v[188:191], v[108:111]
	v_mfma_f32_16x16x32_bf16 v[104:107], v[156:159], v[188:191], v[104:107]
	v_mfma_f32_16x16x32_bf16 v[92:95], v[140:143], v[196:199], v[92:95]
	v_mfma_f32_16x16x32_bf16 v[88:91], v[156:159], v[196:199], v[88:91]
	v_mfma_f32_16x16x32_bf16 v[76:79], v[140:143], v[204:207], v[76:79]
	v_mfma_f32_16x16x32_bf16 v[72:75], v[156:159], v[204:207], v[72:75]
	v_mfma_f32_16x16x32_bf16 v[124:127], v[152:155], v[184:187], v[124:127]
	v_mfma_f32_16x16x32_bf16 v[120:123], v[160:163], v[184:187], v[120:123]
	v_mfma_f32_16x16x32_bf16 v[108:111], v[152:155], v[192:195], v[108:111]
	v_mfma_f32_16x16x32_bf16 v[104:107], v[160:163], v[192:195], v[104:107]
	v_mfma_f32_16x16x32_bf16 v[92:95], v[152:155], v[200:203], v[92:95]
	v_mfma_f32_16x16x32_bf16 v[88:91], v[160:163], v[200:203], v[88:91]
	v_mfma_f32_16x16x32_bf16 v[76:79], v[152:155], v[208:211], v[76:79]
	v_mfma_f32_16x16x32_bf16 v[72:75], v[160:163], v[208:211], v[72:75]
	v_mfma_f32_16x16x32_bf16 v[116:119], v[164:167], v[180:183], v[116:119]
	v_mfma_f32_16x16x32_bf16 v[112:115], v[172:175], v[180:183], v[112:115]
	v_mfma_f32_16x16x32_bf16 v[100:103], v[164:167], v[188:191], v[100:103]
	v_mfma_f32_16x16x32_bf16 v[96:99], v[172:175], v[188:191], v[96:99]
	v_mfma_f32_16x16x32_bf16 v[84:87], v[164:167], v[196:199], v[84:87]
	v_mfma_f32_16x16x32_bf16 v[80:83], v[172:175], v[196:199], v[80:83]
	v_mfma_f32_16x16x32_bf16 v[68:71], v[164:167], v[204:207], v[68:71]
	v_mfma_f32_16x16x32_bf16 v[64:67], v[172:175], v[204:207], v[64:67]
	v_mfma_f32_16x16x32_bf16 v[116:119], v[168:171], v[184:187], v[116:119]
	v_mfma_f32_16x16x32_bf16 v[112:115], v[176:179], v[184:187], v[112:115]
	v_mfma_f32_16x16x32_bf16 v[100:103], v[168:171], v[192:195], v[100:103]
	v_mfma_f32_16x16x32_bf16 v[96:99], v[176:179], v[192:195], v[96:99]
	v_mfma_f32_16x16x32_bf16 v[84:87], v[168:171], v[200:203], v[84:87]
	v_mfma_f32_16x16x32_bf16 v[80:83], v[176:179], v[200:203], v[80:83]
	v_mfma_f32_16x16x32_bf16 v[68:71], v[168:171], v[208:211], v[68:71]
	v_mfma_f32_16x16x32_bf16 v[64:67], v[176:179], v[208:211], v[64:67]
	s_setprio 0
	s_barrier
	s_add_i32 s44, s65, s94
	v_lshl_add_u64 v[212:213], v[212:213], 0, s[16:17]
	s_mov_b32 m0, s44
	ds_read_b128 v[180:183], v151 offset:49152
	ds_read_b128 v[184:187], v151 offset:50176
	ds_read_b128 v[188:191], v151 offset:51200
	ds_read_b128 v[192:195], v151 offset:52224
	ds_read_b128 v[196:199], v151 offset:53248
	ds_read_b128 v[200:203], v151 offset:54272
	ds_read_b128 v[204:207], v151 offset:55296
	ds_read_b128 v[208:211], v151 offset:56320
	global_load_lds_dwordx4 v[212:213], off
	s_add_i32 m0, s44, 0x2000
	s_add_u32 s42, s42, 0x200080
	v_lshl_add_u64 v[212:213], v[214:215], 0, s[16:17]
	s_addc_u32 s43, s43, 0
	s_add_i32 s44, s66, s94
	global_load_lds_dwordx4 v[212:213], off
	v_lshl_add_u64 v[212:213], s[42:43], 0, v[128:129]
	s_mov_b32 m0, s44
	s_nop 0
	global_load_lds_dwordx4 v[212:213], off
	v_lshl_add_u64 v[212:213], s[42:43], 0, v[130:131]
	s_add_i32 m0, s44, 0x2000
	s_nop 0
	global_load_lds_dwordx4 v[212:213], off
	v_lshl_add_u64 v[212:213], v[216:217], 0, s[16:17]
	s_mov_b32 m0, s48
	s_nop 0
	global_load_lds_dwordx4 v[212:213], off
	v_lshl_add_u64 v[212:213], v[218:219], 0, s[16:17]
	s_mov_b32 m0, s49
	s_nop 0
	global_load_lds_dwordx4 v[212:213], off
	s_waitcnt vmcnt(8)
	s_waitcnt lgkmcnt(0)
	s_setprio 1
	s_barrier
	v_mfma_f32_16x16x32_bf16 v[60:63], v[140:143], v[180:183], v[60:63]
	v_mfma_f32_16x16x32_bf16 v[56:59], v[156:159], v[180:183], v[56:59]
	v_mfma_f32_16x16x32_bf16 v[44:47], v[140:143], v[188:191], v[44:47]
	v_mfma_f32_16x16x32_bf16 v[40:43], v[156:159], v[188:191], v[40:43]
	v_mfma_f32_16x16x32_bf16 v[28:31], v[140:143], v[196:199], v[28:31]
	v_mfma_f32_16x16x32_bf16 v[24:27], v[156:159], v[196:199], v[24:27]
	v_mfma_f32_16x16x32_bf16 v[12:15], v[140:143], v[204:207], v[12:15]
	v_mfma_f32_16x16x32_bf16 v[8:11], v[156:159], v[204:207], v[8:11]
	v_mfma_f32_16x16x32_bf16 v[60:63], v[152:155], v[184:187], v[60:63]
	v_mfma_f32_16x16x32_bf16 v[56:59], v[160:163], v[184:187], v[56:59]
	v_mfma_f32_16x16x32_bf16 v[44:47], v[152:155], v[192:195], v[44:47]
	v_mfma_f32_16x16x32_bf16 v[40:43], v[160:163], v[192:195], v[40:43]
	v_mfma_f32_16x16x32_bf16 v[28:31], v[152:155], v[200:203], v[28:31]
	v_mfma_f32_16x16x32_bf16 v[24:27], v[160:163], v[200:203], v[24:27]
	v_mfma_f32_16x16x32_bf16 v[12:15], v[152:155], v[208:211], v[12:15]
	v_mfma_f32_16x16x32_bf16 v[8:11], v[160:163], v[208:211], v[8:11]
	v_mfma_f32_16x16x32_bf16 v[52:55], v[164:167], v[180:183], v[52:55]
	v_mfma_f32_16x16x32_bf16 v[48:51], v[172:175], v[180:183], v[48:51]
	v_mfma_f32_16x16x32_bf16 v[36:39], v[164:167], v[188:191], v[36:39]
	v_mfma_f32_16x16x32_bf16 v[32:35], v[172:175], v[188:191], v[32:35]
	v_mfma_f32_16x16x32_bf16 v[20:23], v[164:167], v[196:199], v[20:23]
	v_mfma_f32_16x16x32_bf16 v[16:19], v[172:175], v[196:199], v[16:19]
	v_mfma_f32_16x16x32_bf16 v[4:7], v[164:167], v[204:207], v[4:7]
	v_mfma_f32_16x16x32_bf16 v[0:3], v[172:175], v[204:207], v[0:3]
	v_mfma_f32_16x16x32_bf16 v[52:55], v[168:171], v[184:187], v[52:55]
	v_mfma_f32_16x16x32_bf16 v[48:51], v[176:179], v[184:187], v[48:51]
	v_mfma_f32_16x16x32_bf16 v[36:39], v[168:171], v[192:195], v[36:39]
	v_mfma_f32_16x16x32_bf16 v[32:35], v[176:179], v[192:195], v[32:35]
	v_mfma_f32_16x16x32_bf16 v[20:23], v[168:171], v[200:203], v[20:23]
	v_mfma_f32_16x16x32_bf16 v[16:19], v[176:179], v[200:203], v[16:19]
	v_mfma_f32_16x16x32_bf16 v[4:7], v[168:171], v[208:211], v[4:7]
	v_mfma_f32_16x16x32_bf16 v[0:3], v[176:179], v[208:211], v[0:3]
	s_setprio 0
	s_barrier
	s_add_i32 s64, s64, 2
	s_add_u32 s40, s40, 0x100
	s_addc_u32 s41, s41, 0
	s_add_u32 s62, s62, 0x100
	s_addc_u32 s63, s63, 0
	s_cmpk_gt_u32 s64, 0x7d
	s_cbranch_scc0 .LBB0_2917
	s_and_b64 vcc, exec, s[58:59]
	s_cbranch_vccz .LBB0_2920
	s_barrier
